# retention-output item: query-fragment and gate loads issued together instead of one round trip each
# speedup vs baseline: 1.0525x; 1.0043x over previous
; #define LAS __attribute__((address_space(3)))
; DI int otid() { int t = threadIdx.x; asm volatile("" : "+v"(t)); return t; }
; DI float ret_lg2(const Params& p, int l, int dir, int h) { return log1pf(-exp2f(p.in[12][(l * 2 + dir) * 5 + h])) * 1.4426950408889634f; }
; DI void ret_out_item(const Params& p, int l, int b, int h, int c, LAS unsigned char* lds) {
;     const int tid = otid(), lane = tid & 63, wid = tid >> 6, r16 = lane & 15, q4 = lane >> 4;
;     unsigned char* ws = p.ws;
;     const bf16_t* P = (const bf16_t*)(ws + WS_P);
;     const float lgf = ret_lg2(p, l, 0, h), lgb = ret_lg2(p, l, 1, h);
; DI void phase_mixers(const Params& p, int l, LAS unsigned char* lds) {
;     ...
;     while (it < e1) { const int i2 = it - e0, c = (i2 % nc) + (18 - nc), bh = i2 / nc; ret_out_item(p, l, bh / 5, bh % 5, c, lds); it = next_item(ctr, slot); }
.LBB0_1180:
	s_add_i32 s0, s28, 0xffffff60
	s_mul_hi_i32 s1, s0, 0x38e38e39
	s_lshr_b32 s16, s1, 31
	s_ashr_i32 s1, s1, 2
	s_add_i32 s1, s1, s16
	s_mul_i32 s16, s1, 18
	s_sub_i32 s19, s0, s16
	s_mul_hi_i32 s16, s0, 0xb60b60b7
	s_add_i32 s16, s16, s0
	s_lshr_b32 s0, s16, 31
	s_ashr_i32 s18, s16, 6
	s_add_i32 s18, s18, s0
	s_mul_hi_i32 s0, s1, 0x66666667
	s_lshr_b32 s16, s0, 31
	s_ashr_i32 s0, s0, 1
	s_add_i32 s0, s0, s16
	s_mul_i32 s0, s0, 5
	s_sub_i32 s16, s1, s0
	s_ashr_i32 s17, s16, 31
	s_lshl_b64 s[0:1], s[16:17], 2
	s_add_u32 s0, s60, s0
	v_mov_b32_e32 v16, v202
	s_addc_u32 s1, s61, s1
	global_load_dword v0, v69, s[0:1]
	global_load_dword v1, v69, s[0:1] offset:20
	v_bfe_u32 v92, v16, 4, 2
	s_waitcnt vmcnt(1)
	v_cmp_gt_f32_e32 vcc, s3, v0
	s_nop 1
	v_cndmask_b32_e32 v2, 0, v82, vcc
	s_waitcnt vmcnt(0)
	v_cmp_gt_f32_e64 s[0:1], s3, v1
	v_add_f32_e32 v0, v0, v2
	v_exp_f32_e32 v0, v0
	v_cndmask_b32_e64 v3, 0, v82, s[0:1]
	v_add_f32_e32 v1, v1, v3
	s_and_b64 s[28:29], vcc, exec
	v_exp_f32_e32 v1, v1
	s_cselect_b32 s17, 0xffffffc0, 0
	s_and_b64 s[0:1], s[0:1], exec
	v_ldexp_f32 v15, v0, s17
	s_cselect_b32 s0, 0xffffffc0, 0
	v_sub_f32_e32 v4, 1.0, v15
	v_ldexp_f32 v14, v1, s0
	v_frexp_mant_f32_e32 v7, v4
	v_cvt_f64_f32_e32 v[0:1], v4
	v_sub_f32_e32 v5, 1.0, v14
	v_add_f32_e32 v6, -1.0, v4
	v_frexp_exp_i32_f64_e32 v0, v[0:1]
	v_cmp_gt_f32_e32 vcc, s4, v7
	v_add_f32_e32 v8, -1.0, v5
	v_frexp_mant_f32_e32 v9, v5
	v_cvt_f64_f32_e32 v[2:3], v5
	v_sub_f32_e32 v10, v6, v4
	v_subbrev_co_u32_e32 v0, vcc, 0, v0, vcc
	v_sub_f32_e64 v6, -v15, v6
	v_sub_f32_e32 v1, v8, v5
	v_frexp_exp_i32_f64_e32 v2, v[2:3]
	v_add_f32_e32 v3, 1.0, v10
	v_cmp_gt_f32_e32 vcc, s4, v9
	v_sub_f32_e64 v8, -v14, v8
	v_add_f32_e32 v1, 1.0, v1
	v_subbrev_co_u32_e32 v17, vcc, 0, v2, vcc
	v_add_f32_e32 v2, v6, v3
	v_sub_u32_e32 v3, 0, v0
	v_add_f32_e32 v1, v8, v1
	v_sub_u32_e32 v6, 0, v17
	v_ldexp_f32 v4, v4, v3
	v_ldexp_f32 v20, v5, v6
	v_ldexp_f32 v21, v1, v6
	v_add_f32_e32 v1, -1.0, v4
	v_add_f32_e32 v5, 1.0, v4
	v_ldexp_f32 v2, v2, v3
	v_add_f32_e32 v3, 1.0, v1
	v_add_f32_e32 v6, -1.0, v5
	v_sub_f32_e32 v3, v4, v3
	v_sub_f32_e32 v4, v4, v6
	v_add_f32_e32 v6, v2, v3
	v_add_f32_e32 v2, v2, v4
	v_add_f32_e32 v8, v5, v2
	v_rcp_f32_e32 v9, v8
	v_add_f32_e32 v3, v1, v6
	v_sub_f32_e32 v4, v8, v5
	v_sub_f32_e32 v1, v3, v1
	v_mul_f32_e32 v11, v3, v9
	v_sub_f32_e32 v10, v2, v4
	v_mul_f32_e32 v4, v8, v11
	v_sub_f32_e32 v1, v6, v1
	v_fma_f32 v6, v11, v8, -v4
	v_fmac_f32_e32 v6, v11, v10
	v_add_f32_e32 v2, v4, v6
	v_sub_f32_e32 v5, v3, v2
	v_mov_b32_e32 v7, v2
	v_pk_add_f32 v[2:3], v[2:3], v[4:5] neg_lo:[0,1] neg_hi:[0,1]
	v_cvt_f32_i32_e32 v0, v0
	v_pk_add_f32 v[2:3], v[2:3], v[6:7] neg_lo:[0,1] neg_hi:[0,1]
	v_cmp_nlt_f32_e32 vcc, 1.0, v15
	v_add_f32_e32 v1, v1, v3
	v_add_f32_e32 v1, v2, v1
	v_add_f32_e32 v3, v5, v1
	v_mul_f32_e32 v2, v9, v3
	v_mul_f32_e32 v4, v8, v2
	v_sub_f32_e32 v5, v5, v3
	v_add_f32_e32 v12, v11, v2
	v_fma_f32 v6, v2, v8, -v4
	v_add_f32_e32 v1, v1, v5
	v_sub_f32_e32 v5, v12, v11
	v_fmac_f32_e32 v6, v2, v10
	v_sub_f32_e32 v8, v2, v5
	v_add_f32_e32 v2, v4, v6
	v_sub_f32_e32 v5, v3, v2
	v_mov_b32_e32 v7, v2
	v_pk_add_f32 v[2:3], v[2:3], v[4:5] neg_lo:[0,1] neg_hi:[0,1]
	v_cmp_lt_f32_e64 s[0:1], |v15|, s20
	v_pk_add_f32 v[2:3], v[2:3], v[6:7] neg_lo:[0,1] neg_hi:[0,1]
	s_lshl_b32 s28, s19, 7
	v_add_f32_e32 v1, v1, v3
	v_add_f32_e32 v1, v2, v1
	v_add_f32_e32 v1, v5, v1
	v_mul_f32_e32 v1, v9, v1
	v_add_f32_e32 v1, v8, v1
	v_add_f32_e32 v2, v12, v1
	v_mul_f32_e32 v4, v2, v2
	v_sub_f32_e32 v5, v2, v12
	v_fmamk_f32 v6, v4, 0x3e9b6dac, v83
	v_sub_f32_e32 v5, v1, v5
	v_mul_f32_e32 v1, v2, v4
	v_fmaak_f32 v73, v4, v6, 0x3f2aaada
	v_ldexp_f32 v7, v5, 1
	v_pk_mul_f32 v[4:5], v[0:1], v[72:73]
	v_ldexp_f32 v3, v2, 1
	v_fma_f32 v2, v0, s5, -v4
	v_fmac_f32_e32 v2, 0xb102e308, v0
	v_pk_add_f32 v[0:1], v[4:5], v[2:3]
	v_mov_b32_e32 v6, v4
	v_sub_f32_e32 v10, v1, v3
	v_pk_add_f32 v[8:9], v[0:1], v[4:5] neg_lo:[0,1] neg_hi:[0,1]
	v_sub_f32_e32 v5, v5, v10
	v_add_f32_e32 v7, v7, v5
	v_pk_add_f32 v[12:13], v[0:1], v[6:7]
	v_mov_b32_e32 v3, v0
	v_mov_b32_e32 v9, v13
	v_pk_add_f32 v[18:19], v[2:3], v[8:9] neg_lo:[0,1] neg_hi:[0,1]
	v_pk_add_f32 v[2:3], v[2:3], v[8:9]
	v_mov_b32_e32 v4, v1
	v_mov_b32_e32 v11, v0
	v_pk_add_f32 v[0:1], v[2:3], v[0:1] op_sel:[1,0] op_sel_hi:[0,1] neg_lo:[0,1] neg_hi:[0,1]
	v_mov_b32_e32 v10, v7
	v_mov_b32_e32 v6, v13
	v_mov_b32_e32 v7, v3
	v_mov_b32_e32 v5, v0
	v_pk_add_f32 v[8:9], v[12:13], v[0:1] op_sel_hi:[1,0] neg_lo:[0,1] neg_hi:[0,1]
	v_pk_add_f32 v[0:1], v[6:7], v[4:5] neg_lo:[0,1] neg_hi:[0,1]
	v_mov_b32_e32 v8, v18
	v_pk_add_f32 v[0:1], v[10:11], v[0:1] neg_lo:[0,1] neg_hi:[0,1]
	v_mov_b32_e32 v19, v3
	v_pk_add_f32 v[4:5], v[8:9], v[0:1]
	s_ashr_i32 s29, s28, 31
	v_pk_add_f32 v[6:7], v[4:5], v[4:5] op_sel:[0,1] op_sel_hi:[1,0]
	s_mul_i32 s17, s18, 5
	v_pk_add_f32 v[2:3], v[2:3], v[6:7] op_sel:[1,0] op_sel_hi:[0,1]
	v_mov_b32_e32 v5, v2
	v_mov_b32_e32 v1, v6
	v_pk_add_f32 v[6:7], v[4:5], v[18:19] neg_lo:[0,1] neg_hi:[0,1]
	s_nop 0
	v_sub_f32_e32 v3, v4, v6
	v_pk_add_f32 v[0:1], v[0:1], v[6:7] neg_lo:[0,1] neg_hi:[0,1]
	v_sub_f32_e32 v3, v18, v3
	v_add_f32_e32 v0, v0, v3
	v_add_f32_e32 v0, v0, v1
	v_add_f32_e32 v0, v2, v0
	v_cndmask_b32_e32 v0, v84, v0, vcc
	v_cmp_neq_f32_e32 vcc, 1.0, v15
	s_nop 1
	v_cndmask_b32_e32 v0, v85, v0, vcc
	v_cndmask_b32_e64 v15, v0, -v15, s[0:1]
	v_add_f32_e32 v0, -1.0, v20
	v_add_f32_e32 v1, 1.0, v0
	v_sub_f32_e32 v1, v20, v1
	v_add_f32_e32 v2, v21, v1
	v_add_f32_e32 v1, 1.0, v20
	v_add_f32_e32 v3, -1.0, v1
	v_sub_f32_e32 v3, v20, v3
	v_add_f32_e32 v3, v21, v3
	v_add_f32_e32 v8, v1, v3
	v_rcp_f32_e32 v10, v8
	v_sub_f32_e32 v1, v8, v1
; DI float ret_lg2(const Params& p, int l, int dir, int h) { return log1pf(-exp2f(p.in[12][(l * 2 + dir) * 5 + h])) * 1.4426950408889634f; }
; DI void ret_out_item(const Params& p, int l, int b, int h, int c, LAS unsigned char* lds) {
;     ...
;     const float lgf = ret_lg2(p, l, 0, h), lgb = ret_lg2(p, l, 1, h);
;     const size_t rowb = (size_t)b * RB; const int tok0 = c * 128, tl = wid * 16 + r16;
;     const size_t row = rowb + tok0 + tl;
;     constexpr int RS = 272, MB = 128 * RS;
;     {
;         const bf16_t* Sf = (const bf16_t*)(ws + WS_S) + ((size_t)((b * 5 + h) * 2 + 0) * 18 + c) * 16384;
;         const bf16_t* Sb = (const bf16_t*)(ws + WS_S) + ((size_t)((b * 5 + h) * 2 + 1) * 18 + c) * 16384;
;         const bf16_t* Kc = P + (rowb + tok0) * INP + C_RK + h * 128;
;         const bf16_t* Vc = (const bf16_t*)(ws + WS_VTR) + ((size_t)b * 640 + h * 128) * RB + tok0;
;         u32x4 t0[4], t1[4], t2[4], t3[4];
; #pragma unroll
;         for (int i = 0; i < 4; ++i) {
;             const int cid = tid + i * 512, rr = cid >> 4, cc = cid & 15;
;             t0[i] = *(const u32x4*)(Sf + rr * 128 + cc * 8); t1[i] = *(const u32x4*)(Sb + rr * 128 + cc * 8);
;             t2[i] = *(const u32x4*)(Kc + (size_t)rr * INP + cc * 8); t3[i] = *(const u32x4*)(Vc + (size_t)rr * RB + cc * 8);
;         }
	v_sub_f32_e32 v9, v3, v1
	v_add_f32_e32 v1, v0, v2
	v_sub_f32_e32 v0, v1, v0
	v_mul_f32_e32 v12, v1, v10
	v_sub_f32_e32 v11, v2, v0
	v_mul_f32_e32 v2, v8, v12
	v_fma_f32 v4, v12, v8, -v2
	v_fmac_f32_e32 v4, v12, v9
	v_add_f32_e32 v0, v2, v4
	v_sub_f32_e32 v3, v1, v0
	v_pk_add_f32 v[6:7], v[0:1], v[2:3] neg_lo:[0,1] neg_hi:[0,1]
	v_mov_b32_e32 v5, v0
	v_pk_add_f32 v[0:1], v[6:7], v[4:5] neg_lo:[0,1] neg_hi:[0,1]
	s_mul_i32 s0, s18, 0x900
	v_add_f32_e32 v1, v11, v1
	v_add_f32_e32 v0, v0, v1
	v_add_f32_e32 v1, v3, v0
	v_mul_f32_e32 v11, v10, v1
	v_mul_f32_e32 v2, v8, v11
	v_fma_f32 v4, v11, v8, -v2
	v_fmac_f32_e32 v4, v11, v9
	v_sub_f32_e32 v3, v3, v1
	v_add_f32_e32 v8, v0, v3
	v_add_f32_e32 v0, v2, v4
	v_sub_f32_e32 v3, v1, v0
	v_pk_add_f32 v[6:7], v[0:1], v[2:3] neg_lo:[0,1] neg_hi:[0,1]
	v_mov_b32_e32 v5, v0
	v_pk_add_f32 v[0:1], v[6:7], v[4:5] neg_lo:[0,1] neg_hi:[0,1]
	s_mul_hi_i32 s1, s18, 0x900
	v_add_f32_e32 v1, v8, v1
	v_add_f32_e32 v0, v0, v1
	v_add_f32_e32 v1, v12, v11
	s_add_u32 s0, s0, s28
	v_add_f32_e32 v0, v3, v0
	v_sub_f32_e32 v2, v1, v12
	s_addc_u32 s1, s1, s29
	s_add_i32 s17, s17, s16
	v_mul_f32_e32 v0, v10, v0
	v_sub_f32_e32 v2, v11, v2
	s_lshl_b32 s56, s17, 1
	s_mul_i32 s17, s17, 36
	s_ashr_i32 s57, s19, 31
	v_add_f32_e32 v2, v2, v0
	s_mul_hi_i32 s55, s56, 18
	s_add_u32 s54, s17, s19
	v_add_f32_e32 v4, v1, v2
	s_addc_u32 s55, s55, s57
	v_mul_f32_e32 v5, v4, v4
	s_lshl_b64 s[54:55], s[54:55], 15
	v_fmamk_f32 v0, v5, 0x3e9b6dac, v83
	s_add_u32 s54, s92, s54
	v_fmaak_f32 v73, v5, v0, 0x3f2aaada
	v_cvt_f32_i32_e32 v0, v17
	s_addc_u32 s55, s93, s55
	s_or_b32 s17, s56, 1
	v_sub_f32_e32 v1, v4, v1
	s_mul_hi_i32 s62, s17, 18
	s_mul_i32 s17, s17, 18
	v_sub_f32_e32 v1, v2, v1
	s_add_u32 s56, s17, s19
	v_ldexp_f32 v8, v1, 1
	v_mul_f32_e32 v1, v4, v5
	s_addc_u32 s57, s62, s57
	v_pk_mul_f32 v[6:7], v[0:1], v[72:73]
	s_lshl_b64 s[56:57], s[56:57], 15
	v_fma_f32 v2, v0, s5, -v6
	s_add_u32 s56, s92, s56
	s_mul_i32 s17, s1, 0x3000
	s_mul_hi_u32 s19, s0, 0x3000
	v_ldexp_f32 v3, v4, 1
	v_fmac_f32_e32 v2, 0xb102e308, v0
	s_addc_u32 s57, s93, s57
	s_add_i32 s19, s19, s17
	s_mul_i32 s17, s0, 0x3000
	v_pk_add_f32 v[4:5], v[6:7], v[2:3]
	s_add_u32 s68, s6, s17
	v_sub_f32_e32 v0, v5, v3
	s_addc_u32 s19, s7, s19
	s_lshl_b32 s62, s16, 7
	v_sub_f32_e32 v0, v7, v0
	s_ashr_i32 s63, s62, 31
	v_add_f32_e32 v9, v8, v0
	v_mov_b32_e32 v8, v6
	s_lshl_b64 s[16:17], s[62:63], 1
	v_pk_add_f32 v[0:1], v[4:5], v[6:7] neg_lo:[0,1] neg_hi:[0,1]
	v_pk_add_f32 v[66:67], v[4:5], v[8:9]
	s_add_u32 s68, s68, s16
	v_mov_b32_e32 v1, v67
	v_mov_b32_e32 v3, v4
	s_addc_u32 s69, s19, s17
	s_mul_hi_i32 s19, s18, 0x280
	s_mulk_i32 s18, 0x280
	v_pk_add_f32 v[10:11], v[2:3], v[0:1]
	s_add_u32 s18, s18, s62
	v_pk_add_f32 v[6:7], v[2:3], v[0:1] neg_lo:[0,1] neg_hi:[0,1]
	v_pk_add_f32 v[0:1], v[10:11], v[4:5] op_sel:[1,0] op_sel_hi:[0,1] neg_lo:[0,1] neg_hi:[0,1]
	s_addc_u32 s19, s19, s63
	v_pk_add_f32 v[12:13], v[66:67], v[0:1] op_sel_hi:[1,0] neg_lo:[0,1] neg_hi:[0,1]
	s_mulk_i32 s19, 0x1200
	s_mul_hi_u32 s62, s18, 0x1200
	v_lshlrev_b32_e32 v1, 4, v16
	s_add_i32 s62, s62, s19
	s_mulk_i32 s18, 0x1200
	v_and_b32_e32 v68, 0xf0, v1
	s_add_u32 s63, s87, s18
	v_lshl_add_u64 v[18:19], s[68:69], 0, v[68:69]
	v_ashrrev_i32_e32 v17, 4, v16
	s_addc_u32 s62, s91, s62
	s_lshl_b64 s[18:19], s[28:29], 1
	v_lshl_add_u64 v[76:77], v[18:19], 0, s[8:9]
	v_lshlrev_b32_e32 v18, 7, v17
	s_add_u32 s18, s63, s18
	v_ashrrev_i32_e32 v19, 31, v18
	v_add_u32_e32 v1, 0x200, v16
	s_addc_u32 s19, s62, s19
	v_lshl_add_u64 v[2:3], s[54:55], 0, v[68:69]
	v_lshl_add_u64 v[74:75], s[56:57], 0, v[68:69]
	v_lshlrev_b64 v[18:19], 1, v[18:19]
	v_ashrrev_i32_e32 v73, 4, v1
	v_lshl_add_u64 v[78:79], s[18:19], 0, v[68:69]
	v_lshl_add_u64 v[20:21], v[2:3], 0, v[18:19]
	v_lshl_add_u64 v[22:23], v[74:75], 0, v[18:19]
	v_lshlrev_b32_e32 v34, 7, v73
	global_load_dwordx4 v[18:21], v[20:21], off
	s_nop 0
	global_load_dwordx4 v[22:25], v[22:23], off
	v_mad_i64_i32 v[26:27], s[18:19], v17, s21, v[76:77]
	v_mad_i64_i32 v[30:31], s[18:19], v17, s22, v[78:79]
	v_ashrrev_i32_e32 v35, 31, v34
	v_add_u32_e32 v1, 0x400, v16
	global_load_dwordx4 v[26:29], v[26:27], off
	s_nop 0
	global_load_dwordx4 v[30:33], v[30:31], off
	v_lshlrev_b64 v[34:35], 1, v[34:35]
	v_ashrrev_i32_e32 v93, 4, v1
	v_lshl_add_u64 v[36:37], v[2:3], 0, v[34:35]
	v_lshl_add_u64 v[38:39], v[74:75], 0, v[34:35]
	v_lshlrev_b32_e32 v50, 7, v93
	global_load_dwordx4 v[34:37], v[36:37], off
	s_nop 0
	global_load_dwordx4 v[38:41], v[38:39], off
	v_mad_i64_i32 v[42:43], s[18:19], v73, s21, v[76:77]
	v_mad_i64_i32 v[46:47], s[18:19], v73, s22, v[78:79]
	v_ashrrev_i32_e32 v51, 31, v50
	v_add_u32_e32 v1, 0x600, v16
	global_load_dwordx4 v[42:45], v[42:43], off
	s_nop 0
	global_load_dwordx4 v[46:49], v[46:47], off
	v_lshlrev_b64 v[50:51], 1, v[50:51]
	v_ashrrev_i32_e32 v114, 4, v1
	v_lshl_add_u64 v[52:53], v[2:3], 0, v[50:51]
	v_lshl_add_u64 v[54:55], v[74:75], 0, v[50:51]
	v_lshlrev_b32_e32 v80, 7, v114
	global_load_dwordx4 v[50:53], v[52:53], off
	s_nop 0
	global_load_dwordx4 v[54:57], v[54:55], off
	v_mad_i64_i32 v[58:59], s[18:19], v93, s21, v[76:77]
	v_mad_i64_i32 v[62:63], s[18:19], v93, s22, v[78:79]
	v_ashrrev_i32_e32 v81, 31, v80
	global_load_dwordx4 v[58:61], v[58:59], off
	s_nop 0
	global_load_dwordx4 v[62:65], v[62:63], off
	v_lshlrev_b64 v[80:81], 1, v[80:81]
	v_lshl_add_u64 v[2:3], v[2:3], 0, v[80:81]
	v_lshl_add_u64 v[74:75], v[74:75], 0, v[80:81]
	global_load_dwordx4 v[94:97], v[2:3], off
	global_load_dwordx4 v[98:101], v[74:75], off
	v_mad_i64_i32 v[2:3], s[18:19], v114, s21, v[76:77]
	global_load_dwordx4 v[102:105], v[2:3], off
	v_mad_i64_i32 v[2:3], s[18:19], v114, s22, v[78:79]
; #define LAS __attribute__((address_space(3)))
; DI void ret_out_item(const Params& p, int l, int b, int h, int c, LAS unsigned char* lds) {
;     ...
;         for (int i = 0; i < 4; ++i) {
;             const int cid = tid + i * 512, rr = cid >> 4, cc = cid & 15;
;             *(LAS u32x4*)(lds + 0 * MB + rr * RS + cc * 16) = t0[i]; *(LAS u32x4*)(lds + 1 * MB + rr * RS + cc * 16) = t1[i];
;             *(LAS u32x4*)(lds + 2 * MB + rr * RS + cc * 16) = t2[i]; *(LAS u32x4*)(lds + 3 * MB + rr * RS + cc * 16) = t3[i];
;         }
;     }
;     bf16x8 qf[4], qff[4], qfb[4];
;     const float qdf = exp2f(lgf * (float)(tl + 1)), qdb = exp2f(lgb * (float)(128 - tl));
; #pragma unroll
;     for (int ks = 0; ks < 4; ++ks) { qf[ks] = *(const bf16x8*)(P + row * INP + C_RQ + h * 128 + ks * 32 + q4 * 8); qff[ks] = scale1_bf16x8(qf[ks], qdf); qfb[ks] = scale1_bf16x8(qf[ks], qdb); }
	v_mov_b32_e32 v111, v0
	v_ashrrev_i32_e32 v0, 2, v16
	global_load_dwordx4 v[106:109], v[2:3], off
	v_bfi_b32 v78, -16, v0, v16
	v_ashrrev_i32_e32 v79, 31, v78
	v_lshl_add_u64 v[74:75], s[0:1], 0, v[78:79]
	v_mad_u64_u32 v[0:1], s[0:1], v74, s21, v[70:71]
	v_mad_i32_i24 v1, v75, s21, v1
	v_lshlrev_b32_e32 v80, 4, v92
	v_mov_b32_e32 v81, v69
	v_lshl_add_u64 v[76:77], v[0:1], 0, s[16:17]
	v_lshl_add_u64 v[112:113], v[76:77], 0, v[80:81]
	v_add_co_u32_e32 v0, vcc, s31, v112
	v_mov_b32_e32 v66, v67
	s_nop 0
	v_addc_co_u32_e32 v1, vcc, 0, v113, vcc
	global_load_dwordx4 v[120:123], v[0:1], off offset:2752
	global_load_dwordx4 v[124:127], v[0:1], off offset:2816
	global_load_dwordx4 v[128:131], v[0:1], off offset:2880
	global_load_dwordx4 v[0:3], v[0:1], off offset:2688
	v_mov_b32_e32 v67, v11
	v_mov_b32_e32 v110, v5
	v_pk_add_f32 v[66:67], v[66:67], v[110:111] neg_lo:[0,1] neg_hi:[0,1]
	v_mov_b32_e32 v8, v9
	v_mov_b32_e32 v9, v4
	v_pk_add_f32 v[4:5], v[8:9], v[66:67] neg_lo:[0,1] neg_hi:[0,1]
	v_mov_b32_e32 v12, v6
	v_pk_add_f32 v[8:9], v[12:13], v[4:5]
	v_mov_b32_e32 v7, v11
	v_pk_add_f32 v[12:13], v[8:9], v[8:9] op_sel:[0,1] op_sel_hi:[1,0]
	v_cmp_nlt_f32_e32 vcc, 1.0, v14
	v_pk_add_f32 v[10:11], v[10:11], v[12:13] op_sel:[1,0] op_sel_hi:[0,1]
	v_mov_b32_e32 v9, v10
	v_pk_add_f32 v[66:67], v[8:9], v[6:7] neg_lo:[0,1] neg_hi:[0,1]
	v_mov_b32_e32 v5, v12
	v_sub_f32_e32 v7, v8, v66
	v_pk_add_f32 v[4:5], v[4:5], v[66:67] neg_lo:[0,1] neg_hi:[0,1]
	v_sub_f32_e32 v6, v6, v7
	v_add_f32_e32 v4, v4, v6
	v_add_f32_e32 v4, v4, v5
	v_add_u32_e32 v5, 0, v68
	v_mul_lo_u32 v8, v17, s30
	v_add_u32_e32 v6, s23, v68
	v_add_u32_e32 v7, s27, v68
	v_add_u32_e32 v9, v5, v8
	s_waitcnt vmcnt(19)
	ds_write_b128 v9, v[18:21]
	s_waitcnt vmcnt(18)
	ds_write_b128 v9, v[22:25] offset:34816
	v_add_u32_e32 v9, v6, v8
	v_add_u32_e32 v8, v7, v8
	s_waitcnt vmcnt(16)
	ds_write_b128 v8, v[30:33]
	v_mul_lo_u32 v8, v73, s30
	ds_write_b128 v9, v[26:29]
	v_add_u32_e32 v9, v5, v8
	s_waitcnt vmcnt(15)
	ds_write_b128 v9, v[34:37]
	s_waitcnt vmcnt(14)
	ds_write_b128 v9, v[38:41] offset:34816
	v_add_u32_e32 v9, v6, v8
	v_add_u32_e32 v8, v7, v8
	v_add_f32_e32 v4, v10, v4
	v_cndmask_b32_e32 v4, v84, v4, vcc
	v_cmp_neq_f32_e32 vcc, 1.0, v14
	s_waitcnt vmcnt(13)
	ds_write_b128 v9, v[42:45]
	s_waitcnt vmcnt(12)
	ds_write_b128 v8, v[46:49]
	v_mul_lo_u32 v8, v93, s30
	v_add_u32_e32 v9, v5, v8
	s_waitcnt vmcnt(11)
	ds_write_b128 v9, v[50:53]
	s_waitcnt vmcnt(10)
	ds_write_b128 v9, v[54:57] offset:34816
	v_add_u32_e32 v9, v6, v8
	v_add_u32_e32 v8, v7, v8
	v_cndmask_b32_e32 v4, v85, v4, vcc
	v_cmp_lt_f32_e64 s[0:1], |v14|, s20
	s_waitcnt vmcnt(9)
	ds_write_b128 v9, v[58:61]
	s_waitcnt vmcnt(8)
	ds_write_b128 v8, v[62:65]
	v_mul_lo_u32 v8, v114, s30
	v_add_u32_e32 v5, v5, v8
	s_waitcnt vmcnt(7)
	ds_write_b128 v5, v[94:97]
	s_waitcnt vmcnt(6)
	ds_write_b128 v5, v[98:101] offset:34816
	v_add_u32_e32 v5, v6, v8
	v_add_u32_e32 v6, v7, v8
	s_waitcnt vmcnt(5)
	ds_write_b128 v5, v[102:105]
	v_add_u32_e32 v5, 1, v78
	v_cvt_f32_i32_e32 v5, v5
	v_sub_u32_e32 v7, 0x80, v78
	v_cvt_f32_i32_e32 v7, v7
	v_cndmask_b32_e64 v4, v4, -v14, s[0:1]
	v_mul_f32_e32 v79, 0x3fb8aa3b, v15
	s_waitcnt vmcnt(4)
	ds_write_b128 v6, v[106:109]
	v_mul_f32_e32 v6, v79, v5
	v_mul_f32_e32 v73, 0xbfb8aa3b, v4
	v_cmp_gt_f32_e32 vcc, s3, v6
	v_mul_f32_e64 v4, -v73, v7
	v_cmp_gt_f32_e64 s[0:1], s3, v4
	v_cndmask_b32_e32 v6, 0, v82, vcc
	v_fmac_f32_e32 v6, v79, v5
	v_cndmask_b32_e64 v4, 0, v82, s[0:1]
	v_exp_f32_e32 v5, v6
	v_fma_f32 v4, -v73, v7, v4
	v_exp_f32_e32 v4, v4
	v_cndmask_b32_e32 v6, 0, v86, vcc
	v_ldexp_f32 v17, v5, v6
	v_cndmask_b32_e64 v5, 0, v86, s[0:1]
	v_ldexp_f32 v19, v4, v5
	s_waitcnt vmcnt(0)
	v_lshlrev_b32_e32 v4, 16, v0
	v_mul_f32_e32 v5, v17, v4
	v_and_b32_e32 v6, 0xffff0000, v0
	v_mul_f32_e32 v7, v17, v6
	v_cvt_pk_bf16_f32 v48, v5, v7
	v_lshlrev_b32_e32 v5, 16, v1
	v_mul_f32_e32 v7, v17, v5
	v_and_b32_e32 v8, 0xffff0000, v1
	v_mul_f32_e32 v9, v17, v8
	v_cvt_pk_bf16_f32 v49, v7, v9
	v_lshlrev_b32_e32 v7, 16, v2
	v_mul_f32_e32 v9, v17, v7
	v_and_b32_e32 v10, 0xffff0000, v2
	v_mul_f32_e32 v11, v17, v10
	v_cvt_pk_bf16_f32 v50, v9, v11
	v_lshlrev_b32_e32 v9, 16, v3
	v_and_b32_e32 v14, 0xffff0000, v3
	v_mul_f32_e32 v4, v19, v4
	v_mul_f32_e32 v11, v17, v9
	v_mul_f32_e32 v15, v17, v14
	v_cvt_pk_bf16_f32 v51, v11, v15
	v_mul_f32_e32 v6, v19, v6
	v_cvt_pk_bf16_f32 v52, v4, v6
	v_mul_f32_e32 v4, v19, v5
	v_mul_f32_e32 v5, v19, v8
	v_cvt_pk_bf16_f32 v53, v4, v5
	v_mul_f32_e32 v4, v19, v7
	v_mul_f32_e32 v5, v19, v10
	v_lshl_add_u64 v[12:13], v[112:113], 0, s[10:11]
	v_cvt_pk_bf16_f32 v54, v4, v5
	v_mul_f32_e32 v4, v19, v9
	v_mul_f32_e32 v5, v19, v14
	v_cvt_pk_bf16_f32 v55, v4, v5
	s_waitcnt vmcnt(0)
	v_mov_b32_e32 v4, v120
	v_mov_b32_e32 v5, v121
	v_mov_b32_e32 v6, v122
	v_mov_b32_e32 v7, v123
	v_lshlrev_b32_e32 v8, 16, v4
	v_mul_f32_e32 v9, v17, v8
	v_and_b32_e32 v10, 0xffff0000, v4
	v_mul_f32_e32 v11, v17, v10
	v_cvt_pk_bf16_f32 v56, v9, v11
	v_lshlrev_b32_e32 v9, 16, v5
	v_mul_f32_e32 v11, v17, v9
	v_and_b32_e32 v14, 0xffff0000, v5
	v_mul_f32_e32 v15, v17, v14
	v_cvt_pk_bf16_f32 v57, v11, v15
	v_lshlrev_b32_e32 v11, 16, v6
	v_mul_f32_e32 v15, v17, v11
	v_and_b32_e32 v18, 0xffff0000, v6
	v_mul_f32_e32 v20, v17, v18
	v_cvt_pk_bf16_f32 v58, v15, v20
	v_lshlrev_b32_e32 v15, 16, v7
	v_and_b32_e32 v21, 0xffff0000, v7
	v_mul_f32_e32 v8, v19, v8
	v_mul_f32_e32 v20, v17, v15
	v_mul_f32_e32 v22, v17, v21
	v_cvt_pk_bf16_f32 v59, v20, v22
	v_mul_f32_e32 v10, v19, v10
	v_cvt_pk_bf16_f32 v60, v8, v10
	v_mul_f32_e32 v8, v19, v9
	v_mul_f32_e32 v9, v19, v14
	v_cvt_pk_bf16_f32 v61, v8, v9
	v_mul_f32_e32 v8, v19, v11
	v_mul_f32_e32 v9, v19, v18
	v_cvt_pk_bf16_f32 v62, v8, v9
	v_mul_f32_e32 v8, v19, v15
	v_mul_f32_e32 v9, v19, v21
	v_cvt_pk_bf16_f32 v63, v8, v9
	s_waitcnt vmcnt(0)
; #define LAS __attribute__((address_space(3)))
; #define MFMA16(a, b, c) __builtin_amdgcn_mfma_f32_16x16x32_bf16((a), (b), (c), 0, 0, 0)
; DI void ret_out_item(const Params& p, int l, int b, int h, int c, LAS unsigned char* lds) {
;     ...
;     for (int ks = 0; ks < 4; ++ks) { qf[ks] = *(const bf16x8*)(P + row * INP + C_RQ + h * 128 + ks * 32 + q4 * 8); qff[ks] = scale1_bf16x8(qf[ks], qdf); qfb[ks] = scale1_bf16x8(qf[ks], qdb); }
;     f32x4 oacc[8];
; #pragma unroll
;     for (int d = 0; d < 8; ++d) oacc[d] = (f32x4){0.f, 0.f, 0.f, 0.f};
;     __syncthreads();
;     const LAS unsigned char* sfp = lds + 0 * MB + r16 * RS + q4 * 16;
;     const LAS unsigned char* sbp = lds + 1 * MB + r16 * RS + q4 * 16;
;     const LAS unsigned char* kcp = lds + 2 * MB + r16 * RS + q4 * 16;
;     const LAS unsigned char* vtp = lds + 3 * MB + r16 * RS + q4 * 8;
; #pragma unroll
;     for (int d = 0; d < 8; ++d)
; #pragma unroll
;         for (int ks = 0; ks < 4; ++ks) {
;             oacc[d] = MFMA16(*(const LAS bf16x8*)(sfp + d * 16 * RS + ks * 64), qff[ks], oacc[d]);
;             oacc[d] = MFMA16(*(const LAS bf16x8*)(sbp + d * 16 * RS + ks * 64), qfb[ks], oacc[d]);
;         }
	v_mov_b32_e32 v8, v124
	v_mov_b32_e32 v9, v125
	v_mov_b32_e32 v10, v126
	v_mov_b32_e32 v11, v127
	v_lshlrev_b32_e32 v14, 16, v8
	v_mul_f32_e32 v15, v17, v14
	v_and_b32_e32 v18, 0xffff0000, v8
	v_mul_f32_e32 v20, v17, v18
	v_cvt_pk_bf16_f32 v64, v15, v20
	v_lshlrev_b32_e32 v15, 16, v9
	v_mul_f32_e32 v20, v17, v15
	v_and_b32_e32 v21, 0xffff0000, v9
	v_mul_f32_e32 v22, v17, v21
	v_cvt_pk_bf16_f32 v65, v20, v22
	v_lshlrev_b32_e32 v20, 16, v10
	v_mul_f32_e32 v22, v17, v20
	v_and_b32_e32 v23, 0xffff0000, v10
	v_mul_f32_e32 v24, v17, v23
	v_cvt_pk_bf16_f32 v66, v22, v24
	v_lshlrev_b32_e32 v22, 16, v11
	v_and_b32_e32 v25, 0xffff0000, v11
	v_mul_f32_e32 v14, v19, v14
	v_mul_f32_e32 v24, v17, v22
	v_mul_f32_e32 v26, v17, v25
	v_cvt_pk_bf16_f32 v67, v24, v26
	v_mul_f32_e32 v18, v19, v18
	v_cvt_pk_bf16_f32 v94, v14, v18
	v_mul_f32_e32 v14, v19, v15
	v_mul_f32_e32 v15, v19, v21
	v_cvt_pk_bf16_f32 v95, v14, v15
	v_mul_f32_e32 v14, v19, v20
	v_mul_f32_e32 v15, v19, v23
	v_cvt_pk_bf16_f32 v96, v14, v15
	v_mul_f32_e32 v14, v19, v22
	v_mul_f32_e32 v15, v19, v25
	v_cvt_pk_bf16_f32 v97, v14, v15
	s_waitcnt vmcnt(0)
	v_mov_b32_e32 v12, v128
	v_mov_b32_e32 v13, v129
	v_mov_b32_e32 v14, v130
	v_mov_b32_e32 v15, v131
	v_and_b32_e32 v20, 15, v16
	v_mul_u32_u24_e32 v81, 0x110, v20
	v_add3_u32 v68, 0, v81, v80
	s_waitcnt vmcnt(0)
	v_lshlrev_b32_e32 v16, 16, v12
	v_mul_f32_e32 v18, v17, v16
	v_and_b32_e32 v21, 0xffff0000, v12
	v_mul_f32_e32 v22, v17, v21
	v_cvt_pk_bf16_f32 v98, v18, v22
	v_lshlrev_b32_e32 v18, 16, v13
	v_mul_f32_e32 v22, v17, v18
	v_and_b32_e32 v23, 0xffff0000, v13
	v_mul_f32_e32 v24, v17, v23
	v_cvt_pk_bf16_f32 v99, v22, v24
	v_lshlrev_b32_e32 v22, 16, v14
	v_mul_f32_e32 v24, v17, v22
	v_and_b32_e32 v25, 0xffff0000, v14
	v_mul_f32_e32 v26, v17, v25
	v_cvt_pk_bf16_f32 v100, v24, v26
	v_lshlrev_b32_e32 v24, 16, v15
	v_and_b32_e32 v27, 0xffff0000, v15
	v_mul_f32_e32 v26, v17, v24
	v_mul_f32_e32 v17, v17, v27
	v_cvt_pk_bf16_f32 v101, v26, v17
	v_mul_f32_e32 v16, v19, v16
	v_mul_f32_e32 v17, v19, v21
	v_cvt_pk_bf16_f32 v16, v16, v17
	v_mul_f32_e32 v17, v19, v18
	v_mul_f32_e32 v18, v19, v23
	v_cvt_pk_bf16_f32 v17, v17, v18
	v_mul_f32_e32 v18, v19, v22
	v_mul_f32_e32 v21, v19, v25
	v_cvt_pk_bf16_f32 v18, v18, v21
	v_mul_f32_e32 v21, v19, v24
	v_mul_f32_e32 v19, v19, v27
	v_cvt_pk_bf16_f32 v19, v21, v19
	s_waitcnt lgkmcnt(0)
	s_barrier
	ds_read_b128 v[20:23], v68
	ds_read_b128 v[24:27], v68 offset:64
	s_waitcnt lgkmcnt(1)
	v_mfma_f32_16x16x32_bf16 v[20:23], v[20:23], v[48:51], 0
	ds_read_b128 v[28:31], v68 offset:34816
	ds_read_b128 v[32:35], v68 offset:34880
	s_waitcnt lgkmcnt(1)
	v_mfma_f32_16x16x32_bf16 v[20:23], v[28:31], v[52:55], v[20:23]
	v_mfma_f32_16x16x32_bf16 v[20:23], v[24:27], v[56:59], v[20:23]
	ds_read_b128 v[24:27], v68 offset:128
	ds_read_b128 v[28:31], v68 offset:192
	s_waitcnt lgkmcnt(2)
	v_mfma_f32_16x16x32_bf16 v[20:23], v[32:35], v[60:63], v[20:23]
	s_waitcnt lgkmcnt(1)
	v_mfma_f32_16x16x32_bf16 v[20:23], v[24:27], v[64:67], v[20:23]
	ds_read_b128 v[24:27], v68 offset:34944
	ds_read_b128 v[32:35], v68 offset:35008
	s_waitcnt lgkmcnt(1)
	v_mfma_f32_16x16x32_bf16 v[20:23], v[24:27], v[94:97], v[20:23]
	v_mfma_f32_16x16x32_bf16 v[20:23], v[28:31], v[98:101], v[20:23]
	ds_read_b128 v[24:27], v68 offset:4352
	ds_read_b128 v[28:31], v68 offset:4416
	s_waitcnt lgkmcnt(2)
	v_mfma_f32_16x16x32_bf16 v[20:23], v[32:35], v[16:19], v[20:23]
	ds_read_b128 v[32:35], v68 offset:39168
	ds_read_b128 v[36:39], v68 offset:39232
	s_waitcnt lgkmcnt(3)
	v_mfma_f32_16x16x32_bf16 v[24:27], v[24:27], v[48:51], 0
	s_waitcnt lgkmcnt(1)
	v_mfma_f32_16x16x32_bf16 v[24:27], v[32:35], v[52:55], v[24:27]
	v_mfma_f32_16x16x32_bf16 v[24:27], v[28:31], v[56:59], v[24:27]
	ds_read_b128 v[28:31], v68 offset:4480
	ds_read_b128 v[32:35], v68 offset:4544
	s_waitcnt lgkmcnt(2)
	v_mfma_f32_16x16x32_bf16 v[24:27], v[36:39], v[60:63], v[24:27]
	s_waitcnt lgkmcnt(1)
	v_mfma_f32_16x16x32_bf16 v[24:27], v[28:31], v[64:67], v[24:27]
	ds_read_b128 v[28:31], v68 offset:39296
	ds_read_b128 v[36:39], v68 offset:39360
	s_waitcnt lgkmcnt(1)
	v_mfma_f32_16x16x32_bf16 v[24:27], v[28:31], v[94:97], v[24:27]
	v_mfma_f32_16x16x32_bf16 v[24:27], v[32:35], v[98:101], v[24:27]
	ds_read_b128 v[28:31], v68 offset:8704
	ds_read_b128 v[32:35], v68 offset:8768
	s_waitcnt lgkmcnt(2)
	v_mfma_f32_16x16x32_bf16 v[24:27], v[36:39], v[16:19], v[24:27]
	ds_read_b128 v[36:39], v68 offset:43520
	ds_read_b128 v[40:43], v68 offset:43584
	s_waitcnt lgkmcnt(3)
	v_mfma_f32_16x16x32_bf16 v[28:31], v[28:31], v[48:51], 0
	s_waitcnt lgkmcnt(1)
	v_mfma_f32_16x16x32_bf16 v[28:31], v[36:39], v[52:55], v[28:31]
	v_mfma_f32_16x16x32_bf16 v[28:31], v[32:35], v[56:59], v[28:31]
	ds_read_b128 v[32:35], v68 offset:8832
	ds_read_b128 v[36:39], v68 offset:8896
	s_waitcnt lgkmcnt(2)
	v_mfma_f32_16x16x32_bf16 v[28:31], v[40:43], v[60:63], v[28:31]
	s_waitcnt lgkmcnt(1)
	v_mfma_f32_16x16x32_bf16 v[28:31], v[32:35], v[64:67], v[28:31]
	ds_read_b128 v[32:35], v68 offset:43648
	ds_read_b128 v[40:43], v68 offset:43712
	s_waitcnt lgkmcnt(1)
	v_mfma_f32_16x16x32_bf16 v[28:31], v[32:35], v[94:97], v[28:31]
	v_mfma_f32_16x16x32_bf16 v[28:31], v[36:39], v[98:101], v[28:31]
	ds_read_b128 v[32:35], v68 offset:13056
	ds_read_b128 v[36:39], v68 offset:13120
	s_waitcnt lgkmcnt(2)
	v_mfma_f32_16x16x32_bf16 v[28:31], v[40:43], v[16:19], v[28:31]
	ds_read_b128 v[40:43], v68 offset:47872
	ds_read_b128 v[44:47], v68 offset:47936
	s_waitcnt lgkmcnt(3)
	v_mfma_f32_16x16x32_bf16 v[32:35], v[32:35], v[48:51], 0
	s_waitcnt lgkmcnt(1)
	v_mfma_f32_16x16x32_bf16 v[32:35], v[40:43], v[52:55], v[32:35]
	v_mfma_f32_16x16x32_bf16 v[32:35], v[36:39], v[56:59], v[32:35]
	ds_read_b128 v[36:39], v68 offset:13184
	ds_read_b128 v[40:43], v68 offset:13248
	s_waitcnt lgkmcnt(2)
; #define LAS __attribute__((address_space(3)))
; #define MFMA16(a, b, c) __builtin_amdgcn_mfma_f32_16x16x32_bf16((a), (b), (c), 0, 0, 0)
; DI void ret_out_item(const Params& p, int l, int b, int h, int c, LAS unsigned char* lds) {
;     ...
; #pragma unroll
;     for (int d = 0; d < 8; ++d)
; #pragma unroll
;         for (int ks = 0; ks < 4; ++ks) {
;             oacc[d] = MFMA16(*(const LAS bf16x8*)(sfp + d * 16 * RS + ks * 64), qff[ks], oacc[d]);
;             oacc[d] = MFMA16(*(const LAS bf16x8*)(sbp + d * 16 * RS + ks * 64), qfb[ks], oacc[d]);
;         }
; #pragma unroll
;     for (int kc = 0; kc < 4; ++kc) {
;         f32x4 s[2];
; #pragma unroll
;         for (int hf = 0; hf < 2; ++hf) {
;             s[hf] = (f32x4){0.f, 0.f, 0.f, 0.f};
; #pragma unroll
;             for (int ks = 0; ks < 4; ++ks) s[hf] = MFMA16(*(const LAS bf16x8*)(kcp + (2 * kc + hf) * 16 * RS + ks * 64), qf[ks], s[hf]);
; #pragma unroll
;             for (int j = 0; j < 4; ++j) {
;                 const int m = (2 * kc + hf) * 16 + q4 * 4 + j, d = tl - m;
;                 const float w = (d >= 0 ? exp2f(lgf * (float)d) : 0.f) + (d <= 0 ? exp2f(-lgb * (float)d) : 0.f);
;                 s[hf][j] *= w;
;             }
	v_mfma_f32_16x16x32_bf16 v[32:35], v[44:47], v[60:63], v[32:35]
	s_waitcnt lgkmcnt(1)
	v_mfma_f32_16x16x32_bf16 v[32:35], v[36:39], v[64:67], v[32:35]
	ds_read_b128 v[36:39], v68 offset:48000
	ds_read_b128 v[44:47], v68 offset:48064
	s_waitcnt lgkmcnt(1)
	v_mfma_f32_16x16x32_bf16 v[32:35], v[36:39], v[94:97], v[32:35]
	v_mfma_f32_16x16x32_bf16 v[32:35], v[40:43], v[98:101], v[32:35]
	ds_read_b128 v[36:39], v68 offset:17408
	ds_read_b128 v[40:43], v68 offset:17472
	s_waitcnt lgkmcnt(2)
	v_mfma_f32_16x16x32_bf16 v[32:35], v[44:47], v[16:19], v[32:35]
	ds_read_b128 v[44:47], v68 offset:52224
	ds_read_b128 v[102:105], v68 offset:52288
	s_waitcnt lgkmcnt(3)
	v_mfma_f32_16x16x32_bf16 v[36:39], v[36:39], v[48:51], 0
	s_waitcnt lgkmcnt(1)
	v_mfma_f32_16x16x32_bf16 v[36:39], v[44:47], v[52:55], v[36:39]
	v_mfma_f32_16x16x32_bf16 v[36:39], v[40:43], v[56:59], v[36:39]
	ds_read_b128 v[40:43], v68 offset:17536
	ds_read_b128 v[44:47], v68 offset:17600
	s_waitcnt lgkmcnt(2)
	v_mfma_f32_16x16x32_bf16 v[36:39], v[102:105], v[60:63], v[36:39]
	s_waitcnt lgkmcnt(1)
	v_mfma_f32_16x16x32_bf16 v[36:39], v[40:43], v[64:67], v[36:39]
	ds_read_b128 v[40:43], v68 offset:52352
	ds_read_b128 v[102:105], v68 offset:52416
	s_waitcnt lgkmcnt(1)
	v_mfma_f32_16x16x32_bf16 v[36:39], v[40:43], v[94:97], v[36:39]
	v_mfma_f32_16x16x32_bf16 v[36:39], v[44:47], v[98:101], v[36:39]
	ds_read_b128 v[40:43], v68 offset:21760
	ds_read_b128 v[44:47], v68 offset:21824
	s_waitcnt lgkmcnt(2)
	v_mfma_f32_16x16x32_bf16 v[36:39], v[102:105], v[16:19], v[36:39]
	ds_read_b128 v[102:105], v68 offset:56576
	ds_read_b128 v[106:109], v68 offset:56640
	s_waitcnt lgkmcnt(3)
	v_mfma_f32_16x16x32_bf16 v[40:43], v[40:43], v[48:51], 0
	s_waitcnt lgkmcnt(1)
	v_mfma_f32_16x16x32_bf16 v[40:43], v[102:105], v[52:55], v[40:43]
	v_mfma_f32_16x16x32_bf16 v[40:43], v[44:47], v[56:59], v[40:43]
	ds_read_b128 v[44:47], v68 offset:21888
	ds_read_b128 v[102:105], v68 offset:21952
	s_waitcnt lgkmcnt(2)
	v_mfma_f32_16x16x32_bf16 v[40:43], v[106:109], v[60:63], v[40:43]
	s_waitcnt lgkmcnt(1)
	v_mfma_f32_16x16x32_bf16 v[40:43], v[44:47], v[64:67], v[40:43]
	ds_read_b128 v[44:47], v68 offset:56704
	ds_read_b128 v[106:109], v68 offset:56768
	s_waitcnt lgkmcnt(1)
	v_mfma_f32_16x16x32_bf16 v[40:43], v[44:47], v[94:97], v[40:43]
	v_mfma_f32_16x16x32_bf16 v[40:43], v[102:105], v[98:101], v[40:43]
	ds_read_b128 v[44:47], v68 offset:26112
	ds_read_b128 v[102:105], v68 offset:26176
	s_waitcnt lgkmcnt(2)
	v_mfma_f32_16x16x32_bf16 v[40:43], v[106:109], v[16:19], v[40:43]
	ds_read_b128 v[106:109], v68 offset:60928
	ds_read_b128 v[110:113], v68 offset:60992
	s_waitcnt lgkmcnt(3)
	v_mfma_f32_16x16x32_bf16 v[44:47], v[44:47], v[48:51], 0
	s_waitcnt lgkmcnt(1)
	v_mfma_f32_16x16x32_bf16 v[44:47], v[106:109], v[52:55], v[44:47]
	v_mfma_f32_16x16x32_bf16 v[44:47], v[102:105], v[56:59], v[44:47]
	ds_read_b128 v[102:105], v68 offset:26240
	ds_read_b128 v[106:109], v68 offset:26304
	s_waitcnt lgkmcnt(2)
	v_mfma_f32_16x16x32_bf16 v[44:47], v[110:113], v[60:63], v[44:47]
	s_waitcnt lgkmcnt(1)
	v_mfma_f32_16x16x32_bf16 v[44:47], v[102:105], v[64:67], v[44:47]
	ds_read_b128 v[102:105], v68 offset:61056
	ds_read_b128 v[110:113], v68 offset:61120
	s_waitcnt lgkmcnt(1)
	v_mfma_f32_16x16x32_bf16 v[44:47], v[102:105], v[94:97], v[44:47]
	v_mfma_f32_16x16x32_bf16 v[44:47], v[106:109], v[98:101], v[44:47]
	ds_read_b128 v[102:105], v68 offset:30464
	ds_read_b128 v[106:109], v68 offset:30528
	s_waitcnt lgkmcnt(2)
	v_mfma_f32_16x16x32_bf16 v[44:47], v[110:113], v[16:19], v[44:47]
	s_waitcnt lgkmcnt(1)
	v_mfma_f32_16x16x32_bf16 v[48:51], v[102:105], v[48:51], 0
	ds_read_b128 v[102:105], v68 offset:65280
	ds_read_b128 v[110:113], v68 offset:65344
	s_waitcnt lgkmcnt(1)
	v_mfma_f32_16x16x32_bf16 v[48:51], v[102:105], v[52:55], v[48:51]
	v_mfma_f32_16x16x32_bf16 v[48:51], v[106:109], v[56:59], v[48:51]
	ds_read_b128 v[52:55], v68 offset:30592
	ds_read_b128 v[56:59], v68 offset:30656
	s_waitcnt lgkmcnt(2)
	v_mfma_f32_16x16x32_bf16 v[48:51], v[110:113], v[60:63], v[48:51]
	v_add3_u32 v62, s23, v81, v80
	v_lshlrev_b32_e32 v61, 2, v92
	v_sub_u32_e32 v63, v78, v61
	s_waitcnt lgkmcnt(1)
	v_mfma_f32_16x16x32_bf16 v[48:51], v[52:55], v[64:67], v[48:51]
	ds_read_b128 v[64:67], v68 offset:65408
	ds_read_b128 v[52:55], v68 offset:65472
	v_cvt_f32_u32_e32 v80, v63
	s_waitcnt lgkmcnt(1)
	v_mfma_f32_16x16x32_bf16 v[48:51], v[64:67], v[94:97], v[48:51]
	ds_read_b128 v[64:67], v62
	ds_read_b128 v[94:97], v62 offset:128
	v_lshlrev_b32_e32 v68, 3, v92
	v_mfma_f32_16x16x32_bf16 v[56:59], v[56:59], v[98:101], v[48:51]
	v_add3_u32 v60, s27, v81, v68
	v_mul_f32_e32 v81, v79, v80
	v_cmp_gt_f32_e32 vcc, s3, v81
	s_nop 0
	ds_read_b128 v[48:51], v62 offset:64
	s_waitcnt lgkmcnt(2)
	v_mfma_f32_16x16x32_bf16 v[64:67], v[64:67], v[0:3], 0
	v_cndmask_b32_e32 v81, 0, v82, vcc
	v_fmac_f32_e32 v81, v79, v80
	v_exp_f32_e32 v80, v81
	s_waitcnt lgkmcnt(0)
	v_mfma_f32_16x16x32_bf16 v[48:51], v[48:51], v[4:7], v[64:67]
	s_nop 2
	ds_read_b128 v[64:67], v62 offset:192
	v_cvt_f32_i32_e32 v81, v63
	v_cmp_lt_i32_e64 s[0:1], -1, v63
	v_mfma_f32_16x16x32_bf16 v[48:51], v[94:97], v[8:11], v[48:51]
	ds_read_b128 v[96:99], v62 offset:4480
	s_waitcnt lgkmcnt(1)
; #define LAS __attribute__((address_space(3)))
; DI unsigned cvt_pk_bf16(float lo, float hi) { unsigned r; asm volatile("v_cvt_pk_bf16_f32 %0, %1, %2" : "=v"(r) : "v"(lo), "v"(hi)); return r; }
; #define MFMA16(a, b, c) __builtin_amdgcn_mfma_f32_16x16x32_bf16((a), (b), (c), 0, 0, 0)
; DI void ret_out_item(const Params& p, int l, int b, int h, int c, LAS unsigned char* lds) {
;     ...
;     for (int kc = 0; kc < 4; ++kc) {
;         f32x4 s[2];
; #pragma unroll
;         for (int hf = 0; hf < 2; ++hf) {
;             s[hf] = (f32x4){0.f, 0.f, 0.f, 0.f};
; #pragma unroll
;             for (int ks = 0; ks < 4; ++ks) s[hf] = MFMA16(*(const LAS bf16x8*)(kcp + (2 * kc + hf) * 16 * RS + ks * 64), qf[ks], s[hf]);
; #pragma unroll
;             for (int j = 0; j < 4; ++j) {
;                 const int m = (2 * kc + hf) * 16 + q4 * 4 + j, d = tl - m;
;                 const float w = (d >= 0 ? exp2f(lgf * (float)d) : 0.f) + (d <= 0 ? exp2f(-lgb * (float)d) : 0.f);
;                 s[hf][j] *= w;
;             }
;         }
;         u32x4 w4; w4.x = cvt_pk_bf16(s[0][0], s[0][1]); w4.y = cvt_pk_bf16(s[0][2], s[0][3]); w4.z = cvt_pk_bf16(s[1][0], s[1][1]); w4.w = cvt_pk_bf16(s[1][2], s[1][3]);
;         const bf16x8 pb = __builtin_bit_cast(bf16x8, w4);
; #pragma unroll
;         for (int d = 0; d < 8; ++d) {
;             const u32x2 lo = *(const LAS u32x2*)(vtp + d * 16 * RS + kc * 64), hi = *(const LAS u32x2*)(vtp + d * 16 * RS + kc * 64 + 32);
;             u32x4 a4; a4.x = lo.x; a4.y = lo.y; a4.z = hi.x; a4.w = hi.y;
;             oacc[d] = MFMA16(__builtin_bit_cast(bf16x8, a4), pb, oacc[d]);
;         }
	v_mfma_f32_16x16x32_bf16 v[48:51], v[64:67], v[12:15], v[48:51]
	v_mul_f32_e32 v65, v81, v73
	v_cndmask_b32_e32 v64, 0, v86, vcc
	v_cmp_gt_f32_e32 vcc, s3, v65
	v_ldexp_f32 v64, v80, v64
	v_cndmask_b32_e64 v64, 0, v64, s[0:1]
	v_cndmask_b32_e32 v65, 0, v82, vcc
	v_fmac_f32_e32 v65, v81, v73
	v_exp_f32_e32 v65, v65
	v_cndmask_b32_e32 v66, 0, v86, vcc
	v_cmp_gt_i32_e32 vcc, 1, v63
	v_mfma_f32_16x16x32_bf16 v[52:55], v[52:55], v[16:19], v[56:59]
	v_ldexp_f32 v65, v65, v66
	v_xad_u32 v66, v61, -1, v78
	v_cvt_f32_u32_e32 v67, v66
	v_cndmask_b32_e32 v63, 0, v65, vcc
	v_add_f32_e32 v63, v64, v63
	v_cvt_f32_i32_e32 v65, v66
	v_mul_f32_e32 v64, v79, v67
	v_cmp_gt_f32_e32 vcc, s3, v64
	v_mul_f32_e32 v63, v63, v48
	v_cmp_lt_i32_e64 s[0:1], -1, v66
	v_cndmask_b32_e32 v64, 0, v82, vcc
	v_fmac_f32_e32 v64, v79, v67
	v_exp_f32_e32 v64, v64
	v_cndmask_b32_e32 v48, 0, v86, vcc
	v_ldexp_f32 v48, v64, v48
	v_mul_f32_e32 v64, v65, v73
	v_cmp_gt_f32_e32 vcc, s3, v64
	v_cndmask_b32_e64 v48, 0, v48, s[0:1]
	s_nop 0
	v_cndmask_b32_e32 v64, 0, v82, vcc
	v_fmac_f32_e32 v64, v65, v73
	v_exp_f32_e32 v64, v64
	v_cndmask_b32_e32 v65, 0, v86, vcc
	v_cmp_gt_i32_e32 vcc, 1, v66
	v_ldexp_f32 v64, v64, v65
	v_or_b32_e32 v65, 2, v61
	v_sub_u32_e32 v65, v78, v65
	v_cvt_f32_u32_e32 v67, v65
	v_cvt_f32_i32_e32 v66, v65
	v_cndmask_b32_e32 v64, 0, v64, vcc
	v_add_f32_e32 v48, v48, v64
	v_mul_f32_e32 v64, v79, v67
	v_cmp_gt_f32_e32 vcc, s3, v64
	v_mul_f32_e32 v80, v48, v49
	v_mul_f32_e32 v49, v66, v73
	v_cndmask_b32_e32 v64, 0, v82, vcc
	v_cndmask_b32_e32 v48, 0, v86, vcc
	v_cmp_gt_f32_e32 vcc, s3, v49
	v_fmac_f32_e32 v64, v79, v67
	v_exp_f32_e32 v64, v64
	v_cndmask_b32_e32 v49, 0, v82, vcc
	v_fmac_f32_e32 v49, v66, v73
	v_exp_f32_e32 v49, v49
	v_ldexp_f32 v48, v64, v48
	v_cndmask_b32_e32 v64, 0, v86, vcc
	v_cmp_lt_i32_e64 s[0:1], -1, v65
	v_ldexp_f32 v49, v49, v64
	v_or_b32_e32 v64, 3, v61
	v_sub_u32_e32 v81, v78, v64
	v_cvt_f32_u32_e32 v64, v81
	v_cmp_gt_i32_e32 vcc, 1, v65
	v_cndmask_b32_e64 v48, 0, v48, s[0:1]
	v_cvt_f32_i32_e32 v92, v81
	v_cndmask_b32_e32 v49, 0, v49, vcc
	v_add_f32_e32 v48, v48, v49
	v_mul_f32_e32 v49, v79, v64
	v_cmp_gt_f32_e32 vcc, s3, v49
	v_mul_f32_e32 v100, v48, v50
	v_cmp_lt_i32_e64 s[0:1], -1, v81
	v_cndmask_b32_e32 v49, 0, v82, vcc
	v_fmac_f32_e32 v49, v79, v64
	v_exp_f32_e32 v49, v49
	v_cndmask_b32_e32 v48, 0, v86, vcc
	ds_read_b128 v[64:67], v62 offset:4352
	v_ldexp_f32 v48, v49, v48
	v_mul_f32_e32 v49, v92, v73
	v_cmp_gt_f32_e32 vcc, s3, v49
	v_cndmask_b32_e64 v48, 0, v48, s[0:1]
	s_nop 0
	v_cndmask_b32_e32 v49, 0, v82, vcc
	v_fmac_f32_e32 v49, v92, v73
	ds_read_b128 v[92:95], v62 offset:4416
	v_exp_f32_e32 v49, v49
	v_cndmask_b32_e32 v50, 0, v86, vcc
	s_waitcnt lgkmcnt(1)
	v_mfma_f32_16x16x32_bf16 v[64:67], v[64:67], v[0:3], 0
	v_cmp_gt_i32_e32 vcc, 1, v81
	v_ldexp_f32 v49, v49, v50
	s_nop 0
	v_cndmask_b32_e32 v49, 0, v49, vcc
	v_add_f32_e32 v48, v48, v49
	v_or_b32_e32 v49, 16, v61
	v_sub_u32_e32 v81, v78, v49
	s_waitcnt lgkmcnt(0)
	v_mfma_f32_16x16x32_bf16 v[64:67], v[92:95], v[4:7], v[64:67]
	v_cvt_f32_u32_e32 v101, v81
	ds_read_b128 v[92:95], v62 offset:4544
	v_mul_f32_e32 v102, v48, v51
	v_mfma_f32_16x16x32_bf16 v[48:51], v[96:99], v[8:11], v[64:67]
	v_cmp_lt_i32_e64 s[0:1], -1, v81
	s_nop 2
	v_mul_f32_e32 v64, v79, v101
	v_cmp_gt_f32_e32 vcc, s3, v64
	v_cvt_f32_i32_e32 v65, v81
	s_waitcnt lgkmcnt(0)
	v_mfma_f32_16x16x32_bf16 v[48:51], v[92:95], v[12:15], v[48:51]
	v_cndmask_b32_e32 v64, 0, v82, vcc
	v_fmac_f32_e32 v64, v79, v101
	v_exp_f32_e32 v64, v64
	v_cndmask_b32_e32 v66, 0, v86, vcc
	v_ldexp_f32 v64, v64, v66
	v_mul_f32_e32 v66, v65, v73
	v_cmp_gt_f32_e32 vcc, s3, v66
	v_cndmask_b32_e64 v64, 0, v64, s[0:1]
	s_nop 0
	v_cndmask_b32_e32 v66, 0, v82, vcc
	v_fmac_f32_e32 v66, v65, v73
	v_exp_f32_e32 v65, v66
	v_cndmask_b32_e32 v66, 0, v86, vcc
	v_cmp_gt_i32_e32 vcc, 1, v81
	v_ldexp_f32 v65, v65, v66
	v_or_b32_e32 v66, 17, v61
	v_sub_u32_e32 v66, v78, v66
	v_cvt_f32_u32_e32 v67, v66
	v_cndmask_b32_e32 v65, 0, v65, vcc
	v_add_f32_e32 v64, v64, v65
	v_mul_f32_e32 v64, v64, v48
	v_mul_f32_e32 v65, v79, v67
	v_cmp_gt_f32_e32 vcc, s3, v65
	v_cmp_lt_i32_e64 s[0:1], -1, v66
	s_nop 0
	v_cndmask_b32_e32 v65, 0, v82, vcc
	v_fmac_f32_e32 v65, v79, v67
	v_exp_f32_e32 v65, v65
	v_cvt_f32_i32_e32 v67, v66
	v_cndmask_b32_e32 v48, 0, v86, vcc
	v_ldexp_f32 v48, v65, v48
	v_mul_f32_e32 v65, v67, v73
	v_cmp_gt_f32_e32 vcc, s3, v65
	v_cndmask_b32_e64 v48, 0, v48, s[0:1]
	s_nop 0
	v_cndmask_b32_e32 v65, 0, v82, vcc
	v_fmac_f32_e32 v65, v67, v73
	v_exp_f32_e32 v65, v65
	v_cndmask_b32_e32 v67, 0, v86, vcc
	v_cmp_gt_i32_e32 vcc, 1, v66
	v_ldexp_f32 v65, v65, v67
	v_or_b32_e32 v67, 18, v61
	v_sub_u32_e32 v67, v78, v67
	v_cvt_f32_u32_e32 v81, v67
	v_cndmask_b32_e32 v65, 0, v65, vcc
	v_cvt_f32_i32_e32 v66, v67
	v_add_f32_e32 v48, v48, v65
	v_mul_f32_e32 v65, v79, v81
	v_cmp_gt_f32_e32 vcc, s3, v65
	v_cmp_lt_i32_e64 s[0:1], -1, v67
	s_nop 0
	v_cndmask_b32_e32 v65, 0, v82, vcc
	v_fmac_f32_e32 v65, v79, v81
	v_mul_f32_e32 v81, v48, v49
	v_mul_f32_e32 v49, v66, v73
	v_cndmask_b32_e32 v48, 0, v86, vcc
	v_cmp_gt_f32_e32 vcc, s3, v49
	v_exp_f32_e32 v65, v65
	s_nop 0
	v_cndmask_b32_e32 v49, 0, v82, vcc
	v_fmac_f32_e32 v49, v66, v73
	v_exp_f32_e32 v49, v49
	v_ldexp_f32 v48, v65, v48
	v_cndmask_b32_e32 v65, 0, v86, vcc
	v_cmp_gt_i32_e32 vcc, 1, v67
	v_ldexp_f32 v49, v49, v65
	v_or_b32_e32 v65, 19, v61
	v_sub_u32_e32 v65, v78, v65
	v_cvt_f32_u32_e32 v66, v65
	v_cndmask_b32_e64 v48, 0, v48, s[0:1]
	v_cndmask_b32_e32 v49, 0, v49, vcc
	v_add_f32_e32 v48, v48, v49
	v_mul_f32_e32 v49, v79, v66
	v_cmp_gt_f32_e32 vcc, s3, v49
	v_mul_f32_e32 v67, v48, v50
	v_cmp_lt_i32_e64 s[0:1], -1, v65
	v_cndmask_b32_e32 v49, 0, v82, vcc
	v_fmac_f32_e32 v49, v79, v66
	v_exp_f32_e32 v49, v49
	v_cvt_f32_i32_e32 v66, v65
	v_cndmask_b32_e32 v48, 0, v86, vcc
	v_ldexp_f32 v48, v49, v48
	v_mul_f32_e32 v49, v66, v73
	v_cmp_gt_f32_e32 vcc, s3, v49
	v_cndmask_b32_e64 v48, 0, v48, s[0:1]
	s_nop 0
	v_cndmask_b32_e32 v49, 0, v82, vcc
	v_fmac_f32_e32 v49, v66, v73
	v_exp_f32_e32 v49, v49
	v_cndmask_b32_e32 v50, 0, v86, vcc
	v_cmp_gt_i32_e32 vcc, 1, v65
	v_ldexp_f32 v49, v49, v50
	s_nop 0
	v_cndmask_b32_e32 v49, 0, v49, vcc
	v_add_f32_e32 v48, v48, v49
	v_mul_f32_e32 v51, v48, v51
	v_cvt_pk_bf16_f32 v48, v63, v80
	v_cvt_pk_bf16_f32 v49, v100, v102
	v_cvt_pk_bf16_f32 v50, v64, v81
	v_cvt_pk_bf16_f32 v51, v67, v51
	ds_read2_b64 v[64:67], v60 offset1:4
	v_add_u32_e32 v63, 0x1000, v60
	ds_read2_b64 v[16:19], v63 offset0:32 offset1:36
	s_waitcnt lgkmcnt(1)
; #define LAS __attribute__((address_space(3)))
; DI unsigned cvt_pk_bf16(float lo, float hi) { unsigned r; asm volatile("v_cvt_pk_bf16_f32 %0, %1, %2" : "=v"(r) : "v"(lo), "v"(hi)); return r; }
; #define MFMA16(a, b, c) __builtin_amdgcn_mfma_f32_16x16x32_bf16((a), (b), (c), 0, 0, 0)
; DI void ret_out_item(const Params& p, int l, int b, int h, int c, LAS unsigned char* lds) {
;     ...
;     for (int kc = 0; kc < 4; ++kc) {
;         f32x4 s[2];
; #pragma unroll
;         for (int hf = 0; hf < 2; ++hf) {
;             s[hf] = (f32x4){0.f, 0.f, 0.f, 0.f};
; #pragma unroll
;             for (int ks = 0; ks < 4; ++ks) s[hf] = MFMA16(*(const LAS bf16x8*)(kcp + (2 * kc + hf) * 16 * RS + ks * 64), qf[ks], s[hf]);
; #pragma unroll
;             for (int j = 0; j < 4; ++j) {
;                 const int m = (2 * kc + hf) * 16 + q4 * 4 + j, d = tl - m;
;                 const float w = (d >= 0 ? exp2f(lgf * (float)d) : 0.f) + (d <= 0 ? exp2f(-lgb * (float)d) : 0.f);
;                 s[hf][j] *= w;
;             }
;         }
;         u32x4 w4; w4.x = cvt_pk_bf16(s[0][0], s[0][1]); w4.y = cvt_pk_bf16(s[0][2], s[0][3]); w4.z = cvt_pk_bf16(s[1][0], s[1][1]); w4.w = cvt_pk_bf16(s[1][2], s[1][3]);
;         const bf16x8 pb = __builtin_bit_cast(bf16x8, w4);
; #pragma unroll
;         for (int d = 0; d < 8; ++d) {
;             const u32x2 lo = *(const LAS u32x2*)(vtp + d * 16 * RS + kc * 64), hi = *(const LAS u32x2*)(vtp + d * 16 * RS + kc * 64 + 32);
;             u32x4 a4; a4.x = lo.x; a4.y = lo.y; a4.z = hi.x; a4.w = hi.y;
;             oacc[d] = MFMA16(__builtin_bit_cast(bf16x8, a4), pb, oacc[d]);
;         }
	v_mfma_f32_16x16x32_bf16 v[20:23], v[64:67], v[48:51], v[20:23]
	v_add_u32_e32 v64, 0x2000, v60
	ds_read2_b64 v[56:59], v64 offset0:64 offset1:68
	v_add_u32_e32 v65, 0x3000, v60
	s_waitcnt lgkmcnt(1)
	v_mfma_f32_16x16x32_bf16 v[24:27], v[16:19], v[48:51], v[24:27]
	ds_read2_b64 v[16:19], v65 offset0:96 offset1:100
	v_add_u32_e32 v66, 0x4000, v60
	v_add_u32_e32 v67, 0x5000, v60
	s_waitcnt lgkmcnt(1)
	v_mfma_f32_16x16x32_bf16 v[28:31], v[56:59], v[48:51], v[28:31]
	ds_read2_b64 v[56:59], v66 offset0:128 offset1:132
	v_add_u32_e32 v80, 0x6000, v60
	ds_read_b128 v[92:95], v62 offset:8832
	s_waitcnt lgkmcnt(2)
	v_mfma_f32_16x16x32_bf16 v[32:35], v[16:19], v[48:51], v[32:35]
	ds_read2_b64 v[16:19], v67 offset0:160 offset1:164
	v_add_u32_e32 v81, 0x7000, v60
	s_waitcnt lgkmcnt(2)
	v_mfma_f32_16x16x32_bf16 v[36:39], v[56:59], v[48:51], v[36:39]
	ds_read2_b64 v[56:59], v80 offset0:192 offset1:196
	s_waitcnt lgkmcnt(1)
	v_mfma_f32_16x16x32_bf16 v[40:43], v[16:19], v[48:51], v[40:43]
	ds_read_b128 v[16:19], v62 offset:8704
	s_waitcnt lgkmcnt(1)
	v_mfma_f32_16x16x32_bf16 v[44:47], v[56:59], v[48:51], v[44:47]
	ds_read_b128 v[56:59], v62 offset:8768
	s_waitcnt lgkmcnt(1)
	v_mfma_f32_16x16x32_bf16 v[16:19], v[16:19], v[0:3], 0
	s_waitcnt lgkmcnt(0)
	v_mfma_f32_16x16x32_bf16 v[16:19], v[56:59], v[4:7], v[16:19]
	v_or_b32_e32 v56, 32, v61
	v_sub_u32_e32 v100, v78, v56
	v_cvt_f32_u32_e32 v101, v100
	v_mfma_f32_16x16x32_bf16 v[16:19], v[92:95], v[8:11], v[16:19]
	v_cvt_f32_i32_e32 v93, v100
	v_cmp_lt_i32_e64 s[0:1], -1, v100
	v_mul_f32_e32 v92, v79, v101
	v_cmp_gt_f32_e32 vcc, s3, v92
	ds_read_b128 v[96:99], v62 offset:8896
	ds_read2_b64 v[56:59], v81 offset0:224 offset1:228
	v_cndmask_b32_e32 v92, 0, v82, vcc
	v_fmac_f32_e32 v92, v79, v101
	v_exp_f32_e32 v92, v92
	v_cndmask_b32_e32 v94, 0, v86, vcc
	s_waitcnt lgkmcnt(1)
	v_mfma_f32_16x16x32_bf16 v[16:19], v[96:99], v[12:15], v[16:19]
	v_ldexp_f32 v92, v92, v94
	v_mul_f32_e32 v94, v93, v73
	v_cmp_gt_f32_e32 vcc, s3, v94
	v_cndmask_b32_e64 v92, 0, v92, s[0:1]
	s_waitcnt lgkmcnt(0)
	v_mfma_f32_16x16x32_bf16 v[48:51], v[56:59], v[48:51], v[52:55]
	v_cndmask_b32_e32 v94, 0, v82, vcc
	v_fmac_f32_e32 v94, v93, v73
	v_exp_f32_e32 v93, v94
	v_cndmask_b32_e32 v94, 0, v86, vcc
	v_cmp_gt_i32_e32 vcc, 1, v100
	ds_read_b128 v[100:103], v62 offset:13184
	v_ldexp_f32 v93, v93, v94
	v_or_b32_e32 v94, 33, v61
	v_sub_u32_e32 v94, v78, v94
	v_cvt_f32_u32_e32 v95, v94
	v_cndmask_b32_e32 v93, 0, v93, vcc
	v_add_f32_e32 v92, v92, v93
	v_mul_f32_e32 v104, v92, v16
	v_mul_f32_e32 v93, v79, v95
	v_cmp_gt_f32_e32 vcc, s3, v93
	v_cmp_lt_i32_e64 s[0:1], -1, v94
	s_nop 0
	v_cndmask_b32_e32 v93, 0, v82, vcc
	v_fmac_f32_e32 v93, v79, v95
	v_cvt_f32_i32_e32 v95, v94
	v_cndmask_b32_e32 v16, 0, v86, vcc
	v_exp_f32_e32 v93, v93
	v_mul_f32_e32 v92, v95, v73
	v_cmp_gt_f32_e32 vcc, s3, v92
	v_ldexp_f32 v16, v93, v16
	v_cndmask_b32_e64 v16, 0, v16, s[0:1]
	v_cndmask_b32_e32 v92, 0, v82, vcc
	v_fmac_f32_e32 v92, v95, v73
	v_exp_f32_e32 v92, v92
	v_cndmask_b32_e32 v93, 0, v86, vcc
	v_cmp_gt_i32_e32 vcc, 1, v94
	v_ldexp_f32 v92, v92, v93
	v_or_b32_e32 v93, 34, v61
	v_sub_u32_e32 v93, v78, v93
	v_cvt_f32_u32_e32 v95, v93
	v_cvt_f32_i32_e32 v94, v93
	v_cndmask_b32_e32 v92, 0, v92, vcc
	v_add_f32_e32 v16, v16, v92
	v_mul_f32_e32 v92, v79, v95
	v_cmp_gt_f32_e32 vcc, s3, v92
	v_mul_f32_e32 v105, v16, v17
	v_mul_f32_e32 v17, v94, v73
	v_cndmask_b32_e32 v92, 0, v82, vcc
	v_cndmask_b32_e32 v16, 0, v86, vcc
	v_cmp_gt_f32_e32 vcc, s3, v17
	v_fmac_f32_e32 v92, v79, v95
	v_exp_f32_e32 v92, v92
	v_cndmask_b32_e32 v17, 0, v82, vcc
	v_fmac_f32_e32 v17, v94, v73
	v_exp_f32_e32 v17, v17
	v_ldexp_f32 v16, v92, v16
	v_cndmask_b32_e32 v92, 0, v86, vcc
	v_cmp_lt_i32_e64 s[0:1], -1, v93
	v_ldexp_f32 v17, v17, v92
	v_or_b32_e32 v92, 35, v61
	v_sub_u32_e32 v106, v78, v92
	v_cvt_f32_u32_e32 v92, v106
	v_cmp_gt_i32_e32 vcc, 1, v93
	v_cndmask_b32_e64 v16, 0, v16, s[0:1]
	v_cvt_f32_i32_e32 v96, v106
	v_cndmask_b32_e32 v17, 0, v17, vcc
	v_add_f32_e32 v16, v16, v17
	v_mul_f32_e32 v17, v79, v92
	v_cmp_gt_f32_e32 vcc, s3, v17
	v_mul_f32_e32 v107, v16, v18
	v_cmp_lt_i32_e64 s[0:1], -1, v106
	v_cndmask_b32_e32 v17, 0, v82, vcc
	v_fmac_f32_e32 v17, v79, v92
	v_exp_f32_e32 v17, v17
	v_cndmask_b32_e32 v16, 0, v86, vcc
	ds_read_b128 v[92:95], v62 offset:13056
	v_ldexp_f32 v16, v17, v16
	v_mul_f32_e32 v17, v96, v73
	v_cmp_gt_f32_e32 vcc, s3, v17
	v_cndmask_b32_e64 v16, 0, v16, s[0:1]
	s_nop 0
	v_cndmask_b32_e32 v17, 0, v82, vcc
	v_fmac_f32_e32 v17, v96, v73
	ds_read_b128 v[96:99], v62 offset:13120
	v_exp_f32_e32 v17, v17
	v_cndmask_b32_e32 v18, 0, v86, vcc
	s_waitcnt lgkmcnt(1)
	v_mfma_f32_16x16x32_bf16 v[92:95], v[92:95], v[0:3], 0
	v_cmp_gt_i32_e32 vcc, 1, v106
	v_ldexp_f32 v17, v17, v18
	s_nop 0
	v_cndmask_b32_e32 v17, 0, v17, vcc
	v_add_f32_e32 v16, v16, v17
	v_or_b32_e32 v17, 48, v61
	v_sub_u32_e32 v106, v78, v17
	s_waitcnt lgkmcnt(0)
	v_mfma_f32_16x16x32_bf16 v[92:95], v[96:99], v[4:7], v[92:95]
	v_cvt_f32_u32_e32 v108, v106
	ds_read_b128 v[96:99], v62 offset:13248
	v_mul_f32_e32 v109, v16, v19
	v_mfma_f32_16x16x32_bf16 v[16:19], v[100:103], v[8:11], v[92:95]
	v_cmp_lt_i32_e64 s[0:1], -1, v106
	s_nop 2
	v_mul_f32_e32 v92, v79, v108
	v_cmp_gt_f32_e32 vcc, s3, v92
	v_cvt_f32_i32_e32 v93, v106
	s_waitcnt lgkmcnt(0)
; #define LAS __attribute__((address_space(3)))
; DI unsigned cvt_pk_bf16(float lo, float hi) { unsigned r; asm volatile("v_cvt_pk_bf16_f32 %0, %1, %2" : "=v"(r) : "v"(lo), "v"(hi)); return r; }
; #define MFMA16(a, b, c) __builtin_amdgcn_mfma_f32_16x16x32_bf16((a), (b), (c), 0, 0, 0)
; DI void ret_out_item(const Params& p, int l, int b, int h, int c, LAS unsigned char* lds) {
;     ...
;     for (int kc = 0; kc < 4; ++kc) {
;         f32x4 s[2];
; #pragma unroll
;         for (int hf = 0; hf < 2; ++hf) {
;             s[hf] = (f32x4){0.f, 0.f, 0.f, 0.f};
; #pragma unroll
;             for (int ks = 0; ks < 4; ++ks) s[hf] = MFMA16(*(const LAS bf16x8*)(kcp + (2 * kc + hf) * 16 * RS + ks * 64), qf[ks], s[hf]);
; #pragma unroll
;             for (int j = 0; j < 4; ++j) {
;                 const int m = (2 * kc + hf) * 16 + q4 * 4 + j, d = tl - m;
;                 const float w = (d >= 0 ? exp2f(lgf * (float)d) : 0.f) + (d <= 0 ? exp2f(-lgb * (float)d) : 0.f);
;                 s[hf][j] *= w;
;             }
;         }
;         u32x4 w4; w4.x = cvt_pk_bf16(s[0][0], s[0][1]); w4.y = cvt_pk_bf16(s[0][2], s[0][3]); w4.z = cvt_pk_bf16(s[1][0], s[1][1]); w4.w = cvt_pk_bf16(s[1][2], s[1][3]);
;         const bf16x8 pb = __builtin_bit_cast(bf16x8, w4);
; #pragma unroll
;         for (int d = 0; d < 8; ++d) {
;             const u32x2 lo = *(const LAS u32x2*)(vtp + d * 16 * RS + kc * 64), hi = *(const LAS u32x2*)(vtp + d * 16 * RS + kc * 64 + 32);
;             u32x4 a4; a4.x = lo.x; a4.y = lo.y; a4.z = hi.x; a4.w = hi.y;
;             oacc[d] = MFMA16(__builtin_bit_cast(bf16x8, a4), pb, oacc[d]);
;         }
	v_mfma_f32_16x16x32_bf16 v[16:19], v[96:99], v[12:15], v[16:19]
	v_cndmask_b32_e32 v92, 0, v82, vcc
	v_fmac_f32_e32 v92, v79, v108
	v_exp_f32_e32 v92, v92
	v_cndmask_b32_e32 v94, 0, v86, vcc
	v_ldexp_f32 v92, v92, v94
	v_mul_f32_e32 v94, v93, v73
	v_cmp_gt_f32_e32 vcc, s3, v94
	v_cndmask_b32_e64 v92, 0, v92, s[0:1]
	s_nop 0
	v_cndmask_b32_e32 v94, 0, v82, vcc
	v_fmac_f32_e32 v94, v93, v73
	v_exp_f32_e32 v93, v94
	v_cndmask_b32_e32 v94, 0, v86, vcc
	v_cmp_gt_i32_e32 vcc, 1, v106
	v_ldexp_f32 v93, v93, v94
	v_or_b32_e32 v94, 49, v61
	v_sub_u32_e32 v94, v78, v94
	v_cvt_f32_u32_e32 v95, v94
	v_cndmask_b32_e32 v93, 0, v93, vcc
	v_add_f32_e32 v92, v92, v93
	v_mul_f32_e32 v92, v92, v16
	v_mul_f32_e32 v93, v79, v95
	v_cmp_gt_f32_e32 vcc, s3, v93
	v_cmp_lt_i32_e64 s[0:1], -1, v94
	s_nop 0
	v_cndmask_b32_e32 v93, 0, v82, vcc
	v_fmac_f32_e32 v93, v79, v95
	v_exp_f32_e32 v93, v93
	v_cvt_f32_i32_e32 v95, v94
	v_cndmask_b32_e32 v16, 0, v86, vcc
	v_ldexp_f32 v16, v93, v16
	v_mul_f32_e32 v93, v95, v73
	v_cmp_gt_f32_e32 vcc, s3, v93
	v_cndmask_b32_e64 v16, 0, v16, s[0:1]
	s_nop 0
	v_cndmask_b32_e32 v93, 0, v82, vcc
	v_fmac_f32_e32 v93, v95, v73
	v_exp_f32_e32 v93, v93
	v_cndmask_b32_e32 v95, 0, v86, vcc
	v_cmp_gt_i32_e32 vcc, 1, v94
	v_ldexp_f32 v93, v93, v95
	v_or_b32_e32 v95, 50, v61
	v_sub_u32_e32 v95, v78, v95
	v_cvt_f32_u32_e32 v96, v95
	v_cndmask_b32_e32 v93, 0, v93, vcc
	v_cvt_f32_i32_e32 v94, v95
	v_add_f32_e32 v16, v16, v93
	v_mul_f32_e32 v93, v79, v96
	v_cmp_gt_f32_e32 vcc, s3, v93
	v_cmp_lt_i32_e64 s[0:1], -1, v95
	s_nop 0
	v_cndmask_b32_e32 v93, 0, v82, vcc
	v_fmac_f32_e32 v93, v79, v96
	v_mul_f32_e32 v96, v16, v17
	v_mul_f32_e32 v17, v94, v73
	v_cndmask_b32_e32 v16, 0, v86, vcc
	v_cmp_gt_f32_e32 vcc, s3, v17
	v_exp_f32_e32 v93, v93
	s_nop 0
	v_cndmask_b32_e32 v17, 0, v82, vcc
	v_fmac_f32_e32 v17, v94, v73
	v_exp_f32_e32 v17, v17
	v_ldexp_f32 v16, v93, v16
	v_cndmask_b32_e32 v93, 0, v86, vcc
	v_cmp_gt_i32_e32 vcc, 1, v95
	v_ldexp_f32 v17, v17, v93
	v_or_b32_e32 v93, 51, v61
	v_sub_u32_e32 v93, v78, v93
	v_cvt_f32_u32_e32 v94, v93
	v_cndmask_b32_e64 v16, 0, v16, s[0:1]
	v_cndmask_b32_e32 v17, 0, v17, vcc
	v_add_f32_e32 v16, v16, v17
	v_mul_f32_e32 v17, v79, v94
	v_cmp_gt_f32_e32 vcc, s3, v17
	v_mul_f32_e32 v95, v16, v18
	v_cmp_lt_i32_e64 s[0:1], -1, v93
	v_cndmask_b32_e32 v17, 0, v82, vcc
	v_fmac_f32_e32 v17, v79, v94
	v_exp_f32_e32 v17, v17
	v_cvt_f32_i32_e32 v94, v93
	v_cndmask_b32_e32 v16, 0, v86, vcc
	v_ldexp_f32 v16, v17, v16
	v_mul_f32_e32 v17, v94, v73
	v_cmp_gt_f32_e32 vcc, s3, v17
	v_cndmask_b32_e64 v16, 0, v16, s[0:1]
	s_nop 0
	v_cndmask_b32_e32 v17, 0, v82, vcc
	v_fmac_f32_e32 v17, v94, v73
	v_exp_f32_e32 v17, v17
	v_cndmask_b32_e32 v18, 0, v86, vcc
	v_cmp_gt_i32_e32 vcc, 1, v93
	v_ldexp_f32 v17, v17, v18
	s_nop 0
	v_cndmask_b32_e32 v17, 0, v17, vcc
	v_add_f32_e32 v16, v16, v17
	v_mul_f32_e32 v19, v16, v19
	v_cvt_pk_bf16_f32 v16, v104, v105
	v_cvt_pk_bf16_f32 v17, v107, v109
	v_cvt_pk_bf16_f32 v18, v92, v96
	v_cvt_pk_bf16_f32 v19, v95, v19
	ds_read2_b64 v[52:55], v63 offset0:40 offset1:44
	ds_read2_b64 v[56:59], v64 offset0:72 offset1:76
	s_waitcnt lgkmcnt(1)
	v_mfma_f32_16x16x32_bf16 v[24:27], v[52:55], v[16:19], v[24:27]
	ds_read2_b64 v[52:55], v65 offset0:104 offset1:108
	ds_read2_b64 v[92:95], v60 offset0:8 offset1:12
	s_waitcnt lgkmcnt(2)
	v_mfma_f32_16x16x32_bf16 v[28:31], v[56:59], v[16:19], v[28:31]
	ds_read2_b64 v[56:59], v66 offset0:136 offset1:140
	s_waitcnt lgkmcnt(2)
	v_mfma_f32_16x16x32_bf16 v[32:35], v[52:55], v[16:19], v[32:35]
	ds_read2_b64 v[52:55], v67 offset0:168 offset1:172
	s_waitcnt lgkmcnt(1)
	v_mfma_f32_16x16x32_bf16 v[36:39], v[56:59], v[16:19], v[36:39]
	ds_read2_b64 v[56:59], v80 offset0:200 offset1:204
	s_waitcnt lgkmcnt(1)
	v_mfma_f32_16x16x32_bf16 v[40:43], v[52:55], v[16:19], v[40:43]
	ds_read_b128 v[52:55], v62 offset:17408
	s_waitcnt lgkmcnt(1)
	v_mfma_f32_16x16x32_bf16 v[44:47], v[56:59], v[16:19], v[44:47]
	ds_read_b128 v[56:59], v62 offset:17472
	s_waitcnt lgkmcnt(1)
	v_mfma_f32_16x16x32_bf16 v[52:55], v[52:55], v[0:3], 0
	v_mfma_f32_16x16x32_bf16 v[20:23], v[92:95], v[16:19], v[20:23]
	ds_read_b128 v[92:95], v62 offset:17536
	s_waitcnt lgkmcnt(1)
	v_mfma_f32_16x16x32_bf16 v[56:59], v[56:59], v[4:7], v[52:55]
	s_nop 3
	v_or_b32_e32 v52, 64, v61
	v_sub_u32_e32 v100, v78, v52
	v_cvt_f32_u32_e32 v101, v100
	s_waitcnt lgkmcnt(0)
	v_mfma_f32_16x16x32_bf16 v[56:59], v[92:95], v[8:11], v[56:59]
	v_cvt_f32_i32_e32 v93, v100
	v_cmp_lt_i32_e64 s[0:1], -1, v100
	v_mul_f32_e32 v92, v79, v101
	v_cmp_gt_f32_e32 vcc, s3, v92
	ds_read_b128 v[96:99], v62 offset:17600
	ds_read2_b64 v[52:55], v81 offset0:232 offset1:236
	v_cndmask_b32_e32 v92, 0, v82, vcc
	v_fmac_f32_e32 v92, v79, v101
	v_exp_f32_e32 v92, v92
	v_cndmask_b32_e32 v94, 0, v86, vcc
	s_waitcnt lgkmcnt(1)
	v_mfma_f32_16x16x32_bf16 v[56:59], v[96:99], v[12:15], v[56:59]
	v_ldexp_f32 v92, v92, v94
	v_mul_f32_e32 v94, v93, v73
	v_cmp_gt_f32_e32 vcc, s3, v94
	v_cndmask_b32_e64 v92, 0, v92, s[0:1]
	s_waitcnt lgkmcnt(0)
; #define LAS __attribute__((address_space(3)))
; DI unsigned cvt_pk_bf16(float lo, float hi) { unsigned r; asm volatile("v_cvt_pk_bf16_f32 %0, %1, %2" : "=v"(r) : "v"(lo), "v"(hi)); return r; }
; #define MFMA16(a, b, c) __builtin_amdgcn_mfma_f32_16x16x32_bf16((a), (b), (c), 0, 0, 0)
; DI void ret_out_item(const Params& p, int l, int b, int h, int c, LAS unsigned char* lds) {
;     ...
;     for (int kc = 0; kc < 4; ++kc) {
;         f32x4 s[2];
; #pragma unroll
;         for (int hf = 0; hf < 2; ++hf) {
;             s[hf] = (f32x4){0.f, 0.f, 0.f, 0.f};
; #pragma unroll
;             for (int ks = 0; ks < 4; ++ks) s[hf] = MFMA16(*(const LAS bf16x8*)(kcp + (2 * kc + hf) * 16 * RS + ks * 64), qf[ks], s[hf]);
; #pragma unroll
;             for (int j = 0; j < 4; ++j) {
;                 const int m = (2 * kc + hf) * 16 + q4 * 4 + j, d = tl - m;
;                 const float w = (d >= 0 ? exp2f(lgf * (float)d) : 0.f) + (d <= 0 ? exp2f(-lgb * (float)d) : 0.f);
;                 s[hf][j] *= w;
;             }
;         }
;         u32x4 w4; w4.x = cvt_pk_bf16(s[0][0], s[0][1]); w4.y = cvt_pk_bf16(s[0][2], s[0][3]); w4.z = cvt_pk_bf16(s[1][0], s[1][1]); w4.w = cvt_pk_bf16(s[1][2], s[1][3]);
;         const bf16x8 pb = __builtin_bit_cast(bf16x8, w4);
; #pragma unroll
;         for (int d = 0; d < 8; ++d) {
;             const u32x2 lo = *(const LAS u32x2*)(vtp + d * 16 * RS + kc * 64), hi = *(const LAS u32x2*)(vtp + d * 16 * RS + kc * 64 + 32);
;             u32x4 a4; a4.x = lo.x; a4.y = lo.y; a4.z = hi.x; a4.w = hi.y;
;             oacc[d] = MFMA16(__builtin_bit_cast(bf16x8, a4), pb, oacc[d]);
;         }
	v_mfma_f32_16x16x32_bf16 v[48:51], v[52:55], v[16:19], v[48:51]
	v_cndmask_b32_e32 v94, 0, v82, vcc
	v_fmac_f32_e32 v94, v93, v73
	v_exp_f32_e32 v93, v94
	v_cndmask_b32_e32 v94, 0, v86, vcc
	v_cmp_gt_i32_e32 vcc, 1, v100
	ds_read_b128 v[100:103], v62 offset:21888
	v_ldexp_f32 v93, v93, v94
	v_or_b32_e32 v94, 0x41, v61
	v_sub_u32_e32 v94, v78, v94
	v_cvt_f32_u32_e32 v95, v94
	v_cndmask_b32_e32 v93, 0, v93, vcc
	v_add_f32_e32 v92, v92, v93
	v_mul_f32_e32 v104, v92, v56
	v_mul_f32_e32 v93, v79, v95
	v_cmp_gt_f32_e32 vcc, s3, v93
	v_cmp_lt_i32_e64 s[0:1], -1, v94
	s_nop 0
	v_cndmask_b32_e32 v93, 0, v82, vcc
	v_fmac_f32_e32 v93, v79, v95
	v_cvt_f32_i32_e32 v95, v94
	v_cndmask_b32_e32 v56, 0, v86, vcc
	v_exp_f32_e32 v93, v93
	v_mul_f32_e32 v92, v95, v73
	v_cmp_gt_f32_e32 vcc, s3, v92
	v_ldexp_f32 v56, v93, v56
	v_cndmask_b32_e64 v56, 0, v56, s[0:1]
	v_cndmask_b32_e32 v92, 0, v82, vcc
	v_fmac_f32_e32 v92, v95, v73
	v_exp_f32_e32 v92, v92
	v_cndmask_b32_e32 v93, 0, v86, vcc
	v_cmp_gt_i32_e32 vcc, 1, v94
	v_ldexp_f32 v92, v92, v93
	v_or_b32_e32 v93, 0x42, v61
	v_sub_u32_e32 v93, v78, v93
	v_cvt_f32_u32_e32 v95, v93
	v_cvt_f32_i32_e32 v94, v93
	v_cndmask_b32_e32 v92, 0, v92, vcc
	v_add_f32_e32 v56, v56, v92
	v_mul_f32_e32 v92, v79, v95
	v_cmp_gt_f32_e32 vcc, s3, v92
	v_mul_f32_e32 v105, v56, v57
	v_mul_f32_e32 v57, v94, v73
	v_cndmask_b32_e32 v92, 0, v82, vcc
	v_cndmask_b32_e32 v56, 0, v86, vcc
	v_cmp_gt_f32_e32 vcc, s3, v57
	v_fmac_f32_e32 v92, v79, v95
	v_exp_f32_e32 v92, v92
	v_cndmask_b32_e32 v57, 0, v82, vcc
	v_fmac_f32_e32 v57, v94, v73
	v_exp_f32_e32 v57, v57
	v_ldexp_f32 v56, v92, v56
	v_cndmask_b32_e32 v92, 0, v86, vcc
	v_cmp_lt_i32_e64 s[0:1], -1, v93
	v_ldexp_f32 v57, v57, v92
	v_or_b32_e32 v92, 0x43, v61
	v_sub_u32_e32 v106, v78, v92
	v_cvt_f32_u32_e32 v92, v106
	v_cmp_gt_i32_e32 vcc, 1, v93
	v_cndmask_b32_e64 v56, 0, v56, s[0:1]
	v_cvt_f32_i32_e32 v96, v106
	v_cndmask_b32_e32 v57, 0, v57, vcc
	v_add_f32_e32 v56, v56, v57
	v_mul_f32_e32 v57, v79, v92
	v_cmp_gt_f32_e32 vcc, s3, v57
	v_mul_f32_e32 v107, v56, v58
	v_cmp_lt_i32_e64 s[0:1], -1, v106
	v_cndmask_b32_e32 v57, 0, v82, vcc
	v_fmac_f32_e32 v57, v79, v92
	v_exp_f32_e32 v57, v57
	v_cndmask_b32_e32 v56, 0, v86, vcc
	ds_read_b128 v[92:95], v62 offset:21760
	v_ldexp_f32 v56, v57, v56
	v_mul_f32_e32 v57, v96, v73
	v_cmp_gt_f32_e32 vcc, s3, v57
	v_cndmask_b32_e64 v56, 0, v56, s[0:1]
	s_nop 0
	v_cndmask_b32_e32 v57, 0, v82, vcc
	v_fmac_f32_e32 v57, v96, v73
	ds_read_b128 v[96:99], v62 offset:21824
	v_exp_f32_e32 v57, v57
	v_cndmask_b32_e32 v58, 0, v86, vcc
	s_waitcnt lgkmcnt(1)
	v_mfma_f32_16x16x32_bf16 v[92:95], v[92:95], v[0:3], 0
	v_cmp_gt_i32_e32 vcc, 1, v106
	v_ldexp_f32 v57, v57, v58
	s_nop 0
	v_cndmask_b32_e32 v57, 0, v57, vcc
	v_add_f32_e32 v56, v56, v57
	v_or_b32_e32 v57, 0x50, v61
	v_sub_u32_e32 v106, v78, v57
	s_waitcnt lgkmcnt(0)
	v_mfma_f32_16x16x32_bf16 v[92:95], v[96:99], v[4:7], v[92:95]
	v_cvt_f32_u32_e32 v108, v106
	ds_read_b128 v[96:99], v62 offset:21952
	v_mul_f32_e32 v109, v56, v59
	v_mfma_f32_16x16x32_bf16 v[56:59], v[100:103], v[8:11], v[92:95]
	v_cmp_lt_i32_e64 s[0:1], -1, v106
	s_nop 2
	v_mul_f32_e32 v92, v79, v108
	v_cmp_gt_f32_e32 vcc, s3, v92
	v_cvt_f32_i32_e32 v93, v106
	s_waitcnt lgkmcnt(0)
	v_mfma_f32_16x16x32_bf16 v[56:59], v[96:99], v[12:15], v[56:59]
	v_cndmask_b32_e32 v92, 0, v82, vcc
	v_fmac_f32_e32 v92, v79, v108
	v_exp_f32_e32 v92, v92
	v_cndmask_b32_e32 v94, 0, v86, vcc
	v_ldexp_f32 v92, v92, v94
	v_mul_f32_e32 v94, v93, v73
	v_cmp_gt_f32_e32 vcc, s3, v94
	v_cndmask_b32_e64 v92, 0, v92, s[0:1]
	s_nop 0
	v_cndmask_b32_e32 v94, 0, v82, vcc
	v_fmac_f32_e32 v94, v93, v73
	v_exp_f32_e32 v93, v94
	v_cndmask_b32_e32 v94, 0, v86, vcc
	v_cmp_gt_i32_e32 vcc, 1, v106
	v_ldexp_f32 v93, v93, v94
	v_or_b32_e32 v94, 0x51, v61
	v_sub_u32_e32 v94, v78, v94
	v_cvt_f32_u32_e32 v95, v94
	v_cndmask_b32_e32 v93, 0, v93, vcc
	v_add_f32_e32 v92, v92, v93
	v_mul_f32_e32 v92, v92, v56
	v_mul_f32_e32 v93, v79, v95
	v_cmp_gt_f32_e32 vcc, s3, v93
	v_cmp_lt_i32_e64 s[0:1], -1, v94
	s_nop 0
	v_cndmask_b32_e32 v93, 0, v82, vcc
	v_fmac_f32_e32 v93, v79, v95
	v_exp_f32_e32 v93, v93
	v_cvt_f32_i32_e32 v95, v94
	v_cndmask_b32_e32 v56, 0, v86, vcc
	v_ldexp_f32 v56, v93, v56
	v_mul_f32_e32 v93, v95, v73
	v_cmp_gt_f32_e32 vcc, s3, v93
	v_cndmask_b32_e64 v56, 0, v56, s[0:1]
	s_nop 0
	v_cndmask_b32_e32 v93, 0, v82, vcc
	v_fmac_f32_e32 v93, v95, v73
	v_exp_f32_e32 v93, v93
	v_cndmask_b32_e32 v95, 0, v86, vcc
	v_cmp_gt_i32_e32 vcc, 1, v94
	v_ldexp_f32 v93, v93, v95
	v_or_b32_e32 v95, 0x52, v61
	v_sub_u32_e32 v95, v78, v95
	v_cvt_f32_u32_e32 v96, v95
	v_cndmask_b32_e32 v93, 0, v93, vcc
	v_cvt_f32_i32_e32 v94, v95
	v_add_f32_e32 v56, v56, v93
	v_mul_f32_e32 v93, v79, v96
	v_cmp_gt_f32_e32 vcc, s3, v93
	v_cmp_lt_i32_e64 s[0:1], -1, v95
	s_nop 0
	v_cndmask_b32_e32 v93, 0, v82, vcc
	v_fmac_f32_e32 v93, v79, v96
	v_mul_f32_e32 v96, v56, v57
	v_mul_f32_e32 v57, v94, v73
	v_cndmask_b32_e32 v56, 0, v86, vcc
	v_cmp_gt_f32_e32 vcc, s3, v57
	v_exp_f32_e32 v93, v93
	s_nop 0
	v_cndmask_b32_e32 v57, 0, v82, vcc
	v_fmac_f32_e32 v57, v94, v73
	v_exp_f32_e32 v57, v57
	v_ldexp_f32 v56, v93, v56
	v_cndmask_b32_e32 v93, 0, v86, vcc
	v_cmp_gt_i32_e32 vcc, 1, v95
	v_ldexp_f32 v57, v57, v93
	v_or_b32_e32 v93, 0x53, v61
	v_sub_u32_e32 v93, v78, v93
	v_cvt_f32_u32_e32 v94, v93
	v_cndmask_b32_e64 v56, 0, v56, s[0:1]
	v_cndmask_b32_e32 v57, 0, v57, vcc
	v_add_f32_e32 v56, v56, v57
	v_mul_f32_e32 v57, v79, v94
	v_cmp_gt_f32_e32 vcc, s3, v57
	v_mul_f32_e32 v95, v56, v58
	v_cmp_lt_i32_e64 s[0:1], -1, v93
	v_cndmask_b32_e32 v57, 0, v82, vcc
	v_fmac_f32_e32 v57, v79, v94
	v_exp_f32_e32 v57, v57
	v_cvt_f32_i32_e32 v94, v93
	v_cndmask_b32_e32 v56, 0, v86, vcc
	v_ldexp_f32 v56, v57, v56
	v_mul_f32_e32 v57, v94, v73
	v_cmp_gt_f32_e32 vcc, s3, v57
	v_cndmask_b32_e64 v56, 0, v56, s[0:1]
	s_nop 0
	v_cndmask_b32_e32 v57, 0, v82, vcc
	v_fmac_f32_e32 v57, v94, v73
	v_exp_f32_e32 v57, v57
	v_cndmask_b32_e32 v58, 0, v86, vcc
	v_cmp_gt_i32_e32 vcc, 1, v93
	v_ldexp_f32 v57, v57, v58
	s_nop 0
	v_cndmask_b32_e32 v57, 0, v57, vcc
	v_add_f32_e32 v56, v56, v57
	v_mul_f32_e32 v59, v56, v59
	v_cvt_pk_bf16_f32 v56, v104, v105
	v_cvt_pk_bf16_f32 v57, v107, v109
	v_cvt_pk_bf16_f32 v58, v92, v96
	v_cvt_pk_bf16_f32 v59, v95, v59
	ds_read2_b64 v[92:95], v60 offset0:16 offset1:20
	ds_read2_b64 v[52:55], v63 offset0:48 offset1:52
	s_waitcnt lgkmcnt(1)
; #define LAS __attribute__((address_space(3)))
; DI unsigned cvt_pk_bf16(float lo, float hi) { unsigned r; asm volatile("v_cvt_pk_bf16_f32 %0, %1, %2" : "=v"(r) : "v"(lo), "v"(hi)); return r; }
; #define MFMA16(a, b, c) __builtin_amdgcn_mfma_f32_16x16x32_bf16((a), (b), (c), 0, 0, 0)
; DI void ret_out_item(const Params& p, int l, int b, int h, int c, LAS unsigned char* lds) {
;     ...
;     for (int kc = 0; kc < 4; ++kc) {
;         f32x4 s[2];
; #pragma unroll
;         for (int hf = 0; hf < 2; ++hf) {
;             s[hf] = (f32x4){0.f, 0.f, 0.f, 0.f};
; #pragma unroll
;             for (int ks = 0; ks < 4; ++ks) s[hf] = MFMA16(*(const LAS bf16x8*)(kcp + (2 * kc + hf) * 16 * RS + ks * 64), qf[ks], s[hf]);
; #pragma unroll
;             for (int j = 0; j < 4; ++j) {
;                 const int m = (2 * kc + hf) * 16 + q4 * 4 + j, d = tl - m;
;                 const float w = (d >= 0 ? exp2f(lgf * (float)d) : 0.f) + (d <= 0 ? exp2f(-lgb * (float)d) : 0.f);
;                 s[hf][j] *= w;
;             }
;         }
;         u32x4 w4; w4.x = cvt_pk_bf16(s[0][0], s[0][1]); w4.y = cvt_pk_bf16(s[0][2], s[0][3]); w4.z = cvt_pk_bf16(s[1][0], s[1][1]); w4.w = cvt_pk_bf16(s[1][2], s[1][3]);
;         const bf16x8 pb = __builtin_bit_cast(bf16x8, w4);
; #pragma unroll
;         for (int d = 0; d < 8; ++d) {
;             const u32x2 lo = *(const LAS u32x2*)(vtp + d * 16 * RS + kc * 64), hi = *(const LAS u32x2*)(vtp + d * 16 * RS + kc * 64 + 32);
;             u32x4 a4; a4.x = lo.x; a4.y = lo.y; a4.z = hi.x; a4.w = hi.y;
;             oacc[d] = MFMA16(__builtin_bit_cast(bf16x8, a4), pb, oacc[d]);
;         }
	v_mfma_f32_16x16x32_bf16 v[16:19], v[92:95], v[56:59], v[20:23]
	ds_read2_b64 v[92:95], v64 offset0:80 offset1:84
	s_waitcnt lgkmcnt(1)
	v_mfma_f32_16x16x32_bf16 v[20:23], v[52:55], v[56:59], v[24:27]
	ds_read2_b64 v[52:55], v66 offset0:144 offset1:148
	s_nop 1
	ds_read2_b64 v[24:27], v65 offset0:112 offset1:116
	s_waitcnt lgkmcnt(0)
	v_mfma_f32_16x16x32_bf16 v[32:35], v[24:27], v[56:59], v[32:35]
	ds_read2_b64 v[24:27], v67 offset0:176 offset1:180
	v_mfma_f32_16x16x32_bf16 v[36:39], v[52:55], v[56:59], v[36:39]
	ds_read2_b64 v[52:55], v80 offset0:208 offset1:212
	s_waitcnt lgkmcnt(1)
	v_mfma_f32_16x16x32_bf16 v[40:43], v[24:27], v[56:59], v[40:43]
	ds_read2_b64 v[24:27], v81 offset0:240 offset1:244
	s_waitcnt lgkmcnt(1)
	v_mfma_f32_16x16x32_bf16 v[44:47], v[52:55], v[56:59], v[44:47]
	ds_read_b128 v[52:55], v62 offset:26112
	s_waitcnt lgkmcnt(1)
	v_mfma_f32_16x16x32_bf16 v[48:51], v[24:27], v[56:59], v[48:51]
	ds_read_b128 v[24:27], v62 offset:26176
	s_waitcnt lgkmcnt(1)
	v_mfma_f32_16x16x32_bf16 v[52:55], v[52:55], v[0:3], 0
	v_mfma_f32_16x16x32_bf16 v[28:31], v[92:95], v[56:59], v[28:31]
	ds_read_b128 v[56:59], v62 offset:26240
	s_waitcnt lgkmcnt(1)
	v_mfma_f32_16x16x32_bf16 v[24:27], v[24:27], v[4:7], v[52:55]
	s_nop 3
	v_or_b32_e32 v52, 0x60, v61
	v_sub_u32_e32 v92, v78, v52
	ds_read_b128 v[52:55], v62 offset:26304
	v_cvt_f32_u32_e32 v93, v92
	s_waitcnt lgkmcnt(1)
	v_mfma_f32_16x16x32_bf16 v[24:27], v[56:59], v[8:11], v[24:27]
	v_cvt_f32_i32_e32 v57, v92
	v_cmp_lt_i32_e64 s[0:1], -1, v92
	v_mul_f32_e32 v56, v79, v93
	v_cmp_gt_f32_e32 vcc, s3, v56
	s_waitcnt lgkmcnt(0)
	v_mfma_f32_16x16x32_bf16 v[24:27], v[52:55], v[12:15], v[24:27]
	v_mul_f32_e32 v53, v57, v73
	v_cndmask_b32_e32 v56, 0, v82, vcc
	v_cndmask_b32_e32 v52, 0, v86, vcc
	v_cmp_gt_f32_e32 vcc, s3, v53
	v_fmac_f32_e32 v56, v79, v93
	v_exp_f32_e32 v56, v56
	v_cndmask_b32_e32 v53, 0, v82, vcc
	v_fmac_f32_e32 v53, v57, v73
	v_exp_f32_e32 v53, v53
	v_cndmask_b32_e32 v54, 0, v86, vcc
	v_ldexp_f32 v52, v56, v52
	v_cmp_gt_i32_e32 vcc, 1, v92
	v_ldexp_f32 v53, v53, v54
	v_or_b32_e32 v54, 0x61, v61
	v_sub_u32_e32 v54, v78, v54
	v_cvt_f32_u32_e32 v55, v54
	v_cndmask_b32_e64 v52, 0, v52, s[0:1]
	v_cndmask_b32_e32 v53, 0, v53, vcc
	v_add_f32_e32 v52, v52, v53
	v_mul_f32_e32 v53, v79, v55
	v_cmp_gt_f32_e32 vcc, s3, v53
	v_mul_f32_e32 v24, v52, v24
	v_cmp_lt_i32_e64 s[0:1], -1, v54
	v_cndmask_b32_e32 v53, 0, v82, vcc
	v_fmac_f32_e32 v53, v79, v55
	v_exp_f32_e32 v53, v53
	v_cvt_f32_i32_e32 v55, v54
	v_cndmask_b32_e32 v52, 0, v86, vcc
	v_ldexp_f32 v52, v53, v52
	v_mul_f32_e32 v53, v55, v73
	v_cmp_gt_f32_e32 vcc, s3, v53
	v_cndmask_b32_e64 v52, 0, v52, s[0:1]
	s_nop 0
	v_cndmask_b32_e32 v53, 0, v82, vcc
	v_fmac_f32_e32 v53, v55, v73
	v_exp_f32_e32 v53, v53
	v_cndmask_b32_e32 v55, 0, v86, vcc
	v_cmp_gt_i32_e32 vcc, 1, v54
	v_ldexp_f32 v53, v53, v55
	v_or_b32_e32 v55, 0x62, v61
	v_sub_u32_e32 v55, v78, v55
	v_cvt_f32_u32_e32 v56, v55
	v_cndmask_b32_e32 v53, 0, v53, vcc
	v_add_f32_e32 v52, v52, v53
	v_cvt_f32_i32_e32 v54, v55
	v_mul_f32_e32 v53, v79, v56
	v_cmp_gt_f32_e32 vcc, s3, v53
	v_mul_f32_e32 v25, v52, v25
	v_cmp_lt_i32_e64 s[0:1], -1, v55
	v_cndmask_b32_e32 v53, 0, v82, vcc
	v_fmac_f32_e32 v53, v79, v56
	v_exp_f32_e32 v53, v53
	v_cndmask_b32_e32 v52, 0, v86, vcc
	v_ldexp_f32 v52, v53, v52
	v_mul_f32_e32 v53, v54, v73
	v_cmp_gt_f32_e32 vcc, s3, v53
	v_cndmask_b32_e64 v52, 0, v52, s[0:1]
	s_nop 0
	v_cndmask_b32_e32 v53, 0, v82, vcc
	v_fmac_f32_e32 v53, v54, v73
	v_exp_f32_e32 v53, v53
	v_cndmask_b32_e32 v54, 0, v86, vcc
	v_cmp_gt_i32_e32 vcc, 1, v55
	v_ldexp_f32 v53, v53, v54
	v_or_b32_e32 v54, 0x63, v61
	v_sub_u32_e32 v92, v78, v54
	v_cvt_f32_u32_e32 v54, v92
	v_cndmask_b32_e32 v53, 0, v53, vcc
	v_add_f32_e32 v52, v52, v53
	v_cvt_f32_i32_e32 v56, v92
	v_mul_f32_e32 v53, v79, v54
	v_cmp_gt_f32_e32 vcc, s3, v53
	v_mul_f32_e32 v26, v52, v26
	v_mul_f32_e32 v57, v56, v73
	v_cndmask_b32_e32 v53, 0, v82, vcc
	v_fmac_f32_e32 v53, v79, v54
	v_exp_f32_e32 v53, v53
	v_cndmask_b32_e32 v52, 0, v86, vcc
	v_cmp_gt_f32_e32 vcc, s3, v57
	v_cmp_lt_i32_e64 s[0:1], -1, v92
	v_ldexp_f32 v93, v53, v52
	ds_read_b128 v[52:55], v62 offset:30464
	v_cndmask_b32_e32 v57, 0, v82, vcc
	v_fmac_f32_e32 v57, v56, v73
	v_exp_f32_e32 v94, v57
	ds_read_b128 v[56:59], v62 offset:30528
	s_waitcnt lgkmcnt(1)
	v_mfma_f32_16x16x32_bf16 v[0:3], v[52:55], v[0:3], 0
	ds_read_b128 v[52:55], v62 offset:30592
	v_cndmask_b32_e32 v95, 0, v86, vcc
	v_ldexp_f32 v94, v94, v95
	s_waitcnt lgkmcnt(1)
	v_mfma_f32_16x16x32_bf16 v[0:3], v[56:59], v[4:7], v[0:3]
	v_or_b32_e32 v4, 0x70, v61
	v_sub_u32_e32 v56, v78, v4
	ds_read_b128 v[4:7], v62 offset:30656
	v_cvt_f32_u32_e32 v57, v56
	s_waitcnt lgkmcnt(1)
	v_mfma_f32_16x16x32_bf16 v[0:3], v[52:55], v[8:11], v[0:3]
	v_cvt_f32_i32_e32 v9, v56
	v_cmp_gt_i32_e32 vcc, 1, v92
	v_mul_f32_e32 v8, v79, v57
	s_waitcnt lgkmcnt(0)
; #define LAS __attribute__((address_space(3)))
; DI unsigned cvt_pk_bf16(float lo, float hi) { unsigned r; asm volatile("v_cvt_pk_bf16_f32 %0, %1, %2" : "=v"(r) : "v"(lo), "v"(hi)); return r; }
; #define MFMA16(a, b, c) __builtin_amdgcn_mfma_f32_16x16x32_bf16((a), (b), (c), 0, 0, 0)
; DI void ret_out_item(const Params& p, int l, int b, int h, int c, LAS unsigned char* lds) {
;     ...
;     for (int kc = 0; kc < 4; ++kc) {
;         f32x4 s[2];
; #pragma unroll
;         for (int hf = 0; hf < 2; ++hf) {
;             s[hf] = (f32x4){0.f, 0.f, 0.f, 0.f};
; #pragma unroll
;             for (int ks = 0; ks < 4; ++ks) s[hf] = MFMA16(*(const LAS bf16x8*)(kcp + (2 * kc + hf) * 16 * RS + ks * 64), qf[ks], s[hf]);
; #pragma unroll
;             for (int j = 0; j < 4; ++j) {
;                 const int m = (2 * kc + hf) * 16 + q4 * 4 + j, d = tl - m;
;                 const float w = (d >= 0 ? exp2f(lgf * (float)d) : 0.f) + (d <= 0 ? exp2f(-lgb * (float)d) : 0.f);
;                 s[hf][j] *= w;
;             }
;         }
;         u32x4 w4; w4.x = cvt_pk_bf16(s[0][0], s[0][1]); w4.y = cvt_pk_bf16(s[0][2], s[0][3]); w4.z = cvt_pk_bf16(s[1][0], s[1][1]); w4.w = cvt_pk_bf16(s[1][2], s[1][3]);
;         const bf16x8 pb = __builtin_bit_cast(bf16x8, w4);
; #pragma unroll
;         for (int d = 0; d < 8; ++d) {
;             const u32x2 lo = *(const LAS u32x2*)(vtp + d * 16 * RS + kc * 64), hi = *(const LAS u32x2*)(vtp + d * 16 * RS + kc * 64 + 32);
;             u32x4 a4; a4.x = lo.x; a4.y = lo.y; a4.z = hi.x; a4.w = hi.y;
;             oacc[d] = MFMA16(__builtin_bit_cast(bf16x8, a4), pb, oacc[d]);
;         }
;     }
;     float sum = 0.f;
; #pragma unroll
;     for (int d = 0; d < 8; ++d) sum += oacc[d][0] + oacc[d][1] + oacc[d][2] + oacc[d][3];
;     sum += __shfl_xor(sum, 16); sum += __shfl_xor(sum, 32);
	v_mfma_f32_16x16x32_bf16 v[0:3], v[4:7], v[12:15], v[0:3]
	v_cndmask_b32_e32 v92, 0, v94, vcc
	v_cmp_gt_f32_e32 vcc, s3, v8
	v_mul_f32_e32 v5, v9, v73
	v_cndmask_b32_e64 v93, 0, v93, s[0:1]
	v_cndmask_b32_e32 v8, 0, v82, vcc
	v_cndmask_b32_e32 v4, 0, v86, vcc
	v_cmp_gt_f32_e32 vcc, s3, v5
	v_fmac_f32_e32 v8, v79, v57
	v_exp_f32_e32 v8, v8
	v_cndmask_b32_e32 v5, 0, v82, vcc
	v_fmac_f32_e32 v5, v9, v73
	v_exp_f32_e32 v5, v5
	v_cndmask_b32_e32 v6, 0, v86, vcc
	v_ldexp_f32 v4, v8, v4
	v_cmp_lt_i32_e64 s[0:1], -1, v56
	v_ldexp_f32 v5, v5, v6
	v_or_b32_e32 v6, 0x71, v61
	v_sub_u32_e32 v6, v78, v6
	v_cvt_f32_u32_e32 v7, v6
	v_cmp_gt_i32_e32 vcc, 1, v56
	v_cndmask_b32_e64 v4, 0, v4, s[0:1]
	v_cmp_lt_i32_e64 s[0:1], -1, v6
	v_cndmask_b32_e32 v5, 0, v5, vcc
	v_add_f32_e32 v4, v4, v5
	v_mul_f32_e32 v5, v79, v7
	v_cmp_gt_f32_e32 vcc, s3, v5
	v_mul_f32_e32 v4, v4, v0
	v_add_f32_e32 v92, v93, v92
	v_cndmask_b32_e32 v5, 0, v82, vcc
	v_fmac_f32_e32 v5, v79, v7
	v_exp_f32_e32 v5, v5
	v_cvt_f32_i32_e32 v7, v6
	v_cndmask_b32_e32 v0, 0, v86, vcc
	v_mul_f32_e32 v27, v92, v27
	v_ldexp_f32 v0, v5, v0
	v_mul_f32_e32 v5, v7, v73
	v_cmp_gt_f32_e32 vcc, s3, v5
	v_cndmask_b32_e64 v0, 0, v0, s[0:1]
	s_nop 0
	v_cndmask_b32_e32 v5, 0, v82, vcc
	v_fmac_f32_e32 v5, v7, v73
	v_exp_f32_e32 v5, v5
	v_cndmask_b32_e32 v7, 0, v86, vcc
	v_cmp_gt_i32_e32 vcc, 1, v6
	v_ldexp_f32 v5, v5, v7
	v_or_b32_e32 v7, 0x72, v61
	v_sub_u32_e32 v7, v78, v7
	v_cvt_f32_u32_e32 v8, v7
	v_cndmask_b32_e32 v5, 0, v5, vcc
	v_cvt_f32_i32_e32 v6, v7
	v_add_f32_e32 v0, v0, v5
	v_mul_f32_e32 v5, v79, v8
	v_cmp_gt_f32_e32 vcc, s3, v5
	v_cmp_lt_i32_e64 s[0:1], -1, v7
	s_nop 0
	v_cndmask_b32_e32 v5, 0, v82, vcc
	v_fmac_f32_e32 v5, v79, v8
	v_mul_f32_e32 v8, v0, v1
	v_mul_f32_e32 v1, v6, v73
	v_cndmask_b32_e32 v0, 0, v86, vcc
	v_cmp_gt_f32_e32 vcc, s3, v1
	v_exp_f32_e32 v5, v5
	s_nop 0
	v_cndmask_b32_e32 v1, 0, v82, vcc
	v_fmac_f32_e32 v1, v6, v73
	v_exp_f32_e32 v1, v1
	v_ldexp_f32 v0, v5, v0
	v_cndmask_b32_e32 v5, 0, v86, vcc
	v_cmp_gt_i32_e32 vcc, 1, v7
	v_ldexp_f32 v1, v1, v5
	v_or_b32_e32 v5, 0x73, v61
	v_sub_u32_e32 v5, v78, v5
	v_cvt_f32_u32_e32 v6, v5
	v_cndmask_b32_e64 v0, 0, v0, s[0:1]
	v_cndmask_b32_e32 v1, 0, v1, vcc
	v_add_f32_e32 v0, v0, v1
	v_mul_f32_e32 v1, v79, v6
	v_cmp_gt_f32_e32 vcc, s3, v1
	v_mul_f32_e32 v7, v0, v2
	v_cmp_lt_i32_e64 s[0:1], -1, v5
	v_cndmask_b32_e32 v1, 0, v82, vcc
	v_fmac_f32_e32 v1, v79, v6
	v_exp_f32_e32 v1, v1
	v_cvt_f32_i32_e32 v6, v5
	v_cndmask_b32_e32 v0, 0, v86, vcc
	v_ldexp_f32 v0, v1, v0
	v_mul_f32_e32 v1, v6, v73
	v_cmp_gt_f32_e32 vcc, s3, v1
	v_cndmask_b32_e64 v0, 0, v0, s[0:1]
	s_nop 0
	v_cndmask_b32_e32 v1, 0, v82, vcc
	v_fmac_f32_e32 v1, v6, v73
	v_exp_f32_e32 v1, v1
	v_cndmask_b32_e32 v2, 0, v86, vcc
	v_cmp_gt_i32_e32 vcc, 1, v5
	v_ldexp_f32 v1, v1, v2
	s_nop 0
	v_cndmask_b32_e32 v1, 0, v1, vcc
	v_add_f32_e32 v0, v0, v1
	v_mul_f32_e32 v3, v0, v3
	v_cvt_pk_bf16_f32 v0, v24, v25
	v_cvt_pk_bf16_f32 v1, v26, v27
	v_cvt_pk_bf16_f32 v2, v4, v8
	v_cvt_pk_bf16_f32 v3, v7, v3
	ds_read2_b64 v[4:7], v60 offset0:24 offset1:28
	s_waitcnt lgkmcnt(0)
	v_mfma_f32_16x16x32_bf16 v[52:55], v[4:7], v[0:3], v[16:19]
	ds_read2_b64 v[4:7], v63 offset0:56 offset1:60
	v_cmp_lt_i32_e32 vcc, v88, v89
	s_waitcnt lgkmcnt(0)
	v_mfma_f32_16x16x32_bf16 v[24:27], v[4:7], v[0:3], v[20:23]
	ds_read2_b64 v[4:7], v64 offset0:88 offset1:92
	s_waitcnt lgkmcnt(0)
	v_mfma_f32_16x16x32_bf16 v[20:23], v[4:7], v[0:3], v[28:31]
	ds_read2_b64 v[4:7], v65 offset0:120 offset1:124
	s_nop 1
	ds_read2_b64 v[28:31], v81 offset0:248 offset1:252
	s_waitcnt lgkmcnt(1)
	v_mfma_f32_16x16x32_bf16 v[16:19], v[4:7], v[0:3], v[32:35]
	ds_read2_b64 v[4:7], v66 offset0:152 offset1:156
	s_waitcnt lgkmcnt(0)
	v_mfma_f32_16x16x32_bf16 v[12:15], v[4:7], v[0:3], v[36:39]
	ds_read2_b64 v[4:7], v67 offset0:184 offset1:188
	s_waitcnt lgkmcnt(0)
	v_mfma_f32_16x16x32_bf16 v[8:11], v[4:7], v[0:3], v[40:43]
	ds_read2_b64 v[4:7], v80 offset0:216 offset1:220
	s_nop 1
	v_lshl_add_u64 v[42:43], v[76:77], 0, v[68:69]
	s_waitcnt lgkmcnt(0)
	v_mfma_f32_16x16x32_bf16 v[4:7], v[4:7], v[0:3], v[44:47]
	v_mfma_f32_16x16x32_bf16 v[0:3], v[28:31], v[0:3], v[48:51]
	v_mov_b32_e32 v28, v52
	v_mov_b32_e32 v29, v24
	v_mov_b32_e32 v30, v53
	v_mov_b32_e32 v31, v25
	v_pk_add_f32 v[28:29], v[28:29], v[30:31]
	v_mov_b32_e32 v30, v54
	v_mov_b32_e32 v31, v26
	v_pk_add_f32 v[28:29], v[30:31], v[28:29]
	v_mov_b32_e32 v30, v55
	v_mov_b32_e32 v31, v27
	v_pk_add_f32 v[28:29], v[30:31], v[28:29]
	v_mov_b32_e32 v30, v21
	v_add_f32_e32 v28, 0, v28
	v_add_f32_e32 v32, v28, v29
	v_mov_b32_e32 v28, v20
	v_mov_b32_e32 v29, v16
	v_mov_b32_e32 v31, v17
	v_pk_add_f32 v[28:29], v[28:29], v[30:31]
	v_mov_b32_e32 v30, v22
	v_mov_b32_e32 v31, v18
	v_pk_add_f32 v[28:29], v[30:31], v[28:29]
	v_mov_b32_e32 v30, v23
	v_mov_b32_e32 v31, v19
	v_pk_add_f32 v[28:29], v[30:31], v[28:29]
	v_mov_b32_e32 v30, v13
	v_add_f32_e32 v28, v32, v28
	v_add_f32_e32 v32, v28, v29
	v_mov_b32_e32 v28, v12
	v_mov_b32_e32 v29, v8
	v_mov_b32_e32 v31, v9
	v_pk_add_f32 v[28:29], v[28:29], v[30:31]
	v_mov_b32_e32 v30, v14
	v_mov_b32_e32 v31, v10
	v_pk_add_f32 v[28:29], v[30:31], v[28:29]
	v_mov_b32_e32 v30, v15
	v_mov_b32_e32 v31, v11
	v_pk_add_f32 v[28:29], v[30:31], v[28:29]
	v_mov_b32_e32 v30, v5
	v_add_f32_e32 v28, v32, v28
	v_add_f32_e32 v32, v28, v29
	v_mov_b32_e32 v28, v4
	v_mov_b32_e32 v29, v0
	v_mov_b32_e32 v31, v1
	v_pk_add_f32 v[28:29], v[28:29], v[30:31]
	v_mov_b32_e32 v30, v6
	v_mov_b32_e32 v31, v2
	v_pk_add_f32 v[28:29], v[30:31], v[28:29]
	v_mov_b32_e32 v30, v7
	v_mov_b32_e32 v31, v3
	v_pk_add_f32 v[28:29], v[30:31], v[28:29]
	s_nop 0
	v_add_f32_e32 v28, v32, v28
	v_add_f32_e32 v28, v28, v29
	v_cndmask_b32_e32 v29, v87, v88, vcc
	v_lshlrev_b32_e32 v50, 2, v29
	ds_bpermute_b32 v29, v50, v28
	v_cmp_lt_i32_e32 vcc, v90, v89
	s_waitcnt lgkmcnt(0)
; DI float silu(float v) { return v * __builtin_amdgcn_rcpf(1.f + __builtin_amdgcn_exp2f(-1.4426950408889634f * v)); }
; DI void st_bf16x4(bf16_t* p, f32x4 v) { u32x2 w; w.x = cvt_pk_bf16(v[0], v[1]); w.y = cvt_pk_bf16(v[2], v[3]); *(u32x2*)p = w; }
; DI void ret_out_item(const Params& p, int l, int b, int h, int c, LAS unsigned char* lds) {
;     ...
;     const float mu = sum * (1.f / 128.f);
;     float sq = 0.f;
; #pragma unroll
;     for (int d = 0; d < 8; ++d) { oacc[d] -= mu; sq += oacc[d][0] * oacc[d][0] + oacc[d][1] * oacc[d][1] + oacc[d][2] * oacc[d][2] + oacc[d][3] * oacc[d][3]; }
;     sq += __shfl_xor(sq, 16); sq += __shfl_xor(sq, 32);
;     const float rs = rsqrtf(sq * (1.f / 128.f) + 1e-5f);
;     const bf16_t* gp = P + row * INP + C_RG + h * 128 + q4 * 4;
;     bf16_t* op = (bf16_t*)(ws + WS_YMIX) + row * DM + 1408 + h * 128 + q4 * 4;
; #pragma unroll
;     for (int d = 0; d < 8; ++d) {
;         const u32x2 g2 = *(const u32x2*)(gp + d * 16);
;         f32x4 g; g[0] = __uint_as_float(g2.x << 16); g[1] = __uint_as_float(g2.x & 0xffff0000u); g[2] = __uint_as_float(g2.y << 16); g[3] = __uint_as_float(g2.y & 0xffff0000u);
;         f32x4 y;
; #pragma unroll
;         for (int j = 0; j < 4; ++j) y[j] = oacc[d][j] * rs * silu(g[j]);
;         st_bf16x4(op + d * 16, y);
	v_add_f32_e32 v28, v28, v29
	v_cndmask_b32_e32 v29, v87, v90, vcc
	v_lshlrev_b32_e32 v51, 2, v29
	ds_bpermute_b32 v29, v51, v28
	s_waitcnt lgkmcnt(0)
	v_add_f32_e32 v56, v28, v29
	v_add_co_u32_e32 v28, vcc, s35, v42
	v_fmamk_f32 v38, v56, 0xbc000000, v53
	s_nop 0
	v_addc_co_u32_e32 v29, vcc, 0, v43, vcc
	global_load_dwordx2 v[44:45], v[28:29], off offset:2432
	global_load_dwordx2 v[140:141], v[28:29], off offset:2464
	global_load_dwordx2 v[142:143], v[28:29], off offset:2496
	global_load_dwordx2 v[144:145], v[28:29], off offset:2528
	global_load_dwordx2 v[146:147], v[28:29], off offset:2560
	global_load_dwordx2 v[148:149], v[28:29], off offset:2592
	global_load_dwordx2 v[150:151], v[28:29], off offset:2624
	global_load_dwordx2 v[152:153], v[28:29], off offset:2656
	v_fmamk_f32 v39, v56, 0xbc000000, v25
	v_fmac_f32_e32 v24, 0xbc000000, v56
	v_fmac_f32_e32 v52, 0xbc000000, v56
	v_fmamk_f32 v31, v56, 0xbc000000, v27
	v_fmamk_f32 v35, v56, 0xbc000000, v26
	v_mov_b32_e32 v53, v24
	v_pk_mul_f32 v[26:27], v[38:39], v[38:39]
	v_fmamk_f32 v34, v56, 0xbc000000, v54
	v_pk_fma_f32 v[26:27], v[52:53], v[52:53], v[26:27]
	v_fmamk_f32 v30, v56, 0xbc000000, v55
	v_pk_fma_f32 v[26:27], v[34:35], v[34:35], v[26:27]
	v_fmamk_f32 v29, v56, 0xbc000000, v13
	v_fmac_f32_e32 v12, 0xbc000000, v56
	v_fmamk_f32 v28, v56, 0xbc000000, v9
	v_pk_fma_f32 v[46:47], v[30:31], v[30:31], v[26:27]
	v_fmamk_f32 v37, v56, 0xbc000000, v22
	v_fmamk_f32 v41, v56, 0xbc000000, v21
	v_fmac_f32_e32 v20, 0xbc000000, v56
	v_fmamk_f32 v40, v56, 0xbc000000, v17
	v_fmamk_f32 v22, v56, 0xbc000000, v11
	v_fmamk_f32 v26, v56, 0xbc000000, v10
	v_fmac_f32_e32 v8, 0xbc000000, v56
	v_mov_b32_e32 v9, v12
	v_pk_mul_f32 v[10:11], v[28:29], v[28:29]
	v_fmamk_f32 v32, v56, 0xbc000000, v19
	v_fmamk_f32 v36, v56, 0xbc000000, v18
	v_fmac_f32_e32 v16, 0xbc000000, v56
	v_mov_b32_e32 v17, v20
	v_pk_mul_f32 v[18:19], v[40:41], v[40:41]
	v_fmamk_f32 v27, v56, 0xbc000000, v14
	v_pk_fma_f32 v[10:11], v[8:9], v[8:9], v[10:11]
	v_fmamk_f32 v33, v56, 0xbc000000, v23
	v_pk_fma_f32 v[18:19], v[16:17], v[16:17], v[18:19]
	v_fmamk_f32 v23, v56, 0xbc000000, v15
	v_pk_fma_f32 v[10:11], v[26:27], v[26:27], v[10:11]
	v_fmamk_f32 v15, v56, 0xbc000000, v5
	v_fmac_f32_e32 v4, 0xbc000000, v56
	v_fmamk_f32 v14, v56, 0xbc000000, v1
	v_pk_fma_f32 v[18:19], v[36:37], v[36:37], v[18:19]
	v_pk_fma_f32 v[48:49], v[22:23], v[22:23], v[10:11]
	v_fmamk_f32 v11, v56, 0xbc000000, v6
	v_fmamk_f32 v6, v56, 0xbc000000, v3
	v_fmamk_f32 v10, v56, 0xbc000000, v2
	v_fmac_f32_e32 v0, 0xbc000000, v56
	v_mov_b32_e32 v1, v4
	v_pk_mul_f32 v[2:3], v[14:15], v[14:15]
	v_pk_fma_f32 v[18:19], v[32:33], v[32:33], v[18:19]
	v_pk_fma_f32 v[2:3], v[0:1], v[0:1], v[2:3]
	v_add_f32_e32 v1, v46, v47
	v_add_f32_e32 v1, v19, v1
	v_add_f32_e32 v1, v18, v1
	v_fmamk_f32 v7, v56, 0xbc000000, v7
	v_pk_fma_f32 v[2:3], v[10:11], v[10:11], v[2:3]
	v_add_f32_e32 v1, v49, v1
	v_pk_fma_f32 v[2:3], v[6:7], v[6:7], v[2:3]
	v_add_f32_e32 v1, v48, v1
	v_add_f32_e32 v1, v3, v1
	v_add_f32_e32 v1, v2, v1
	ds_bpermute_b32 v2, v50, v1
	v_lshl_add_u64 v[18:19], v[42:43], 0, s[12:13]
	v_mov_b32_e32 v49, v52
	s_waitcnt lgkmcnt(0)
	v_add_f32_e32 v1, v1, v2
	ds_bpermute_b32 v2, v51, v1
	v_mov_b32_e32 v51, v24
	s_waitcnt lgkmcnt(0)
	v_add_f32_e32 v1, v1, v2
	v_fmamk_f32 v1, v1, 0x3c000000, v91
	v_mul_f32_e32 v2, 0x4b800000, v1
	v_cmp_gt_f32_e32 vcc, s34, v1
	s_waitcnt vmcnt(7)
	v_and_b32_e32 v42, 0xffff0000, v44
	v_cndmask_b32_e32 v1, v1, v2, vcc
	v_rsq_f32_e32 v1, v1
	v_and_b32_e32 v46, 0xffff0000, v45
	v_mul_f32_e32 v2, 0x45800000, v1
	v_cndmask_b32_e32 v3, v1, v2, vcc
	v_lshlrev_b32_e32 v2, 16, v44
	v_mul_f32_e32 v1, 0xbfb8aa3b, v2
	v_exp_f32_e32 v1, v1
	v_lshlrev_b32_e32 v44, 16, v45
	v_mov_b32_e32 v43, v3
	v_mov_b32_e32 v45, v3
	v_add_f32_e32 v1, 1.0, v1
	v_rcp_f32_e32 v48, v1
	v_mul_f32_e32 v1, 0xbfb8aa3b, v42
	v_exp_f32_e32 v1, v1
	v_mov_b32_e32 v47, v3
	v_pk_mul_f32 v[48:49], v[48:49], v[2:3]
	v_add_f32_e32 v1, 1.0, v1
	v_mul_f32_e32 v2, v48, v49
	v_rcp_f32_e32 v48, v1
	v_mul_f32_e32 v1, 0xbfb8aa3b, v44
	v_exp_f32_e32 v1, v1
	v_mov_b32_e32 v49, v38
	v_pk_mul_f32 v[42:43], v[48:49], v[42:43]
	v_add_f32_e32 v1, 1.0, v1
	v_mul_f32_e32 v5, v42, v43
	v_rcp_f32_e32 v42, v1
	v_mul_f32_e32 v1, 0xbfb8aa3b, v46
	v_exp_f32_e32 v1, v1
	v_mov_b32_e32 v43, v34
	v_pk_mul_f32 v[42:43], v[42:43], v[44:45]
	v_mov_b32_e32 v45, v30
	v_add_f32_e32 v1, 1.0, v1
	v_rcp_f32_e32 v44, v1
	v_mul_f32_e32 v1, v42, v43
	v_pk_mul_f32 v[42:43], v[44:45], v[46:47]
	s_nop 0
	v_mul_f32_e32 v9, v42, v43
	v_cvt_pk_bf16_f32 v42, v2, v5
	v_cvt_pk_bf16_f32 v43, v1, v9
	s_waitcnt vmcnt(6)
	v_mov_b32_e32 v44, v140
	v_mov_b32_e32 v45, v141
	v_lshlrev_b64 v[46:47], 12, v[74:75]
	v_lshl_add_u64 v[46:47], s[50:51], 0, v[46:47]
	v_lshl_add_u64 v[46:47], v[46:47], 0, s[16:17]
	v_lshl_add_u64 v[46:47], v[46:47], 0, v[68:69]
	v_add_co_u32_e32 v48, vcc, s36, v46
	v_lshlrev_b32_e32 v2, 16, v44
	v_mul_f32_e32 v1, 0xbfb8aa3b, v2
	v_exp_f32_e32 v1, v1
	v_addc_co_u32_e32 v49, vcc, 0, v47, vcc
	global_store_dwordx2 v[48:49], v[42:43], off offset:2816
	v_add_f32_e32 v1, 1.0, v1
	v_rcp_f32_e32 v50, v1
	v_and_b32_e32 v42, 0xffff0000, v44
	v_lshlrev_b32_e32 v44, 16, v45
	v_mul_f32_e32 v5, 0xbfb8aa3b, v42
	v_and_b32_e32 v48, 0xffff0000, v45
	v_exp_f32_e32 v5, v5
	v_pk_mul_f32 v[24:25], v[50:51], v[2:3]
	v_mul_f32_e32 v2, 0xbfb8aa3b, v44
	v_exp_f32_e32 v2, v2
	v_mul_f32_e32 v9, 0xbfb8aa3b, v48
	v_exp_f32_e32 v9, v9
	v_add_f32_e32 v1, 1.0, v5
	v_rcp_f32_e32 v38, v1
	v_add_f32_e32 v2, 1.0, v2
	v_rcp_f32_e32 v34, v2
	v_add_f32_e32 v2, 1.0, v9
	v_rcp_f32_e32 v30, v2
	v_mov_b32_e32 v43, v3
	v_mul_f32_e32 v1, v24, v25
	v_pk_mul_f32 v[24:25], v[38:39], v[42:43]
	v_mov_b32_e32 v45, v3
	v_mul_f32_e32 v5, v24, v25
	v_pk_mul_f32 v[24:25], v[34:35], v[44:45]
	v_mov_b32_e32 v49, v3
	v_mul_f32_e32 v2, v24, v25
	v_pk_mul_f32 v[24:25], v[30:31], v[48:49]
	v_cvt_pk_bf16_f32 v30, v1, v5
	v_mov_b32_e32 v43, v20
	v_mul_f32_e32 v9, v24, v25
	v_cvt_pk_bf16_f32 v31, v2, v9
	s_waitcnt vmcnt(6)
; DI float silu(float v) { return v * __builtin_amdgcn_rcpf(1.f + __builtin_amdgcn_exp2f(-1.4426950408889634f * v)); }
; DI void st_bf16x4(bf16_t* p, f32x4 v) { u32x2 w; w.x = cvt_pk_bf16(v[0], v[1]); w.y = cvt_pk_bf16(v[2], v[3]); *(u32x2*)p = w; }
; DI void ret_out_item(const Params& p, int l, int b, int h, int c, LAS unsigned char* lds) {
;     ...
; #pragma unroll
;     for (int d = 0; d < 8; ++d) {
;         const u32x2 g2 = *(const u32x2*)(gp + d * 16);
;         f32x4 g; g[0] = __uint_as_float(g2.x << 16); g[1] = __uint_as_float(g2.x & 0xffff0000u); g[2] = __uint_as_float(g2.y << 16); g[3] = __uint_as_float(g2.y & 0xffff0000u);
;         f32x4 y;
; #pragma unroll
;         for (int j = 0; j < 4; ++j) y[j] = oacc[d][j] * rs * silu(g[j]);
;         st_bf16x4(op + d * 16, y);
;     }
	v_mov_b32_e32 v34, v142
	v_mov_b32_e32 v35, v143
	v_lshl_add_u64 v[24:25], v[46:47], 0, s[14:15]
	global_store_dwordx2 v[24:25], v[30:31], off offset:32
	v_mov_b32_e32 v31, v3
	v_mov_b32_e32 v39, v3
	v_lshlrev_b32_e32 v2, 16, v34
	v_mul_f32_e32 v1, 0xbfb8aa3b, v2
	v_exp_f32_e32 v1, v1
	v_and_b32_e32 v30, 0xffff0000, v34
	v_lshlrev_b32_e32 v34, 16, v35
	v_and_b32_e32 v38, 0xffff0000, v35
	v_add_f32_e32 v1, 1.0, v1
	v_rcp_f32_e32 v42, v1
	v_mul_f32_e32 v1, 0xbfb8aa3b, v30
	v_exp_f32_e32 v1, v1
	v_mov_b32_e32 v35, v3
	v_pk_mul_f32 v[20:21], v[42:43], v[2:3]
	v_add_f32_e32 v1, 1.0, v1
	v_mul_f32_e32 v2, v20, v21
	v_rcp_f32_e32 v20, v1
	v_mul_f32_e32 v1, 0xbfb8aa3b, v34
	v_exp_f32_e32 v1, v1
	v_mov_b32_e32 v21, v41
	v_pk_mul_f32 v[20:21], v[20:21], v[30:31]
	v_mov_b32_e32 v31, v33
	v_add_f32_e32 v1, 1.0, v1
	v_mul_f32_e32 v5, v20, v21
	v_rcp_f32_e32 v20, v1
	v_mul_f32_e32 v1, 0xbfb8aa3b, v38
	v_exp_f32_e32 v1, v1
	v_mov_b32_e32 v21, v37
	v_pk_mul_f32 v[20:21], v[20:21], v[34:35]
	v_mov_b32_e32 v33, v12
	v_add_f32_e32 v1, 1.0, v1
	v_rcp_f32_e32 v30, v1
	v_mul_f32_e32 v1, v20, v21
	v_pk_mul_f32 v[20:21], v[30:31], v[38:39]
	s_nop 0
	v_mul_f32_e32 v9, v20, v21
	v_cvt_pk_bf16_f32 v20, v2, v5
	v_cvt_pk_bf16_f32 v21, v1, v9
	s_waitcnt vmcnt(6)
	v_mov_b32_e32 v30, v144
	v_mov_b32_e32 v31, v145
	v_mov_b32_e32 v39, v16
	global_store_dwordx2 v[24:25], v[20:21], off offset:64
	v_mov_b32_e32 v21, v3
	v_lshlrev_b32_e32 v2, 16, v30
	v_mul_f32_e32 v1, 0xbfb8aa3b, v2
	v_exp_f32_e32 v1, v1
	v_and_b32_e32 v20, 0xffff0000, v30
	v_lshlrev_b32_e32 v30, 16, v31
	v_and_b32_e32 v34, 0xffff0000, v31
	v_add_f32_e32 v1, 1.0, v1
	v_rcp_f32_e32 v38, v1
	v_mul_f32_e32 v1, 0xbfb8aa3b, v20
	v_exp_f32_e32 v1, v1
	v_mov_b32_e32 v31, v3
	v_pk_mul_f32 v[16:17], v[38:39], v[2:3]
	v_add_f32_e32 v1, 1.0, v1
	v_mul_f32_e32 v2, v16, v17
	v_rcp_f32_e32 v16, v1
	v_mul_f32_e32 v1, 0xbfb8aa3b, v30
	v_exp_f32_e32 v1, v1
	v_mov_b32_e32 v17, v40
	v_pk_mul_f32 v[16:17], v[16:17], v[20:21]
	v_mov_b32_e32 v21, v32
	v_add_f32_e32 v1, 1.0, v1
	v_mul_f32_e32 v5, v16, v17
	v_rcp_f32_e32 v16, v1
	v_mul_f32_e32 v1, 0xbfb8aa3b, v34
	v_exp_f32_e32 v1, v1
	v_mov_b32_e32 v17, v36
	v_pk_mul_f32 v[16:17], v[16:17], v[30:31]
	v_add_f32_e32 v1, 1.0, v1
	v_rcp_f32_e32 v20, v1
	v_mul_f32_e32 v1, v16, v17
	v_pk_mul_f32 v[16:17], v[20:21], v[34:35]
	s_nop 0
	v_mul_f32_e32 v9, v16, v17
	v_cvt_pk_bf16_f32 v16, v2, v5
	v_cvt_pk_bf16_f32 v17, v1, v9
	s_waitcnt vmcnt(6)
	v_mov_b32_e32 v20, v146
	v_mov_b32_e32 v21, v147
	v_lshlrev_b32_e32 v2, 16, v20
	v_mul_f32_e32 v1, 0xbfb8aa3b, v2
	v_exp_f32_e32 v1, v1
	global_store_dwordx2 v[24:25], v[16:17], off offset:96
	v_and_b32_e32 v16, 0xffff0000, v20
	v_lshlrev_b32_e32 v20, 16, v21
	v_add_f32_e32 v1, 1.0, v1
	v_rcp_f32_e32 v32, v1
	v_mul_f32_e32 v1, 0xbfb8aa3b, v16
	v_exp_f32_e32 v1, v1
	v_mov_b32_e32 v17, v3
	v_pk_mul_f32 v[12:13], v[32:33], v[2:3]
	v_and_b32_e32 v30, 0xffff0000, v21
	v_add_f32_e32 v1, 1.0, v1
	v_mul_f32_e32 v2, v12, v13
	v_rcp_f32_e32 v12, v1
	v_mul_f32_e32 v1, 0xbfb8aa3b, v20
	v_exp_f32_e32 v1, v1
	v_mov_b32_e32 v13, v29
	v_pk_mul_f32 v[12:13], v[12:13], v[16:17]
	v_mov_b32_e32 v21, v3
	v_add_f32_e32 v1, 1.0, v1
	v_mul_f32_e32 v5, v12, v13
	v_rcp_f32_e32 v12, v1
	v_mul_f32_e32 v1, 0xbfb8aa3b, v30
	v_exp_f32_e32 v1, v1
	v_mov_b32_e32 v13, v27
	v_pk_mul_f32 v[12:13], v[12:13], v[20:21]
	v_mov_b32_e32 v17, v23
	v_add_f32_e32 v1, 1.0, v1
	v_rcp_f32_e32 v16, v1
	v_mul_f32_e32 v1, v12, v13
	v_mov_b32_e32 v20, v3
	v_pk_mul_f32 v[12:13], v[16:17], v[30:31]
	s_nop 0
	v_mul_f32_e32 v9, v12, v13
	v_cvt_pk_bf16_f32 v12, v2, v5
	v_cvt_pk_bf16_f32 v13, v1, v9
	s_waitcnt vmcnt(6)
	v_mov_b32_e32 v16, v148
	v_mov_b32_e32 v17, v149
	v_mov_b32_e32 v30, v3
	global_store_dwordx2 v[24:25], v[12:13], off offset:128
	v_mov_b32_e32 v12, v3
	v_lshlrev_b32_e32 v13, 16, v16
	v_and_b32_e32 v21, 0xffff0000, v16
	v_mul_f32_e32 v1, 0xbfb8aa3b, v13
	v_exp_f32_e32 v1, v1
	v_mul_f32_e32 v2, 0xbfb8aa3b, v21
	v_exp_f32_e32 v2, v2
	v_lshlrev_b32_e32 v31, 16, v17
	v_add_f32_e32 v1, 1.0, v1
	v_rcp_f32_e32 v9, v1
	v_add_f32_e32 v1, 1.0, v2
	v_rcp_f32_e32 v29, v1
	v_and_b32_e32 v17, 0xffff0000, v17
	v_pk_mul_f32 v[8:9], v[8:9], v[12:13]
	v_mul_f32_e32 v2, 0xbfb8aa3b, v31
	v_mul_f32_e32 v1, v8, v9
	v_pk_mul_f32 v[8:9], v[28:29], v[20:21]
	v_exp_f32_e32 v2, v2
	v_mul_f32_e32 v5, v8, v9
	v_mul_f32_e32 v8, 0xbfb8aa3b, v17
	v_exp_f32_e32 v8, v8
	v_add_f32_e32 v2, 1.0, v2
	v_rcp_f32_e32 v27, v2
	v_mov_b32_e32 v16, v3
	v_add_f32_e32 v2, 1.0, v8
	v_rcp_f32_e32 v23, v2
	v_pk_mul_f32 v[8:9], v[26:27], v[30:31]
	s_nop 0
	v_mul_f32_e32 v2, v8, v9
	v_pk_mul_f32 v[8:9], v[22:23], v[16:17]
	s_nop 0
	v_mul_f32_e32 v9, v8, v9
	v_cvt_pk_bf16_f32 v8, v1, v5
	v_cvt_pk_bf16_f32 v9, v2, v9
	s_waitcnt vmcnt(6)
	v_mov_b32_e32 v12, v150
	v_mov_b32_e32 v13, v151
	v_and_b32_e32 v17, 0xffff0000, v12
	global_store_dwordx2 v[24:25], v[8:9], off offset:160
	v_lshlrev_b32_e32 v9, 16, v12
	v_mul_f32_e32 v1, 0xbfb8aa3b, v9
	v_exp_f32_e32 v1, v1
	v_mov_b32_e32 v8, v3
	v_lshlrev_b32_e32 v21, 16, v13
	v_and_b32_e32 v13, 0xffff0000, v13
	v_add_f32_e32 v1, 1.0, v1
	v_rcp_f32_e32 v5, v1
	v_mul_f32_e32 v1, 0xbfb8aa3b, v17
	v_exp_f32_e32 v1, v1
	v_mov_b32_e32 v12, v3
	v_pk_mul_f32 v[4:5], v[4:5], v[8:9]
	v_mov_b32_e32 v8, v7
	v_add_f32_e32 v1, 1.0, v1
	v_mul_f32_e32 v2, v4, v5
	v_rcp_f32_e32 v5, v1
	v_mul_f32_e32 v1, 0xbfb8aa3b, v21
	v_exp_f32_e32 v1, v1
	v_mov_b32_e32 v4, v15
	v_pk_mul_f32 v[4:5], v[4:5], v[16:17]
	v_add_f32_e32 v1, 1.0, v1
	v_mul_f32_e32 v15, v4, v5
	v_rcp_f32_e32 v5, v1
	v_mul_f32_e32 v1, 0xbfb8aa3b, v13
	v_exp_f32_e32 v1, v1
	v_mov_b32_e32 v4, v11
	v_pk_mul_f32 v[4:5], v[4:5], v[20:21]
	v_add_f32_e32 v1, 1.0, v1
	v_rcp_f32_e32 v9, v1
	v_mul_f32_e32 v1, v4, v5
	v_pk_mul_f32 v[4:5], v[8:9], v[12:13]
	s_nop 0
	v_mul_f32_e32 v5, v4, v5
	v_cvt_pk_bf16_f32 v4, v2, v15
	v_cvt_pk_bf16_f32 v5, v1, v5
	s_waitcnt vmcnt(6)
	v_mov_b32_e32 v8, v152
	v_mov_b32_e32 v9, v153
	v_and_b32_e32 v13, 0xffff0000, v8
	global_store_dwordx2 v[24:25], v[4:5], off offset:192
	v_lshlrev_b32_e32 v5, 16, v8
	v_mul_f32_e32 v1, 0xbfb8aa3b, v5
	v_exp_f32_e32 v1, v1
	v_mul_f32_e32 v2, 0xbfb8aa3b, v13
	v_exp_f32_e32 v2, v2
	v_mov_b32_e32 v4, v3
	v_add_f32_e32 v1, 1.0, v1
	v_rcp_f32_e32 v1, v1
	v_add_f32_e32 v2, 1.0, v2
	v_rcp_f32_e32 v15, v2
	v_lshlrev_b32_e32 v17, 16, v9
	v_pk_mul_f32 v[0:1], v[0:1], v[4:5]
	v_and_b32_e32 v9, 0xffff0000, v9
	v_mul_f32_e32 v2, v0, v1
	v_pk_mul_f32 v[0:1], v[14:15], v[12:13]
	v_mul_f32_e32 v4, 0xbfb8aa3b, v17
	v_exp_f32_e32 v4, v4
	v_mul_f32_e32 v5, v0, v1
	v_mul_f32_e32 v0, 0xbfb8aa3b, v9
	v_exp_f32_e32 v0, v0
	v_add_f32_e32 v1, 1.0, v4
	v_rcp_f32_e32 v11, v1
	v_mov_b32_e32 v8, v3
	v_add_f32_e32 v0, 1.0, v0
	v_rcp_f32_e32 v7, v0
	v_pk_mul_f32 v[0:1], v[10:11], v[16:17]
	s_nop 0
	v_mul_f32_e32 v4, v0, v1
	v_pk_mul_f32 v[0:1], v[6:7], v[8:9]
	s_nop 0
	v_mul_f32_e32 v1, v0, v1
	v_cvt_pk_bf16_f32 v0, v2, v5
	v_cvt_pk_bf16_f32 v1, v4, v1
	global_store_dwordx2 v[24:25], v[0:1], off offset:224
	s_barrier
; #define LAS __attribute__((address_space(3)))
; #define MFMA16(a, b, c) __builtin_amdgcn_mfma_f32_16x16x32_bf16((a), (b), (c), 0, 0, 0)
; DI void na_block_item(const Params& p, int l, int b, int h, int rp, LAS unsigned char* lds) {
;     ...
;     constexpr int KROW = 272, KTILE = 64 * KROW, VROW = 144, VTILE = 128 * VROW;
;     const int gr = 2 * rp + (wid >> 2), jq = wid & 3;
;     const int gc = jq * 16 + r16, r0w = min(max(gr - 4, 0), 24), band = min(max(jq * 16 - 8, 0), 32), cs = min(max(gc - 8, 0), 48);
;     const int r0a = min(max(2 * rp - 4, 0), 24), r0b = min(max(2 * rp - 3, 0), 24), nloc = r0b + 8 - r0a, ntl = nloc + 4;
;     const size_t rowb = (size_t)b * RB, rowq = rowb + CL + gr * 64 + gc;
;     const float sl2 = 0.08838834764831845f * 1.4426950408889634f;
;     const float* rpb = p.in[11] + (size_t)(l * 6 + h) * 15 * 31;
;     bf16x8 qf[4];
; #pragma unroll
;     for (int ks = 0; ks < 4; ++ks) qf[ks] = *(const bf16x8*)(P + rowq * INP + C_NAQ + h * 128 + ks * 32 + q4 * 8);
;     f32x4 oacc[8];
; #pragma unroll
;     for (int d = 0; d < 8; ++d) oacc[d] = (f32x4){0.f, 0.f, 0.f, 0.f};
;     float mrun = -1e30f, lsum = 0.f;
;     const bf16_t* kg = P + rowb * INP + C_NAK + h * 128;
;     const bf16_t* vg = (const bf16_t*)(ws + WS_VTNA) + ((size_t)b * 768 + h * 128) * RB;
;     u32x4 kstA[2], vstA[2], kstB[2], vstB[2];
;     ...
;             float bias8[8];
;             if (local) {
;                 const LAS float* rp_ = s_rpb + (kr - gr + 7) * 31;
; #pragma unroll
;                 for (int e = 0; e < 8; ++e) { const int kcol = band + (e >> 2) * 16 + q4 * 4 + (e & 3); bias8[e] = rp_[min(max(kcol - gc + 15, 0), 30)]; }
;             }
;             f32x4 s[2];
; #pragma unroll
;             for (int hf = 0; hf < 2; ++hf) {
;                 s[hf] = (f32x4){0.f, 0.f, 0.f, 0.f};
; #pragma unroll
;                 for (int ks = 0; ks < 4; ++ks) s[hf] = MFMA16(*(const LAS bf16x8*)(kb_ + hf * 16 * KROW + ks * 64), qf[ks], s[hf]);
;             }
;             if (local) {
; #pragma unroll
;                 for (int hf = 0; hf < 2; ++hf)
; #pragma unroll
;                     for (int j = 0; j < 4; ++j) {
;                         const int kcol = band + hf * 16 + q4 * 4 + j; const bool inw = kcol >= cs && kcol < cs + 16;
;                         s[hf][j] = inw ? s[hf][j] * sl2 + bias8[hf * 4 + j] * 1.4426950408889634f : -1e30f;
;                     }
	s_and_saveexec_b64 s[0:1], s[24:25]
	s_cbranch_execz .LBB0_1179
	s_mov_b64 s[18:19], exec
	v_mbcnt_lo_u32_b32 v0, s18, 0
	v_mbcnt_hi_u32_b32 v0, s19, v0
	v_cmp_eq_u32_e32 vcc, 0, v0
	s_and_saveexec_b64 s[16:17], vcc
	s_cbranch_execz .LBB0_1178
	s_bcnt1_i32_b64 s18, s[18:19]
	v_mov_b32_e32 v1, s18
	global_atomic_add v1, v69, v1, s[42:43] sc0
	s_branch .LBB0_1178
.LBB0_1183:
	s_cmpk_gt_u32 s28, 0x387
	s_cbranch_scc1 .LBB0_1234
	s_mov_b32 s29, s28
	s_mov_b32 s22, 0x3e0293ee
	s_mov_b32 s23, 0x3fb8aa3b
	v_and_b32_e32 v196, 15, v202
	v_bfe_u32 v197, v202, 4, 2
	v_lshrrev_b32_e32 v198, 6, v202
	s_nop 0
	v_readfirstlane_b32 s74, v198
	v_mov_b32_e32 v199, v202
	v_lshrrev_b32_e32 v200, 4, v199
	v_and_b32_e32 v201, 15, v199
	v_lshlrev_b32_e32 v201, 4, v201
	v_mul_u32_u24_e32 v230, 0x3000, v200
	v_add_u32_e32 v230, v230, v201
	v_mul_u32_u24_e32 v234, 0x110, v200
	v_add_u32_e32 v234, v234, v201
	v_lshrrev_b32_e32 v200, 3, v199
	v_and_b32_e32 v201, 7, v199
	v_lshlrev_b32_e32 v201, 4, v201
	v_mul_u32_u24_e32 v232, 0x1200, v200
	v_add_u32_e32 v232, v232, v201
	v_mul_u32_u24_e32 v236, 0x90, v200
	v_add_u32_e32 v236, v236, v201
	v_add_u32_e32 v236, 0xcc00, v236
	v_add_u32_e32 v199, 0x200, v202
	v_lshrrev_b32_e32 v200, 4, v199
	v_and_b32_e32 v201, 15, v199
	v_lshlrev_b32_e32 v201, 4, v201
	v_mul_u32_u24_e32 v231, 0x3000, v200
	v_add_u32_e32 v231, v231, v201
	v_mul_u32_u24_e32 v235, 0x110, v200
	v_add_u32_e32 v235, v235, v201
	v_lshrrev_b32_e32 v200, 3, v199
	v_and_b32_e32 v201, 7, v199
	v_lshlrev_b32_e32 v201, 4, v201
	v_mul_u32_u24_e32 v233, 0x1200, v200
	v_add_u32_e32 v233, v233, v201
	v_mul_u32_u24_e32 v237, 0x90, v200
	v_add_u32_e32 v237, v237, v201
	v_add_u32_e32 v237, 0xcc00, v237
	v_mul_u32_u24_e32 v199, 0x110, v196
	v_lshl_add_u32 v238, v197, 4, v199
	v_mul_u32_u24_e32 v199, 0x90, v196
	v_lshl_add_u32 v199, v197, 3, v199
	v_add_u32_e32 v239, 0xcc00, v199
	v_mul_u32_u24_e32 v199, 0x3000, v196
	v_lshl_add_u32 v251, v197, 4, v199
	v_lshlrev_b32_e32 v199, 12, v196
	v_lshl_add_u32 v246, v197, 3, v199
	s_and_b32 s73, s74, 3
	s_lshl_b32 s73, s73, 4
	s_sub_i32 s56, s73, 8
	s_max_i32 s56, s56, 0
	s_min_i32 s56, s56, 32
	v_add_u32_e32 v220, s73, v196
	v_subrev_u32_e32 v221, 8, v220
	v_max_i32_e32 v221, 0, v221
	v_min_i32_e32 v221, 48, v221
	v_add_u32_e32 v222, 16, v221
	v_lshlrev_b32_e32 v223, 2, v197
	v_mov_b32_e32 v224, 0xf149f2ca
	v_mov_b32_e32 v225, 0x7f7fffff
	s_add_u32 s57, s56, 0
	v_add_u32_e32 v199, s57, v223
	v_sub_u32_e32 v200, v199, v220
	v_add_u32_e32 v200, 15, v200
	v_max_i32_e32 v200, 0, v200
	v_min_i32_e32 v200, 30, v200
	v_lshlrev_b32_e32 v200, 2, v200
	v_add_u32_e32 v132, 0x1a400, v200
	v_cmp_ge_i32_e32 vcc, v199, v221
	v_cmp_lt_i32_e64 s[0:1], v199, v222
	s_and_b64 vcc, vcc, s[0:1]
	v_cndmask_b32_e32 v140, v224, v225, vcc
	s_add_u32 s57, s56, 1
	v_add_u32_e32 v199, s57, v223
	v_sub_u32_e32 v200, v199, v220
	v_add_u32_e32 v200, 15, v200
	v_max_i32_e32 v200, 0, v200
	v_min_i32_e32 v200, 30, v200
	v_lshlrev_b32_e32 v200, 2, v200
	v_add_u32_e32 v133, 0x1a400, v200
	v_cmp_ge_i32_e32 vcc, v199, v221
	v_cmp_lt_i32_e64 s[0:1], v199, v222
	s_and_b64 vcc, vcc, s[0:1]
	v_cndmask_b32_e32 v141, v224, v225, vcc
	s_add_u32 s57, s56, 2
	v_add_u32_e32 v199, s57, v223
	v_sub_u32_e32 v200, v199, v220
	v_add_u32_e32 v200, 15, v200
	v_max_i32_e32 v200, 0, v200
	v_min_i32_e32 v200, 30, v200
	v_lshlrev_b32_e32 v200, 2, v200
	v_add_u32_e32 v134, 0x1a400, v200
	v_cmp_ge_i32_e32 vcc, v199, v221
	v_cmp_lt_i32_e64 s[0:1], v199, v222
	s_and_b64 vcc, vcc, s[0:1]
	v_cndmask_b32_e32 v142, v224, v225, vcc
	s_add_u32 s57, s56, 3
	v_add_u32_e32 v199, s57, v223
	v_sub_u32_e32 v200, v199, v220
	v_add_u32_e32 v200, 15, v200
	v_max_i32_e32 v200, 0, v200
	v_min_i32_e32 v200, 30, v200
	v_lshlrev_b32_e32 v200, 2, v200
	v_add_u32_e32 v135, 0x1a400, v200
	v_cmp_ge_i32_e32 vcc, v199, v221
	v_cmp_lt_i32_e64 s[0:1], v199, v222
	s_and_b64 vcc, vcc, s[0:1]
	v_cndmask_b32_e32 v143, v224, v225, vcc
	s_add_u32 s57, s56, 16
	v_add_u32_e32 v199, s57, v223
	v_sub_u32_e32 v200, v199, v220
	v_add_u32_e32 v200, 15, v200
	v_max_i32_e32 v200, 0, v200
	v_min_i32_e32 v200, 30, v200
	v_lshlrev_b32_e32 v200, 2, v200
	v_add_u32_e32 v136, 0x1a400, v200
	v_cmp_ge_i32_e32 vcc, v199, v221
	v_cmp_lt_i32_e64 s[0:1], v199, v222
	s_and_b64 vcc, vcc, s[0:1]
	v_cndmask_b32_e32 v144, v224, v225, vcc
	s_add_u32 s57, s56, 17
	v_add_u32_e32 v199, s57, v223
	v_sub_u32_e32 v200, v199, v220
	v_add_u32_e32 v200, 15, v200
	v_max_i32_e32 v200, 0, v200
	v_min_i32_e32 v200, 30, v200
	v_lshlrev_b32_e32 v200, 2, v200
	v_add_u32_e32 v137, 0x1a400, v200
	v_cmp_ge_i32_e32 vcc, v199, v221
	v_cmp_lt_i32_e64 s[0:1], v199, v222
	s_and_b64 vcc, vcc, s[0:1]
	v_cndmask_b32_e32 v145, v224, v225, vcc
	s_add_u32 s57, s56, 18
	v_add_u32_e32 v199, s57, v223
	v_sub_u32_e32 v200, v199, v220
	v_add_u32_e32 v200, 15, v200
	v_max_i32_e32 v200, 0, v200
	v_min_i32_e32 v200, 30, v200
	v_lshlrev_b32_e32 v200, 2, v200
	v_add_u32_e32 v138, 0x1a400, v200
	v_cmp_ge_i32_e32 vcc, v199, v221
	v_cmp_lt_i32_e64 s[0:1], v199, v222
	s_and_b64 vcc, vcc, s[0:1]
	v_cndmask_b32_e32 v146, v224, v225, vcc
	s_add_u32 s57, s56, 19
	v_add_u32_e32 v199, s57, v223
	v_sub_u32_e32 v200, v199, v220
	v_add_u32_e32 v200, 15, v200
	v_max_i32_e32 v200, 0, v200
	v_min_i32_e32 v200, 30, v200
	v_lshlrev_b32_e32 v200, 2, v200
	v_add_u32_e32 v139, 0x1a400, v200
	v_cmp_ge_i32_e32 vcc, v199, v221
	v_cmp_lt_i32_e64 s[0:1], v199, v222
	s_and_b64 vcc, vcc, s[0:1]
	v_cndmask_b32_e32 v147, v224, v225, vcc
	v_readlane_b32 s10, v255, 62
	v_readlane_b32 s11, v255, 63
	s_nop 4
	s_load_dwordx2 s[8:9], s[10:11], 0x58
	s_waitcnt lgkmcnt(0)
	v_writelane_b32 v254, s8, 0
	v_writelane_b32 v254, s9, 1
	v_writelane_b32 v254, s74, 2
; #define LAS __attribute__((address_space(3)))
; #define NA_LOAD(t, ks_, vs_) do { const int tb_ = NA_TB(t); \
;         _Pragma("unroll") for (int i = 0; i < 2; ++i) { const int cid = tid + i * 512; \
;             ks_[i] = *(const u32x4*)(kg + (size_t)(tb_ + (cid >> 4)) * INP + (cid & 15) * 8); \
;             vs_[i] = *(const u32x4*)(vg + (size_t)(cid >> 3) * RB + tb_ + (cid & 7) * 8); } } while (0)
; #define NA_STORE(buf, ks_, vs_) do { \
;         _Pragma("unroll") for (int i = 0; i < 2; ++i) { const int cid = tid + i * 512; \
;             *(LAS u32x4*)(lds + (buf) * KTILE + (cid >> 4) * KROW + (cid & 15) * 16) = ks_[i]; \
;             *(LAS u32x4*)(lds + 3 * KTILE + (buf) * VTILE + (cid >> 3) * VROW + (cid & 7) * 16) = vs_[i]; } } while (0)
; DI void na_block_item(const Params& p, int l, int b, int h, int rp, LAS unsigned char* lds) {
;     ...
;     const int gr = 2 * rp + (wid >> 2), jq = wid & 3;
;     const int gc = jq * 16 + r16, r0w = min(max(gr - 4, 0), 24), band = min(max(jq * 16 - 8, 0), 32), cs = min(max(gc - 8, 0), 48);
;     const int r0a = min(max(2 * rp - 4, 0), 24), r0b = min(max(2 * rp - 3, 0), 24), nloc = r0b + 8 - r0a, ntl = nloc + 4;
;     const size_t rowb = (size_t)b * RB, rowq = rowb + CL + gr * 64 + gc;
;     const float sl2 = 0.08838834764831845f * 1.4426950408889634f;
;     const float* rpb = p.in[11] + (size_t)(l * 6 + h) * 15 * 31;
;     bf16x8 qf[4];
; #pragma unroll
;     for (int ks = 0; ks < 4; ++ks) qf[ks] = *(const bf16x8*)(P + rowq * INP + C_NAQ + h * 128 + ks * 32 + q4 * 8);
;     f32x4 oacc[8];
; #pragma unroll
;     for (int d = 0; d < 8; ++d) oacc[d] = (f32x4){0.f, 0.f, 0.f, 0.f};
;     float mrun = -1e30f, lsum = 0.f;
;     const bf16_t* kg = P + rowb * INP + C_NAK + h * 128;
;     const bf16_t* vg = (const bf16_t*)(ws + WS_VTNA) + ((size_t)b * 768 + h * 128) * RB;
;     u32x4 kstA[2], vstA[2], kstB[2], vstB[2];
;     ...
;     LAS float* s_rpb = (LAS float*)(lds + 3 * KTILE + 3 * VTILE);
;     if (tid < 465) s_rpb[tid] = rpb[tid];
;     NA_LOAD(0, kstA, vstA); NA_LOAD(1, kstB, vstB);
;     NA_STORE(0, kstA, vstA);
;     NA_LOAD(2, kstA, vstA);
;     __syncthreads();
na0_item:
	s_sub_u32 s57, s29, 0x208
	s_and_b32 s71, s57, 15
	s_lshr_b32 s57, s57, 4
	s_mul_i32 s73, s57, 43
	s_lshr_b32 s73, s73, 8
	s_mul_i32 s63, s73, 6
	s_sub_u32 s72, s57, s63
	s_lshl_b32 s57, s71, 1
	s_sub_i32 s36, s57, 4
	s_max_i32 s36, s36, 0
	s_min_i32 s36, s36, 24
	s_sub_i32 s63, s57, 3
	s_max_i32 s63, s63, 0
	s_min_i32 s63, s63, 24
	s_sub_u32 s30, s63, s36
	s_add_u32 s30, s30, 8
	s_add_u32 s31, s30, 4
	v_readlane_b32 s74, v254, 2
	s_lshr_b32 s63, s74, 2
	s_add_u32 s37, s57, s63
	s_sub_i32 s54, s37, 4
	s_max_i32 s54, s54, 0
	s_min_i32 s54, s54, 24
	s_mul_i32 s68, s73, 0x900
	s_mul_i32 s57, s68, 0x3000
	s_lshl_b32 s63, s72, 8
	s_add_u32 s57, s57, s63
	s_add_u32 s57, s57, 0x113a0600
	s_add_u32 s2, s50, s57
	s_addc_u32 s3, s51, 0
	s_mul_i32 s57, s73, 0x300
	s_lshl_b32 s69, s72, 7
	s_add_u32 s57, s57, s69
	s_mul_i32 s57, s57, 0x1200
	s_add_u32 s57, s57, 0x17fa0000
	s_add_u32 s4, s50, s57
	s_addc_u32 s5, s51, 0
	s_and_b32 s69, s74, 3
	s_lshl_b32 s69, s69, 4
	s_lshl_b32 s70, s37, 6
	s_add_u32 s69, s69, s70
	s_add_u32 s69, s69, s68
	s_addk_i32 s69, 0x100
	s_mul_i32 s57, s69, 0x3000
	s_add_u32 s57, s57, s63
	s_add_u32 s57, s57, 0x113a0000
	s_add_u32 s6, s50, s57
	s_addc_u32 s7, s51, 0
	global_load_dwordx4 v[0:3], v251, s[6:7] offset:0
	global_load_dwordx4 v[4:7], v251, s[6:7] offset:64
	global_load_dwordx4 v[8:11], v251, s[6:7] offset:128
	global_load_dwordx4 v[12:15], v251, s[6:7] offset:192
	s_lshl_b32 s57, s69, 12
	s_add_u32 s57, s57, s63
	s_add_u32 s57, s57, 0x1d9a0000
	s_add_u32 s10, s50, s57
	s_addc_u32 s11, s51, 0
	v_readlane_b32 s6, v254, 0
	v_readlane_b32 s7, v254, 1
	s_mul_i32 s57, s72, 0x744
	s_add_u32 s57, s57, 0x0
	s_nop 2
	s_add_u32 s6, s6, s57
	s_addc_u32 s7, s7, 0
	v_lshlrev_b32_e32 v196, 2, v202
	v_cmp_gt_u32_e32 vcc, 0x1d1, v202
	s_and_saveexec_b64 s[0:1], vcc
	global_load_dword v197, v196, s[6:7]
	s_or_b64 exec, exec, s[0:1]
	s_mov_b32 s70, 0
	s_add_u32 s57, s36, s70
	s_lshl_b32 s57, s57, 6
	s_addk_i32 s57, 0x100
	s_sub_u32 s63, s70, s30
	s_lshl_b32 s63, s63, 6
	s_cmp_lt_u32 s70, s30
	s_cselect_b32 s57, s57, s63
	s_mul_i32 s63, s57, 0x3000
	s_add_u32 s6, s2, s63
	s_addc_u32 s7, s3, 0
	s_lshl_b32 s63, s57, 1
	s_add_u32 s8, s4, s63
	s_addc_u32 s9, s5, 0
	global_load_dwordx4 v[148:151], v230, s[6:7]
	global_load_dwordx4 v[152:155], v231, s[6:7]
	global_load_dwordx4 v[156:159], v232, s[8:9]
	global_load_dwordx4 v[160:163], v233, s[8:9]
	s_mov_b32 s70, 1
	s_add_u32 s57, s36, s70
	s_lshl_b32 s57, s57, 6
	s_addk_i32 s57, 0x100
	s_sub_u32 s63, s70, s30
	s_lshl_b32 s63, s63, 6
	s_cmp_lt_u32 s70, s30
	s_cselect_b32 s57, s57, s63
	s_mul_i32 s63, s57, 0x3000
	s_add_u32 s6, s2, s63
	s_addc_u32 s7, s3, 0
	s_lshl_b32 s63, s57, 1
	s_add_u32 s8, s4, s63
	s_addc_u32 s9, s5, 0
	global_load_dwordx4 v[164:167], v230, s[6:7]
	global_load_dwordx4 v[168:171], v231, s[6:7]
	global_load_dwordx4 v[172:175], v232, s[8:9]
	global_load_dwordx4 v[176:179], v233, s[8:9]
	s_mov_b32 s70, 2
	s_add_u32 s57, s36, s70
	s_lshl_b32 s57, s57, 6
	s_addk_i32 s57, 0x100
	s_sub_u32 s63, s70, s30
	s_lshl_b32 s63, s63, 6
	s_cmp_lt_u32 s70, s30
	s_cselect_b32 s57, s57, s63
	s_mul_i32 s63, s57, 0x3000
	s_add_u32 s6, s2, s63
	s_addc_u32 s7, s3, 0
	s_lshl_b32 s63, s57, 1
	s_add_u32 s8, s4, s63
	s_addc_u32 s9, s5, 0
	global_load_dwordx4 v[180:183], v230, s[6:7]
	global_load_dwordx4 v[184:187], v231, s[6:7]
	global_load_dwordx4 v[188:191], v232, s[8:9]
	global_load_dwordx4 v[192:195], v233, s[8:9]
	s_mov_b32 s70, 3
	s_add_u32 s57, s36, s70
	s_lshl_b32 s57, s57, 6
	s_addk_i32 s57, 0x100
	s_sub_u32 s63, s70, s30
	s_lshl_b32 s63, s63, 6
	s_cmp_lt_u32 s70, s30
	s_cselect_b32 s57, s57, s63
	s_mul_i32 s63, s57, 0x3000
	s_add_u32 s6, s2, s63
	s_addc_u32 s7, s3, 0
	s_lshl_b32 s63, s57, 1
	s_add_u32 s8, s4, s63
	s_addc_u32 s9, s5, 0
	global_load_dwordx4 v[204:207], v230, s[6:7]
	global_load_dwordx4 v[208:211], v231, s[6:7]
	global_load_dwordx4 v[212:215], v232, s[8:9]
	global_load_dwordx4 v[216:219], v233, s[8:9]
	v_mov_b32_e32 v16, 0
	v_mov_b32_e32 v17, 0
	v_mov_b32_e32 v18, 0
	v_mov_b32_e32 v19, 0
	v_mov_b32_e32 v20, 0
	v_mov_b32_e32 v21, 0
	v_mov_b32_e32 v22, 0
	v_mov_b32_e32 v23, 0
	v_mov_b32_e32 v24, 0
	v_mov_b32_e32 v25, 0
	v_mov_b32_e32 v26, 0
	v_mov_b32_e32 v27, 0
	v_mov_b32_e32 v28, 0
	v_mov_b32_e32 v29, 0
	v_mov_b32_e32 v30, 0
	v_mov_b32_e32 v31, 0
	v_mov_b32_e32 v32, 0
	v_mov_b32_e32 v33, 0
	v_mov_b32_e32 v34, 0
	v_mov_b32_e32 v35, 0
	v_mov_b32_e32 v36, 0
	v_mov_b32_e32 v37, 0
	v_mov_b32_e32 v38, 0
	v_mov_b32_e32 v39, 0
	v_mov_b32_e32 v40, 0
	v_mov_b32_e32 v41, 0
	v_mov_b32_e32 v42, 0
	v_mov_b32_e32 v43, 0
	v_mov_b32_e32 v44, 0
	v_mov_b32_e32 v45, 0
	v_mov_b32_e32 v46, 0
	v_mov_b32_e32 v47, 0
	v_mov_b32_e32 v242, 0xf149f2ca
	v_mov_b32_e32 v243, 0
	s_waitcnt vmcnt(12)
	v_cmp_gt_u32_e32 vcc, 0x1d1, v202
	s_and_saveexec_b64 s[0:1], vcc
	v_add_u32_e32 v196, 0x1a400, v196
	ds_write_b32 v196, v197
	s_or_b64 exec, exec, s[0:1]
	ds_write_b128 v234, v[148:151]
	ds_write_b128 v235, v[152:155]
	ds_write_b128 v236, v[156:159]
	ds_write_b128 v237, v[160:163]
	s_waitcnt lgkmcnt(0)
	s_mov_b32 s70, 4
	s_add_u32 s57, s36, s70
	s_lshl_b32 s57, s57, 6
	s_addk_i32 s57, 0x100
	s_sub_u32 s63, s70, s30
	s_lshl_b32 s63, s63, 6
	s_cmp_lt_u32 s70, s30
	s_cselect_b32 s57, s57, s63
	s_mul_i32 s63, s57, 0x3000
	s_add_u32 s6, s2, s63
	s_addc_u32 s7, s3, 0
	s_lshl_b32 s63, s57, 1
	s_add_u32 s8, s4, s63
	s_addc_u32 s9, s5, 0
	global_load_dwordx4 v[148:151], v230, s[6:7]
	global_load_dwordx4 v[152:155], v231, s[6:7]
	global_load_dwordx4 v[156:159], v232, s[8:9]
	global_load_dwordx4 v[160:163], v233, s[8:9]
	s_barrier
	s_mov_b32 s27, 0

; DI void na_block_item(const Params& p, int l, int b, int h, int rp, LAS unsigned char* lds) {
;     ...
;         const int cur = t % 3;
;         const bool local = t < nloc; const int kr = r0a + t;
;         const int nch = local ? ((kr >= r0w && kr < r0w + 8) ? 1 : 0) : 2;
;         for (int ci = 0; ci < nch; ++ci) {
;             const int toff = local ? band : ci * 32;
;             const LAS unsigned char* kb_ = lds + cur * KTILE + (toff + r16) * KROW + q4 * 16;
;             const LAS unsigned char* vb_ = lds + 3 * KTILE + cur * VTILE + r16 * VROW + (toff + q4 * 4) * 2;
;             float bias8[8];
;             if (local) {
;                 const LAS float* rp_ = s_rpb + (kr - gr + 7) * 31;
; #pragma unroll
;                 for (int e = 0; e < 8; ++e) { const int kcol = band + (e >> 2) * 16 + q4 * 4 + (e & 3); bias8[e] = rp_[min(max(kcol - gc + 15, 0), 30)]; }
;             }
;             f32x4 s[2];
; #pragma unroll
;             for (int hf = 0; hf < 2; ++hf) {
;                 s[hf] = (f32x4){0.f, 0.f, 0.f, 0.f};
; #pragma unroll
;                 for (int ks = 0; ks < 4; ++ks) s[hf] = MFMA16(*(const LAS bf16x8*)(kb_ + hf * 16 * KROW + ks * 64), qf[ks], s[hf]);
;             }
;             if (local) {
; #pragma unroll
;                 for (int hf = 0; hf < 2; ++hf)
; #pragma unroll
;                     for (int j = 0; j < 4; ++j) {
;                         const int kcol = band + hf * 16 + q4 * 4 + j; const bool inw = kcol >= cs && kcol < cs + 16;
;                         s[hf][j] = inw ? s[hf][j] * sl2 + bias8[hf * 4 + j] * 1.4426950408889634f : -1e30f;
;                     }
;             } else { s[0] *= sl2; s[1] *= sl2; }
;             float mx = fmaxf(fmaxf(fmaxf(s[0][0], s[0][1]), fmaxf(s[0][2], s[0][3])), fmaxf(fmaxf(s[1][0], s[1][1]), fmaxf(s[1][2], s[1][3])));
;             mx = fmaxf(mx, __shfl_xor(mx, 16)); mx = fmaxf(mx, __shfl_xor(mx, 32));
;             const float mnew = fmaxf(mrun, mx), alpha = fast_exp2(mrun - mnew);
;             mrun = mnew;
;             float ps = 0.f;
; #pragma unroll
;             for (int hf = 0; hf < 2; ++hf)
; #pragma unroll
;                 for (int j = 0; j < 4; ++j) { const float pv = fast_exp2(s[hf][j] - mnew); s[hf][j] = pv; ps += pv; }
;             lsum = lsum * alpha + ps;
; #pragma unroll
;             for (int d = 0; d < 8; ++d) oacc[d] *= alpha;
na0_nostage:
	s_mul_hi_u32 s57, s27, 0x55555556
	s_mul_i32 s57, s57, 3
	s_sub_u32 s57, s27, s57
	s_mul_i32 s75, s57, 0x4400
	s_mul_i32 s76, s57, 0x4800
	s_cmp_lt_u32 s27, s30
	s_cbranch_scc0 na0_ctx
	s_add_u32 s68, s36, s27
	s_cmp_lt_i32 s68, s54
	s_cbranch_scc1 na0_bar
	s_add_u32 s69, s54, 8
	s_cmp_ge_i32 s68, s69
	s_cbranch_scc1 na0_bar
	s_sub_i32 s69, s68, s37
	s_add_u32 s69, s69, 7
	s_mul_i32 s69, s69, 0x7c
	s_mul_i32 s57, s56, 0x110
	s_add_u32 s57, s57, s75
	s_lshl_b32 s63, s56, 1
	s_add_u32 s63, s63, s76
	v_add_u32_e32 v240, s57, v238
	v_add_u32_e32 v241, s63, v239
	v_add_u32_e32 v222, s69, v132
	v_add_u32_e32 v223, s69, v133
	v_add_u32_e32 v224, s69, v134
	v_add_u32_e32 v225, s69, v135
	v_add_u32_e32 v226, s69, v136
	v_add_u32_e32 v227, s69, v137
	v_add_u32_e32 v228, s69, v138
	v_add_u32_e32 v229, s69, v139
	ds_read_b32 v124, v222
	ds_read_b32 v125, v223
	ds_read_b32 v126, v224
	ds_read_b32 v127, v225
	ds_read_b32 v128, v226
	ds_read_b32 v129, v227
	ds_read_b32 v130, v228
	ds_read_b32 v131, v229
	ds_read_b128 v[56:59], v240 offset:0
	ds_read_b128 v[72:75], v240 offset:4352
	ds_read_b128 v[60:63], v240 offset:64
	ds_read_b128 v[76:79], v240 offset:4416
	ds_read_b128 v[64:67], v240 offset:128
	ds_read_b128 v[80:83], v240 offset:4480
	ds_read_b128 v[68:71], v240 offset:192
	ds_read_b128 v[84:87], v240 offset:4544
	s_waitcnt lgkmcnt(7)
	v_mfma_f32_16x16x32_bf16 v[48:51], v[56:59], v[0:3], 0
	ds_read_b64 v[88:89], v241 offset:0
	ds_read_b64 v[90:91], v241 offset:32
	s_waitcnt lgkmcnt(8)
	v_mfma_f32_16x16x32_bf16 v[52:55], v[72:75], v[0:3], 0
	ds_read_b64 v[92:93], v241 offset:2304
	ds_read_b64 v[94:95], v241 offset:2336
	s_waitcnt lgkmcnt(9)
	v_mfma_f32_16x16x32_bf16 v[48:51], v[60:63], v[4:7], v[48:51]
	ds_read_b64 v[96:97], v241 offset:4608
	ds_read_b64 v[98:99], v241 offset:4640
	s_waitcnt lgkmcnt(10)
	v_mfma_f32_16x16x32_bf16 v[52:55], v[76:79], v[4:7], v[52:55]
	ds_read_b64 v[100:101], v241 offset:6912
	ds_read_b64 v[102:103], v241 offset:6944
	s_waitcnt lgkmcnt(11)
	v_mfma_f32_16x16x32_bf16 v[48:51], v[64:67], v[8:11], v[48:51]
	ds_read_b64 v[104:105], v241 offset:9216
	ds_read_b64 v[106:107], v241 offset:9248
	s_waitcnt lgkmcnt(12)
	v_mfma_f32_16x16x32_bf16 v[52:55], v[80:83], v[8:11], v[52:55]
	ds_read_b64 v[108:109], v241 offset:11520
	ds_read_b64 v[110:111], v241 offset:11552
	s_waitcnt lgkmcnt(13)
	v_mfma_f32_16x16x32_bf16 v[48:51], v[68:71], v[12:15], v[48:51]
	ds_read_b64 v[112:113], v241 offset:13824
	ds_read_b64 v[114:115], v241 offset:13856
	s_waitcnt lgkmcnt(14)
	v_mfma_f32_16x16x32_bf16 v[52:55], v[84:87], v[12:15], v[52:55]
	ds_read_b64 v[116:117], v241 offset:16128
	ds_read_b64 v[118:119], v241 offset:16160
	v_mul_f32_e32 v124, s23, v124
	v_mul_f32_e32 v125, s23, v125
	v_mul_f32_e32 v126, s23, v126
	v_mul_f32_e32 v127, s23, v127
	v_mul_f32_e32 v128, s23, v128
	v_mul_f32_e32 v129, s23, v129
	v_mul_f32_e32 v130, s23, v130
	v_mul_f32_e32 v131, s23, v131
	s_nop 1
	v_fma_f32 v48, v48, s22, v124
	v_fma_f32 v49, v49, s22, v125
	v_fma_f32 v50, v50, s22, v126
	v_fma_f32 v51, v51, s22, v127
	v_fma_f32 v52, v52, s22, v128
	v_fma_f32 v53, v53, s22, v129
	v_fma_f32 v54, v54, s22, v130
	v_fma_f32 v55, v55, s22, v131
	v_min_f32_e32 v48, v48, v140
	v_min_f32_e32 v49, v49, v141
	v_min_f32_e32 v50, v50, v142
	v_min_f32_e32 v51, v51, v143
	v_min_f32_e32 v52, v52, v144
	v_min_f32_e32 v53, v53, v145
	v_min_f32_e32 v54, v54, v146
	v_min_f32_e32 v55, v55, v147
	v_max3_f32 v196, v48, v49, v50
	v_max3_f32 v197, v51, v52, v53
	v_max3_f32 v196, v196, v54, v55
	v_max_f32_e32 v196, v196, v197
	v_mov_b32_e32 v197, v196
	s_nop 1
	v_permlane16_swap_b32_e32 v196, v197
	v_max_f32_e32 v196, v196, v197
	v_mov_b32_e32 v197, v196
	s_nop 1
	v_permlane32_swap_b32_e32 v196, v197
	v_max_f32_e32 v196, v196, v197
	v_max_f32_e32 v197, v242, v196
	v_sub_f32_e32 v196, v242, v197
	v_exp_f32_e32 v244, v196
	v_mov_b32_e32 v242, v197
	v_sub_f32_e32 v48, v48, v197
	v_sub_f32_e32 v49, v49, v197
	v_sub_f32_e32 v50, v50, v197
	v_sub_f32_e32 v51, v51, v197
	v_sub_f32_e32 v52, v52, v197
	v_sub_f32_e32 v53, v53, v197
	v_sub_f32_e32 v54, v54, v197
	v_sub_f32_e32 v55, v55, v197
	v_exp_f32_e32 v48, v48
	v_exp_f32_e32 v49, v49
	v_exp_f32_e32 v50, v50
	v_exp_f32_e32 v51, v51
	v_exp_f32_e32 v52, v52
	v_exp_f32_e32 v53, v53
	v_exp_f32_e32 v54, v54
	v_exp_f32_e32 v55, v55
	v_add_f32_e32 v196, v48, v49
	v_add_f32_e32 v196, v196, v50
	v_add_f32_e32 v196, v196, v51
	v_add_f32_e32 v196, v196, v52
	v_add_f32_e32 v196, v196, v53
	v_add_f32_e32 v196, v196, v54
	v_add_f32_e32 v196, v196, v55
	v_fma_f32 v243, v243, v244, v196
	v_cvt_pk_bf16_f32 v120, v48, v49
	v_cvt_pk_bf16_f32 v121, v50, v51
	v_cvt_pk_bf16_f32 v122, v52, v53
	v_cvt_pk_bf16_f32 v123, v54, v55
	v_pk_mul_f32 v[16:17], v[16:17], v[244:245] op_sel_hi:[1,0]
	v_pk_mul_f32 v[18:19], v[18:19], v[244:245] op_sel_hi:[1,0]
	v_pk_mul_f32 v[20:21], v[20:21], v[244:245] op_sel_hi:[1,0]
	v_pk_mul_f32 v[22:23], v[22:23], v[244:245] op_sel_hi:[1,0]
	v_pk_mul_f32 v[24:25], v[24:25], v[244:245] op_sel_hi:[1,0]
	v_pk_mul_f32 v[26:27], v[26:27], v[244:245] op_sel_hi:[1,0]
	v_pk_mul_f32 v[28:29], v[28:29], v[244:245] op_sel_hi:[1,0]
	v_pk_mul_f32 v[30:31], v[30:31], v[244:245] op_sel_hi:[1,0]
	v_pk_mul_f32 v[32:33], v[32:33], v[244:245] op_sel_hi:[1,0]
	v_pk_mul_f32 v[34:35], v[34:35], v[244:245] op_sel_hi:[1,0]
	v_pk_mul_f32 v[36:37], v[36:37], v[244:245] op_sel_hi:[1,0]
	v_pk_mul_f32 v[38:39], v[38:39], v[244:245] op_sel_hi:[1,0]
	v_pk_mul_f32 v[40:41], v[40:41], v[244:245] op_sel_hi:[1,0]
	v_pk_mul_f32 v[42:43], v[42:43], v[244:245] op_sel_hi:[1,0]
	v_pk_mul_f32 v[44:45], v[44:45], v[244:245] op_sel_hi:[1,0]
	v_pk_mul_f32 v[46:47], v[46:47], v[244:245] op_sel_hi:[1,0]
	s_waitcnt lgkmcnt(14)
	v_mfma_f32_16x16x32_bf16 v[16:19], v[88:91], v[120:123], v[16:19]
	s_waitcnt lgkmcnt(12)
	v_mfma_f32_16x16x32_bf16 v[20:23], v[92:95], v[120:123], v[20:23]
	s_waitcnt lgkmcnt(10)
	v_mfma_f32_16x16x32_bf16 v[24:27], v[96:99], v[120:123], v[24:27]
	s_waitcnt lgkmcnt(8)
	v_mfma_f32_16x16x32_bf16 v[28:31], v[100:103], v[120:123], v[28:31]
	s_waitcnt lgkmcnt(6)
	v_mfma_f32_16x16x32_bf16 v[32:35], v[104:107], v[120:123], v[32:35]
	s_waitcnt lgkmcnt(4)
	v_mfma_f32_16x16x32_bf16 v[36:39], v[108:111], v[120:123], v[36:39]
	s_waitcnt lgkmcnt(2)
	v_mfma_f32_16x16x32_bf16 v[40:43], v[112:115], v[120:123], v[40:43]
	s_waitcnt lgkmcnt(0)
	v_mfma_f32_16x16x32_bf16 v[44:47], v[116:119], v[120:123], v[44:47]
	s_branch na0_bar

; #define LAS __attribute__((address_space(3)))
; DI int otid() { int t = threadIdx.x; asm volatile("" : "+v"(t)); return t; }
; DI float ret_lg2(const Params& p, int l, int dir, int h) { return log1pf(-exp2f(p.in[12][(l * 2 + dir) * 5 + h])) * 1.4426950408889634f; }
; DI void ret_out_item(const Params& p, int l, int b, int h, int c, LAS unsigned char* lds) {
;     const int tid = otid(), lane = tid & 63, wid = tid >> 6, r16 = lane & 15, q4 = lane >> 4;
;     unsigned char* ws = p.ws;
;     const bf16_t* P = (const bf16_t*)(ws + WS_P);
;     const float lgf = ret_lg2(p, l, 0, h), lgb = ret_lg2(p, l, 1, h);
;     const size_t rowb = (size_t)b * RB; const int tok0 = c * 128, tl = wid * 16 + r16;
;     const size_t row = rowb + tok0 + tl;
;     constexpr int RS = 272, MB = 128 * RS;
.LBB0_2627:
	s_addk_i32 s0, 0xff60
	s_ashr_i32 s1, s0, 31
	s_lshr_b32 s1, s1, 28
	s_add_i32 s1, s0, s1
	s_ashr_i32 s14, s1, 4
	s_and_b32 s1, s1, -16
	s_sub_i32 s17, s0, s1
	s_mul_hi_i32 s0, s0, 0x66666667
	s_lshr_b32 s1, s0, 31
	s_ashr_i32 s16, s0, 5
	s_mul_hi_i32 s0, s14, 0x66666667
	s_add_i32 s16, s16, s1
	s_lshr_b32 s1, s0, 31
	s_ashr_i32 s0, s0, 1
	s_add_i32 s0, s0, s1
	s_mul_i32 s0, s0, 5
	s_sub_i32 s14, s14, s0
	s_ashr_i32 s15, s14, 31
	s_add_i32 s17, s17, 2
	s_lshl_b64 s[0:1], s[14:15], 2
	s_add_u32 s0, s60, s0
	v_mov_b32_e32 v16, v202
	s_addc_u32 s1, s61, s1
	global_load_dword v0, v69, s[0:1] offset:40
	global_load_dword v1, v69, s[0:1] offset:60
	v_bfe_u32 v92, v16, 4, 2
	s_waitcnt vmcnt(1)
	v_cmp_gt_f32_e32 vcc, s7, v0
	s_nop 1
	v_cndmask_b32_e32 v2, 0, v82, vcc
	s_waitcnt vmcnt(0)
	v_cmp_gt_f32_e64 s[0:1], s7, v1
	v_add_f32_e32 v0, v0, v2
	v_exp_f32_e32 v0, v0
	v_cndmask_b32_e64 v3, 0, v82, s[0:1]
	v_add_f32_e32 v1, v1, v3
	s_and_b64 s[28:29], vcc, exec
	v_exp_f32_e32 v1, v1
	s_cselect_b32 s15, 0xffffffc0, 0
	s_and_b64 s[0:1], s[0:1], exec
	v_ldexp_f32 v15, v0, s15
	s_cselect_b32 s0, 0xffffffc0, 0
	v_sub_f32_e32 v4, 1.0, v15
	v_ldexp_f32 v14, v1, s0
	v_frexp_mant_f32_e32 v7, v4
	v_cvt_f64_f32_e32 v[0:1], v4
	v_sub_f32_e32 v5, 1.0, v14
	v_add_f32_e32 v6, -1.0, v4
	v_frexp_exp_i32_f64_e32 v0, v[0:1]
	v_cmp_gt_f32_e32 vcc, s18, v7
	v_add_f32_e32 v8, -1.0, v5
	v_frexp_mant_f32_e32 v9, v5
	v_cvt_f64_f32_e32 v[2:3], v5
	v_sub_f32_e32 v10, v6, v4
	v_subbrev_co_u32_e32 v0, vcc, 0, v0, vcc
	v_sub_f32_e64 v6, -v15, v6
	v_sub_f32_e32 v1, v8, v5
	v_frexp_exp_i32_f64_e32 v2, v[2:3]
	v_add_f32_e32 v3, 1.0, v10
	v_cmp_gt_f32_e32 vcc, s18, v9
	v_sub_f32_e64 v8, -v14, v8
	v_add_f32_e32 v1, 1.0, v1
	v_subbrev_co_u32_e32 v17, vcc, 0, v2, vcc
	v_add_f32_e32 v2, v6, v3
	v_sub_u32_e32 v3, 0, v0
	v_add_f32_e32 v1, v8, v1
	v_sub_u32_e32 v6, 0, v17
	v_ldexp_f32 v4, v4, v3
	v_ldexp_f32 v20, v5, v6
	v_ldexp_f32 v21, v1, v6
	v_add_f32_e32 v1, -1.0, v4
	v_add_f32_e32 v5, 1.0, v4
	v_ldexp_f32 v2, v2, v3
	v_add_f32_e32 v3, 1.0, v1
	v_add_f32_e32 v6, -1.0, v5
	v_sub_f32_e32 v3, v4, v3
	v_sub_f32_e32 v4, v4, v6
	v_add_f32_e32 v6, v2, v3
	v_add_f32_e32 v2, v2, v4
	v_add_f32_e32 v8, v5, v2
	v_rcp_f32_e32 v9, v8
	v_add_f32_e32 v3, v1, v6
	v_sub_f32_e32 v4, v8, v5
	v_sub_f32_e32 v1, v3, v1
	v_mul_f32_e32 v11, v3, v9
	v_sub_f32_e32 v10, v2, v4
	v_mul_f32_e32 v4, v8, v11
	v_sub_f32_e32 v1, v6, v1
	v_fma_f32 v6, v11, v8, -v4
	v_fmac_f32_e32 v6, v11, v10
	v_add_f32_e32 v2, v4, v6
	v_sub_f32_e32 v5, v3, v2
	v_mov_b32_e32 v7, v2
	v_pk_add_f32 v[2:3], v[2:3], v[4:5] neg_lo:[0,1] neg_hi:[0,1]
	v_cvt_f32_i32_e32 v0, v0
	v_pk_add_f32 v[2:3], v[2:3], v[6:7] neg_lo:[0,1] neg_hi:[0,1]
	v_cmp_nlt_f32_e32 vcc, 1.0, v15
	v_add_f32_e32 v1, v1, v3
	v_add_f32_e32 v1, v2, v1
	v_add_f32_e32 v3, v5, v1
	v_mul_f32_e32 v2, v9, v3
	v_mul_f32_e32 v4, v8, v2
	v_sub_f32_e32 v5, v5, v3
	v_add_f32_e32 v12, v11, v2
	v_fma_f32 v6, v2, v8, -v4
	v_add_f32_e32 v1, v1, v5
	v_sub_f32_e32 v5, v12, v11
	v_fmac_f32_e32 v6, v2, v10
	v_sub_f32_e32 v8, v2, v5
	v_add_f32_e32 v2, v4, v6
	v_sub_f32_e32 v5, v3, v2
	v_mov_b32_e32 v7, v2
	v_pk_add_f32 v[2:3], v[2:3], v[4:5] neg_lo:[0,1] neg_hi:[0,1]
	v_add_f32_e32 v22, -1.0, v20
	v_pk_add_f32 v[2:3], v[2:3], v[6:7] neg_lo:[0,1] neg_hi:[0,1]
	v_cmp_lt_f32_e64 s[0:1], |v15|, s20
	v_add_f32_e32 v1, v1, v3
	v_add_f32_e32 v1, v2, v1
	v_add_f32_e32 v1, v5, v1
	v_mul_f32_e32 v1, v9, v1
	v_add_f32_e32 v1, v8, v1
	v_add_f32_e32 v2, v12, v1
	v_mul_f32_e32 v4, v2, v2
	v_sub_f32_e32 v5, v2, v12
	v_fmamk_f32 v6, v4, 0x3e9b6dac, v83
	v_sub_f32_e32 v5, v1, v5
	v_mul_f32_e32 v1, v2, v4
	v_fmaak_f32 v73, v4, v6, 0x3f2aaada
	v_ldexp_f32 v7, v5, 1
	v_pk_mul_f32 v[4:5], v[0:1], v[72:73]
	v_ldexp_f32 v3, v2, 1
	v_fma_f32 v2, v0, s19, -v4
	v_fmac_f32_e32 v2, 0xb102e308, v0
	v_pk_add_f32 v[0:1], v[4:5], v[2:3]
	v_mov_b32_e32 v6, v4
	v_sub_f32_e32 v10, v1, v3
	v_pk_add_f32 v[8:9], v[0:1], v[4:5] neg_lo:[0,1] neg_hi:[0,1]
	v_sub_f32_e32 v5, v5, v10
	v_add_f32_e32 v7, v7, v5
	v_pk_add_f32 v[12:13], v[0:1], v[6:7]
	v_mov_b32_e32 v3, v0
	v_mov_b32_e32 v9, v13
	v_pk_add_f32 v[18:19], v[2:3], v[8:9] neg_lo:[0,1] neg_hi:[0,1]
	v_pk_add_f32 v[2:3], v[2:3], v[8:9]
	v_mov_b32_e32 v4, v1
	v_mov_b32_e32 v11, v0
	v_pk_add_f32 v[0:1], v[2:3], v[0:1] op_sel:[1,0] op_sel_hi:[0,1] neg_lo:[0,1] neg_hi:[0,1]
	v_mov_b32_e32 v10, v7
	v_mov_b32_e32 v6, v13
	v_mov_b32_e32 v7, v3
	v_mov_b32_e32 v5, v0
	v_pk_add_f32 v[8:9], v[12:13], v[0:1] op_sel_hi:[1,0] neg_lo:[0,1] neg_hi:[0,1]
	v_pk_add_f32 v[0:1], v[6:7], v[4:5] neg_lo:[0,1] neg_hi:[0,1]
	v_mov_b32_e32 v8, v18
	v_pk_add_f32 v[0:1], v[10:11], v[0:1] neg_lo:[0,1] neg_hi:[0,1]
	v_mov_b32_e32 v19, v3
	v_pk_add_f32 v[4:5], v[8:9], v[0:1]
	s_lshl_b32 s28, s17, 7
	v_pk_add_f32 v[6:7], v[4:5], v[4:5] op_sel:[0,1] op_sel_hi:[1,0]
	s_ashr_i32 s29, s28, 31
	v_pk_add_f32 v[2:3], v[2:3], v[6:7] op_sel:[1,0] op_sel_hi:[0,1]
	v_mov_b32_e32 v5, v2
	v_mov_b32_e32 v1, v6
	v_pk_add_f32 v[6:7], v[4:5], v[18:19] neg_lo:[0,1] neg_hi:[0,1]
	s_mul_i32 s15, s16, 5
	v_sub_f32_e32 v3, v4, v6
	v_pk_add_f32 v[0:1], v[0:1], v[6:7] neg_lo:[0,1] neg_hi:[0,1]
	v_sub_f32_e32 v3, v18, v3
	v_add_f32_e32 v0, v0, v3
	v_add_f32_e32 v0, v0, v1
	v_add_f32_e32 v1, 1.0, v20
	v_add_f32_e32 v0, v2, v0
	v_add_f32_e32 v2, -1.0, v1
	v_sub_f32_e32 v2, v20, v2
	v_cndmask_b32_e32 v0, v84, v0, vcc
	v_cmp_neq_f32_e32 vcc, 1.0, v15
	v_add_f32_e32 v2, v21, v2
	v_add_f32_e32 v8, v1, v2
	v_cndmask_b32_e32 v0, v85, v0, vcc
	v_cndmask_b32_e64 v15, v0, -v15, s[0:1]
	v_add_f32_e32 v0, 1.0, v22
	v_rcp_f32_e32 v10, v8
	v_sub_f32_e32 v0, v20, v0
	v_add_f32_e32 v0, v21, v0
	v_sub_f32_e32 v1, v8, v1
	v_sub_f32_e32 v9, v2, v1
; DI float ret_lg2(const Params& p, int l, int dir, int h) { return log1pf(-exp2f(p.in[12][(l * 2 + dir) * 5 + h])) * 1.4426950408889634f; }
; DI void ret_out_item(const Params& p, int l, int b, int h, int c, LAS unsigned char* lds) {
;     ...
;     constexpr int RS = 272, MB = 128 * RS;
;     {
;         const bf16_t* Sf = (const bf16_t*)(ws + WS_S) + ((size_t)((b * 5 + h) * 2 + 0) * 18 + c) * 16384;
;         const bf16_t* Sb = (const bf16_t*)(ws + WS_S) + ((size_t)((b * 5 + h) * 2 + 1) * 18 + c) * 16384;
;         const bf16_t* Kc = P + (rowb + tok0) * INP + C_RK + h * 128;
;         const bf16_t* Vc = (const bf16_t*)(ws + WS_VTR) + ((size_t)b * 640 + h * 128) * RB + tok0;
;         u32x4 t0[4], t1[4], t2[4], t3[4];
; #pragma unroll
;         for (int i = 0; i < 4; ++i) {
;             const int cid = tid + i * 512, rr = cid >> 4, cc = cid & 15;
;             t0[i] = *(const u32x4*)(Sf + rr * 128 + cc * 8); t1[i] = *(const u32x4*)(Sb + rr * 128 + cc * 8);
;             t2[i] = *(const u32x4*)(Kc + (size_t)rr * INP + cc * 8); t3[i] = *(const u32x4*)(Vc + (size_t)rr * RB + cc * 8);
;         }
	v_add_f32_e32 v1, v22, v0
	v_sub_f32_e32 v2, v1, v22
	v_mul_f32_e32 v12, v1, v10
	v_sub_f32_e32 v11, v0, v2
	v_mul_f32_e32 v2, v8, v12
	v_fma_f32 v4, v12, v8, -v2
	v_fmac_f32_e32 v4, v12, v9
	v_add_f32_e32 v0, v2, v4
	v_sub_f32_e32 v3, v1, v0
	v_pk_add_f32 v[6:7], v[0:1], v[2:3] neg_lo:[0,1] neg_hi:[0,1]
	v_mov_b32_e32 v5, v0
	v_pk_add_f32 v[0:1], v[6:7], v[4:5] neg_lo:[0,1] neg_hi:[0,1]
	s_mul_i32 s0, s16, 0x900
	v_add_f32_e32 v1, v11, v1
	v_add_f32_e32 v0, v0, v1
	v_add_f32_e32 v1, v3, v0
	v_mul_f32_e32 v11, v10, v1
	v_mul_f32_e32 v2, v8, v11
	v_fma_f32 v4, v11, v8, -v2
	v_fmac_f32_e32 v4, v11, v9
	v_sub_f32_e32 v3, v3, v1
	v_add_f32_e32 v8, v0, v3
	v_add_f32_e32 v0, v2, v4
	v_sub_f32_e32 v3, v1, v0
	v_pk_add_f32 v[6:7], v[0:1], v[2:3] neg_lo:[0,1] neg_hi:[0,1]
	v_mov_b32_e32 v5, v0
	v_pk_add_f32 v[0:1], v[6:7], v[4:5] neg_lo:[0,1] neg_hi:[0,1]
	s_mul_hi_i32 s1, s16, 0x900
	v_add_f32_e32 v1, v8, v1
	v_add_f32_e32 v0, v0, v1
	v_add_f32_e32 v1, v12, v11
	s_add_u32 s0, s0, s28
	v_add_f32_e32 v0, v3, v0
	v_sub_f32_e32 v2, v1, v12
	s_addc_u32 s1, s1, s29
	s_add_i32 s15, s15, s14
	v_mul_f32_e32 v0, v10, v0
	v_sub_f32_e32 v2, v11, v2
	s_lshl_b32 s57, s15, 1
	s_mul_i32 s15, s15, 36
	s_ashr_i32 s63, s17, 31
	v_add_f32_e32 v2, v2, v0
	s_mul_hi_i32 s43, s57, 18
	s_add_u32 s42, s15, s17
	v_add_f32_e32 v4, v1, v2
	s_addc_u32 s43, s43, s63
	v_mul_f32_e32 v5, v4, v4
	s_lshl_b64 s[42:43], s[42:43], 15
	v_fmamk_f32 v0, v5, 0x3e9b6dac, v83
	s_add_u32 s42, s92, s42
	v_fmaak_f32 v73, v5, v0, 0x3f2aaada
	v_cvt_f32_i32_e32 v0, v17
	s_addc_u32 s43, s93, s43
	s_or_b32 s15, s57, 1
	v_sub_f32_e32 v1, v4, v1
	s_mul_hi_i32 s57, s15, 18
	s_mul_i32 s15, s15, 18
	v_sub_f32_e32 v1, v2, v1
	s_add_u32 s62, s15, s17
	v_ldexp_f32 v8, v1, 1
	v_mul_f32_e32 v1, v4, v5
	s_addc_u32 s63, s57, s63
	v_pk_mul_f32 v[6:7], v[0:1], v[72:73]
	s_lshl_b64 s[62:63], s[62:63], 15
	v_fma_f32 v2, v0, s19, -v6
	s_add_u32 s62, s92, s62
	s_mul_i32 s15, s1, 0x3000
	s_mul_hi_u32 s17, s0, 0x3000
	v_ldexp_f32 v3, v4, 1
	v_fmac_f32_e32 v2, 0xb102e308, v0
	s_addc_u32 s63, s93, s63
	s_add_i32 s17, s17, s15
	s_mul_i32 s15, s0, 0x3000
	v_pk_add_f32 v[4:5], v[6:7], v[2:3]
	s_add_u32 s57, s2, s15
	v_sub_f32_e32 v0, v5, v3
	s_addc_u32 s17, s3, s17
	s_lshl_b32 s68, s14, 7
	v_sub_f32_e32 v0, v7, v0
	s_ashr_i32 s69, s68, 31
	v_add_f32_e32 v9, v8, v0
	v_mov_b32_e32 v8, v6
	s_lshl_b64 s[14:15], s[68:69], 1
	v_pk_add_f32 v[0:1], v[4:5], v[6:7] neg_lo:[0,1] neg_hi:[0,1]
	v_pk_add_f32 v[66:67], v[4:5], v[8:9]
	s_add_u32 s70, s57, s14
	v_mov_b32_e32 v1, v67
	v_mov_b32_e32 v3, v4
	s_addc_u32 s71, s17, s15
	s_mul_hi_i32 s17, s16, 0x280
	s_mulk_i32 s16, 0x280
	v_pk_add_f32 v[10:11], v[2:3], v[0:1]
	s_add_u32 s16, s16, s68
	v_pk_add_f32 v[6:7], v[2:3], v[0:1] neg_lo:[0,1] neg_hi:[0,1]
	v_pk_add_f32 v[0:1], v[10:11], v[4:5] op_sel:[1,0] op_sel_hi:[0,1] neg_lo:[0,1] neg_hi:[0,1]
	s_addc_u32 s17, s17, s69
	v_pk_add_f32 v[12:13], v[66:67], v[0:1] op_sel_hi:[1,0] neg_lo:[0,1] neg_hi:[0,1]
	s_mulk_i32 s17, 0x1200
	s_mul_hi_u32 s57, s16, 0x1200
	v_lshlrev_b32_e32 v1, 4, v16
	s_add_i32 s57, s57, s17
	s_mulk_i32 s16, 0x1200
	v_and_b32_e32 v68, 0xf0, v1
	s_add_u32 s68, s87, s16
	v_lshl_add_u64 v[18:19], s[70:71], 0, v[68:69]
	v_ashrrev_i32_e32 v17, 4, v16
	s_addc_u32 s57, s91, s57
	s_lshl_b64 s[16:17], s[28:29], 1
	v_lshl_add_u64 v[76:77], v[18:19], 0, s[4:5]
	v_lshlrev_b32_e32 v18, 7, v17
	s_add_u32 s16, s68, s16
	v_ashrrev_i32_e32 v19, 31, v18
	v_add_u32_e32 v1, 0x200, v16
	s_addc_u32 s17, s57, s17
	v_lshl_add_u64 v[2:3], s[42:43], 0, v[68:69]
	v_lshl_add_u64 v[74:75], s[62:63], 0, v[68:69]
	v_lshlrev_b64 v[18:19], 1, v[18:19]
	v_ashrrev_i32_e32 v73, 4, v1
	v_lshl_add_u64 v[78:79], s[16:17], 0, v[68:69]
	v_lshl_add_u64 v[20:21], v[2:3], 0, v[18:19]
	v_lshl_add_u64 v[22:23], v[74:75], 0, v[18:19]
	v_lshlrev_b32_e32 v34, 7, v73
	global_load_dwordx4 v[18:21], v[20:21], off
	s_nop 0
	global_load_dwordx4 v[22:25], v[22:23], off
	v_mad_i64_i32 v[26:27], s[16:17], v17, s21, v[76:77]
	v_mad_i64_i32 v[30:31], s[16:17], v17, s22, v[78:79]
	v_ashrrev_i32_e32 v35, 31, v34
	v_add_u32_e32 v1, 0x400, v16
	global_load_dwordx4 v[26:29], v[26:27], off
	s_nop 0
	global_load_dwordx4 v[30:33], v[30:31], off
	v_lshlrev_b64 v[34:35], 1, v[34:35]
	v_ashrrev_i32_e32 v93, 4, v1
	v_lshl_add_u64 v[36:37], v[2:3], 0, v[34:35]
	v_lshl_add_u64 v[38:39], v[74:75], 0, v[34:35]
	v_lshlrev_b32_e32 v50, 7, v93
	global_load_dwordx4 v[34:37], v[36:37], off
	s_nop 0
	global_load_dwordx4 v[38:41], v[38:39], off
	v_mad_i64_i32 v[42:43], s[16:17], v73, s21, v[76:77]
	v_mad_i64_i32 v[46:47], s[16:17], v73, s22, v[78:79]
	v_ashrrev_i32_e32 v51, 31, v50
	v_add_u32_e32 v1, 0x600, v16
	global_load_dwordx4 v[42:45], v[42:43], off
	s_nop 0
	global_load_dwordx4 v[46:49], v[46:47], off
	v_lshlrev_b64 v[50:51], 1, v[50:51]
	v_ashrrev_i32_e32 v114, 4, v1
	v_lshl_add_u64 v[52:53], v[2:3], 0, v[50:51]
	v_lshl_add_u64 v[54:55], v[74:75], 0, v[50:51]
	v_lshlrev_b32_e32 v80, 7, v114
	global_load_dwordx4 v[50:53], v[52:53], off
	s_nop 0
	global_load_dwordx4 v[54:57], v[54:55], off
	v_mad_i64_i32 v[58:59], s[16:17], v93, s21, v[76:77]
	v_mad_i64_i32 v[62:63], s[16:17], v93, s22, v[78:79]
	v_ashrrev_i32_e32 v81, 31, v80
	global_load_dwordx4 v[58:61], v[58:59], off
	s_nop 0
	global_load_dwordx4 v[62:65], v[62:63], off
	v_lshlrev_b64 v[80:81], 1, v[80:81]
	v_lshl_add_u64 v[2:3], v[2:3], 0, v[80:81]
	v_lshl_add_u64 v[74:75], v[74:75], 0, v[80:81]
	global_load_dwordx4 v[94:97], v[2:3], off
	global_load_dwordx4 v[98:101], v[74:75], off
	v_mad_i64_i32 v[2:3], s[16:17], v114, s21, v[76:77]
	global_load_dwordx4 v[102:105], v[2:3], off
	v_mad_i64_i32 v[2:3], s[16:17], v114, s22, v[78:79]
; #define LAS __attribute__((address_space(3)))
; DI void ret_out_item(const Params& p, int l, int b, int h, int c, LAS unsigned char* lds) {
;     ...
; #pragma unroll
;         for (int i = 0; i < 4; ++i) {
;             const int cid = tid + i * 512, rr = cid >> 4, cc = cid & 15;
;             *(LAS u32x4*)(lds + 0 * MB + rr * RS + cc * 16) = t0[i]; *(LAS u32x4*)(lds + 1 * MB + rr * RS + cc * 16) = t1[i];
;             *(LAS u32x4*)(lds + 2 * MB + rr * RS + cc * 16) = t2[i]; *(LAS u32x4*)(lds + 3 * MB + rr * RS + cc * 16) = t3[i];
;         }
;     }
;     bf16x8 qf[4], qff[4], qfb[4];
;     const float qdf = exp2f(lgf * (float)(tl + 1)), qdb = exp2f(lgb * (float)(128 - tl));
; #pragma unroll
;     for (int ks = 0; ks < 4; ++ks) { qf[ks] = *(const bf16x8*)(P + row * INP + C_RQ + h * 128 + ks * 32 + q4 * 8); qff[ks] = scale1_bf16x8(qf[ks], qdf); qfb[ks] = scale1_bf16x8(qf[ks], qdb); }
	v_mov_b32_e32 v111, v0
	v_ashrrev_i32_e32 v0, 2, v16
	global_load_dwordx4 v[106:109], v[2:3], off
	v_bfi_b32 v78, -16, v0, v16
	v_ashrrev_i32_e32 v79, 31, v78
	v_lshl_add_u64 v[74:75], s[0:1], 0, v[78:79]
	v_mad_u64_u32 v[0:1], s[0:1], v74, s21, v[70:71]
	v_mad_i32_i24 v1, v75, s21, v1
	v_lshlrev_b32_e32 v80, 4, v92
	v_mov_b32_e32 v81, v69
	v_lshl_add_u64 v[76:77], v[0:1], 0, s[14:15]
	v_lshl_add_u64 v[112:113], v[76:77], 0, v[80:81]
	v_add_co_u32_e32 v0, vcc, s31, v112
	v_mov_b32_e32 v66, v67
	s_nop 0
	v_addc_co_u32_e32 v1, vcc, 0, v113, vcc
	global_load_dwordx4 v[120:123], v[0:1], off offset:2752
	global_load_dwordx4 v[124:127], v[0:1], off offset:2816
	global_load_dwordx4 v[128:131], v[0:1], off offset:2880
	global_load_dwordx4 v[0:3], v[0:1], off offset:2688
	v_mov_b32_e32 v67, v11
	v_mov_b32_e32 v110, v5
	v_pk_add_f32 v[66:67], v[66:67], v[110:111] neg_lo:[0,1] neg_hi:[0,1]
	v_mov_b32_e32 v8, v9
	v_mov_b32_e32 v9, v4
	v_pk_add_f32 v[4:5], v[8:9], v[66:67] neg_lo:[0,1] neg_hi:[0,1]
	v_mov_b32_e32 v12, v6
	v_pk_add_f32 v[8:9], v[12:13], v[4:5]
	v_mov_b32_e32 v7, v11
	v_pk_add_f32 v[12:13], v[8:9], v[8:9] op_sel:[0,1] op_sel_hi:[1,0]
	v_cmp_nlt_f32_e32 vcc, 1.0, v14
	v_pk_add_f32 v[10:11], v[10:11], v[12:13] op_sel:[1,0] op_sel_hi:[0,1]
	v_mov_b32_e32 v9, v10
	v_pk_add_f32 v[66:67], v[8:9], v[6:7] neg_lo:[0,1] neg_hi:[0,1]
	v_mov_b32_e32 v5, v12
	v_sub_f32_e32 v7, v8, v66
	v_pk_add_f32 v[4:5], v[4:5], v[66:67] neg_lo:[0,1] neg_hi:[0,1]
	v_sub_f32_e32 v6, v6, v7
	v_add_f32_e32 v4, v4, v6
	v_add_f32_e32 v4, v4, v5
	v_add_u32_e32 v5, 0, v68
	v_mul_lo_u32 v8, v17, s30
	v_add_u32_e32 v6, s23, v68
	v_add_u32_e32 v7, s27, v68
	v_add_u32_e32 v9, v5, v8
	s_waitcnt vmcnt(19)
	ds_write_b128 v9, v[18:21]
	s_waitcnt vmcnt(18)
	ds_write_b128 v9, v[22:25] offset:34816
	v_add_u32_e32 v9, v6, v8
	v_add_u32_e32 v8, v7, v8
	s_waitcnt vmcnt(16)
	ds_write_b128 v8, v[30:33]
	v_mul_lo_u32 v8, v73, s30
	ds_write_b128 v9, v[26:29]
	v_add_u32_e32 v9, v5, v8
	s_waitcnt vmcnt(15)
	ds_write_b128 v9, v[34:37]
	s_waitcnt vmcnt(14)
	ds_write_b128 v9, v[38:41] offset:34816
	v_add_u32_e32 v9, v6, v8
	v_add_u32_e32 v8, v7, v8
	v_add_f32_e32 v4, v10, v4
	v_cndmask_b32_e32 v4, v84, v4, vcc
	v_cmp_neq_f32_e32 vcc, 1.0, v14
	s_waitcnt vmcnt(13)
	ds_write_b128 v9, v[42:45]
	s_waitcnt vmcnt(12)
	ds_write_b128 v8, v[46:49]
	v_mul_lo_u32 v8, v93, s30
	v_add_u32_e32 v9, v5, v8
	s_waitcnt vmcnt(11)
	ds_write_b128 v9, v[50:53]
	s_waitcnt vmcnt(10)
	ds_write_b128 v9, v[54:57] offset:34816
	v_add_u32_e32 v9, v6, v8
	v_add_u32_e32 v8, v7, v8
	v_cndmask_b32_e32 v4, v85, v4, vcc
	v_cmp_lt_f32_e64 s[0:1], |v14|, s20
	s_waitcnt vmcnt(9)
	ds_write_b128 v9, v[58:61]
	s_waitcnt vmcnt(8)
	ds_write_b128 v8, v[62:65]
	v_mul_lo_u32 v8, v114, s30
	v_add_u32_e32 v5, v5, v8
	s_waitcnt vmcnt(7)
	ds_write_b128 v5, v[94:97]
	s_waitcnt vmcnt(6)
	ds_write_b128 v5, v[98:101] offset:34816
	v_add_u32_e32 v5, v6, v8
	v_add_u32_e32 v6, v7, v8
	s_waitcnt vmcnt(5)
	ds_write_b128 v5, v[102:105]
	v_add_u32_e32 v5, 1, v78
	v_cvt_f32_i32_e32 v5, v5
	v_sub_u32_e32 v7, 0x80, v78
	v_cvt_f32_i32_e32 v7, v7
	v_cndmask_b32_e64 v4, v4, -v14, s[0:1]
	v_mul_f32_e32 v79, 0x3fb8aa3b, v15
	s_waitcnt vmcnt(4)
	ds_write_b128 v6, v[106:109]
	v_mul_f32_e32 v6, v79, v5
	v_mul_f32_e32 v73, 0xbfb8aa3b, v4
	v_cmp_gt_f32_e32 vcc, s7, v6
	v_mul_f32_e64 v4, -v73, v7
	v_cmp_gt_f32_e64 s[0:1], s7, v4
	v_cndmask_b32_e32 v6, 0, v82, vcc
	v_fmac_f32_e32 v6, v79, v5
	v_cndmask_b32_e64 v4, 0, v82, s[0:1]
	v_exp_f32_e32 v5, v6
	v_fma_f32 v4, -v73, v7, v4
	v_exp_f32_e32 v4, v4
	v_cndmask_b32_e32 v6, 0, v86, vcc
	v_ldexp_f32 v17, v5, v6
	v_cndmask_b32_e64 v5, 0, v86, s[0:1]
	v_ldexp_f32 v19, v4, v5
	s_waitcnt vmcnt(0)
	v_lshlrev_b32_e32 v4, 16, v0
	v_mul_f32_e32 v5, v17, v4
	v_and_b32_e32 v6, 0xffff0000, v0
	v_mul_f32_e32 v7, v17, v6
	v_cvt_pk_bf16_f32 v48, v5, v7
	v_lshlrev_b32_e32 v5, 16, v1
	v_mul_f32_e32 v7, v17, v5
	v_and_b32_e32 v8, 0xffff0000, v1
	v_mul_f32_e32 v9, v17, v8
	v_cvt_pk_bf16_f32 v49, v7, v9
	v_lshlrev_b32_e32 v7, 16, v2
	v_mul_f32_e32 v9, v17, v7
	v_and_b32_e32 v10, 0xffff0000, v2
	v_mul_f32_e32 v11, v17, v10
	v_cvt_pk_bf16_f32 v50, v9, v11
	v_lshlrev_b32_e32 v9, 16, v3
	v_and_b32_e32 v14, 0xffff0000, v3
	v_mul_f32_e32 v4, v19, v4
	v_mul_f32_e32 v11, v17, v9
	v_mul_f32_e32 v15, v17, v14
	v_cvt_pk_bf16_f32 v51, v11, v15
	v_mul_f32_e32 v6, v19, v6
	v_cvt_pk_bf16_f32 v52, v4, v6
	v_mul_f32_e32 v4, v19, v5
	v_mul_f32_e32 v5, v19, v8
	v_cvt_pk_bf16_f32 v53, v4, v5
	v_mul_f32_e32 v4, v19, v7
	v_mul_f32_e32 v5, v19, v10
	v_lshl_add_u64 v[12:13], v[112:113], 0, s[8:9]
	v_cvt_pk_bf16_f32 v54, v4, v5
	v_mul_f32_e32 v4, v19, v9
	v_mul_f32_e32 v5, v19, v14
	v_cvt_pk_bf16_f32 v55, v4, v5
	s_waitcnt vmcnt(0)
	v_mov_b32_e32 v4, v120
	v_mov_b32_e32 v5, v121
	v_mov_b32_e32 v6, v122
	v_mov_b32_e32 v7, v123
	v_lshlrev_b32_e32 v8, 16, v4
	v_mul_f32_e32 v9, v17, v8
	v_and_b32_e32 v10, 0xffff0000, v4
	v_mul_f32_e32 v11, v17, v10
	v_cvt_pk_bf16_f32 v56, v9, v11
	v_lshlrev_b32_e32 v9, 16, v5
	v_mul_f32_e32 v11, v17, v9
	v_and_b32_e32 v14, 0xffff0000, v5
	v_mul_f32_e32 v15, v17, v14
	v_cvt_pk_bf16_f32 v57, v11, v15
	v_lshlrev_b32_e32 v11, 16, v6
	v_mul_f32_e32 v15, v17, v11
	v_and_b32_e32 v18, 0xffff0000, v6
	v_mul_f32_e32 v20, v17, v18
	v_cvt_pk_bf16_f32 v58, v15, v20
	v_lshlrev_b32_e32 v15, 16, v7
	v_and_b32_e32 v21, 0xffff0000, v7
	v_mul_f32_e32 v8, v19, v8
	v_mul_f32_e32 v20, v17, v15
	v_mul_f32_e32 v22, v17, v21
	v_cvt_pk_bf16_f32 v59, v20, v22
	v_mul_f32_e32 v10, v19, v10
	v_cvt_pk_bf16_f32 v60, v8, v10
	v_mul_f32_e32 v8, v19, v9
	v_mul_f32_e32 v9, v19, v14
	v_cvt_pk_bf16_f32 v61, v8, v9
	v_mul_f32_e32 v8, v19, v11
	v_mul_f32_e32 v9, v19, v18
	v_cvt_pk_bf16_f32 v62, v8, v9
	v_mul_f32_e32 v8, v19, v15
	v_mul_f32_e32 v9, v19, v21
	v_cvt_pk_bf16_f32 v63, v8, v9
	s_waitcnt vmcnt(0)
; #define LAS __attribute__((address_space(3)))
; #define MFMA16(a, b, c) __builtin_amdgcn_mfma_f32_16x16x32_bf16((a), (b), (c), 0, 0, 0)
; DI void ret_out_item(const Params& p, int l, int b, int h, int c, LAS unsigned char* lds) {
;     ...
;     for (int ks = 0; ks < 4; ++ks) { qf[ks] = *(const bf16x8*)(P + row * INP + C_RQ + h * 128 + ks * 32 + q4 * 8); qff[ks] = scale1_bf16x8(qf[ks], qdf); qfb[ks] = scale1_bf16x8(qf[ks], qdb); }
;     f32x4 oacc[8];
; #pragma unroll
;     for (int d = 0; d < 8; ++d) oacc[d] = (f32x4){0.f, 0.f, 0.f, 0.f};
;     __syncthreads();
;     const LAS unsigned char* sfp = lds + 0 * MB + r16 * RS + q4 * 16;
;     const LAS unsigned char* sbp = lds + 1 * MB + r16 * RS + q4 * 16;
;     const LAS unsigned char* kcp = lds + 2 * MB + r16 * RS + q4 * 16;
;     const LAS unsigned char* vtp = lds + 3 * MB + r16 * RS + q4 * 8;
; #pragma unroll
;     for (int d = 0; d < 8; ++d)
; #pragma unroll
;         for (int ks = 0; ks < 4; ++ks) {
;             oacc[d] = MFMA16(*(const LAS bf16x8*)(sfp + d * 16 * RS + ks * 64), qff[ks], oacc[d]);
;             oacc[d] = MFMA16(*(const LAS bf16x8*)(sbp + d * 16 * RS + ks * 64), qfb[ks], oacc[d]);
;         }
	v_mov_b32_e32 v8, v124
	v_mov_b32_e32 v9, v125
	v_mov_b32_e32 v10, v126
	v_mov_b32_e32 v11, v127
	v_lshlrev_b32_e32 v14, 16, v8
	v_mul_f32_e32 v15, v17, v14
	v_and_b32_e32 v18, 0xffff0000, v8
	v_mul_f32_e32 v20, v17, v18
	v_cvt_pk_bf16_f32 v64, v15, v20
	v_lshlrev_b32_e32 v15, 16, v9
	v_mul_f32_e32 v20, v17, v15
	v_and_b32_e32 v21, 0xffff0000, v9
	v_mul_f32_e32 v22, v17, v21
	v_cvt_pk_bf16_f32 v65, v20, v22
	v_lshlrev_b32_e32 v20, 16, v10
	v_mul_f32_e32 v22, v17, v20
	v_and_b32_e32 v23, 0xffff0000, v10
	v_mul_f32_e32 v24, v17, v23
	v_cvt_pk_bf16_f32 v66, v22, v24
	v_lshlrev_b32_e32 v22, 16, v11
	v_and_b32_e32 v25, 0xffff0000, v11
	v_mul_f32_e32 v14, v19, v14
	v_mul_f32_e32 v24, v17, v22
	v_mul_f32_e32 v26, v17, v25
	v_cvt_pk_bf16_f32 v67, v24, v26
	v_mul_f32_e32 v18, v19, v18
	v_cvt_pk_bf16_f32 v94, v14, v18
	v_mul_f32_e32 v14, v19, v15
	v_mul_f32_e32 v15, v19, v21
	v_cvt_pk_bf16_f32 v95, v14, v15
	v_mul_f32_e32 v14, v19, v20
	v_mul_f32_e32 v15, v19, v23
	v_cvt_pk_bf16_f32 v96, v14, v15
	v_mul_f32_e32 v14, v19, v22
	v_mul_f32_e32 v15, v19, v25
	v_cvt_pk_bf16_f32 v97, v14, v15
	s_waitcnt vmcnt(0)
	v_mov_b32_e32 v12, v128
	v_mov_b32_e32 v13, v129
	v_mov_b32_e32 v14, v130
	v_mov_b32_e32 v15, v131
	v_and_b32_e32 v20, 15, v16
	v_mul_u32_u24_e32 v81, 0x110, v20
	v_add3_u32 v68, 0, v81, v80
	s_waitcnt vmcnt(0)
	v_lshlrev_b32_e32 v16, 16, v12
	v_mul_f32_e32 v18, v17, v16
	v_and_b32_e32 v21, 0xffff0000, v12
	v_mul_f32_e32 v22, v17, v21
	v_cvt_pk_bf16_f32 v98, v18, v22
	v_lshlrev_b32_e32 v18, 16, v13
	v_mul_f32_e32 v22, v17, v18
	v_and_b32_e32 v23, 0xffff0000, v13
	v_mul_f32_e32 v24, v17, v23
	v_cvt_pk_bf16_f32 v99, v22, v24
	v_lshlrev_b32_e32 v22, 16, v14
	v_mul_f32_e32 v24, v17, v22
	v_and_b32_e32 v25, 0xffff0000, v14
	v_mul_f32_e32 v26, v17, v25
	v_cvt_pk_bf16_f32 v100, v24, v26
	v_lshlrev_b32_e32 v24, 16, v15
	v_and_b32_e32 v27, 0xffff0000, v15
	v_mul_f32_e32 v26, v17, v24
	v_mul_f32_e32 v17, v17, v27
	v_cvt_pk_bf16_f32 v101, v26, v17
	v_mul_f32_e32 v16, v19, v16
	v_mul_f32_e32 v17, v19, v21
	v_cvt_pk_bf16_f32 v16, v16, v17
	v_mul_f32_e32 v17, v19, v18
	v_mul_f32_e32 v18, v19, v23
	v_cvt_pk_bf16_f32 v17, v17, v18
	v_mul_f32_e32 v18, v19, v22
	v_mul_f32_e32 v21, v19, v25
	v_cvt_pk_bf16_f32 v18, v18, v21
	v_mul_f32_e32 v21, v19, v24
	v_mul_f32_e32 v19, v19, v27
	v_cvt_pk_bf16_f32 v19, v21, v19
	s_waitcnt lgkmcnt(0)
	s_barrier
	ds_read_b128 v[20:23], v68
	ds_read_b128 v[24:27], v68 offset:64
	s_waitcnt lgkmcnt(1)
	v_mfma_f32_16x16x32_bf16 v[20:23], v[20:23], v[48:51], 0
	ds_read_b128 v[28:31], v68 offset:34816
	ds_read_b128 v[32:35], v68 offset:34880
	s_waitcnt lgkmcnt(1)
	v_mfma_f32_16x16x32_bf16 v[20:23], v[28:31], v[52:55], v[20:23]
	v_mfma_f32_16x16x32_bf16 v[20:23], v[24:27], v[56:59], v[20:23]
	ds_read_b128 v[24:27], v68 offset:128
	ds_read_b128 v[28:31], v68 offset:192
	s_waitcnt lgkmcnt(2)
	v_mfma_f32_16x16x32_bf16 v[20:23], v[32:35], v[60:63], v[20:23]
	s_waitcnt lgkmcnt(1)
	v_mfma_f32_16x16x32_bf16 v[20:23], v[24:27], v[64:67], v[20:23]
	ds_read_b128 v[24:27], v68 offset:34944
	ds_read_b128 v[32:35], v68 offset:35008
	s_waitcnt lgkmcnt(1)
	v_mfma_f32_16x16x32_bf16 v[20:23], v[24:27], v[94:97], v[20:23]
	v_mfma_f32_16x16x32_bf16 v[20:23], v[28:31], v[98:101], v[20:23]
	ds_read_b128 v[24:27], v68 offset:4352
	ds_read_b128 v[28:31], v68 offset:4416
	s_waitcnt lgkmcnt(2)
	v_mfma_f32_16x16x32_bf16 v[20:23], v[32:35], v[16:19], v[20:23]
	ds_read_b128 v[32:35], v68 offset:39168
	ds_read_b128 v[36:39], v68 offset:39232
	s_waitcnt lgkmcnt(3)
	v_mfma_f32_16x16x32_bf16 v[24:27], v[24:27], v[48:51], 0
	s_waitcnt lgkmcnt(1)
	v_mfma_f32_16x16x32_bf16 v[24:27], v[32:35], v[52:55], v[24:27]
	v_mfma_f32_16x16x32_bf16 v[24:27], v[28:31], v[56:59], v[24:27]
	ds_read_b128 v[28:31], v68 offset:4480
	ds_read_b128 v[32:35], v68 offset:4544
	s_waitcnt lgkmcnt(2)
	v_mfma_f32_16x16x32_bf16 v[24:27], v[36:39], v[60:63], v[24:27]
	s_waitcnt lgkmcnt(1)
	v_mfma_f32_16x16x32_bf16 v[24:27], v[28:31], v[64:67], v[24:27]
	ds_read_b128 v[28:31], v68 offset:39296
	ds_read_b128 v[36:39], v68 offset:39360
	s_waitcnt lgkmcnt(1)
	v_mfma_f32_16x16x32_bf16 v[24:27], v[28:31], v[94:97], v[24:27]
	v_mfma_f32_16x16x32_bf16 v[24:27], v[32:35], v[98:101], v[24:27]
	ds_read_b128 v[28:31], v68 offset:8704
	ds_read_b128 v[32:35], v68 offset:8768
	s_waitcnt lgkmcnt(2)
	v_mfma_f32_16x16x32_bf16 v[24:27], v[36:39], v[16:19], v[24:27]
	ds_read_b128 v[36:39], v68 offset:43520
	ds_read_b128 v[40:43], v68 offset:43584
	s_waitcnt lgkmcnt(3)
	v_mfma_f32_16x16x32_bf16 v[28:31], v[28:31], v[48:51], 0
	s_waitcnt lgkmcnt(1)
	v_mfma_f32_16x16x32_bf16 v[28:31], v[36:39], v[52:55], v[28:31]
	v_mfma_f32_16x16x32_bf16 v[28:31], v[32:35], v[56:59], v[28:31]
	ds_read_b128 v[32:35], v68 offset:8832
	ds_read_b128 v[36:39], v68 offset:8896
	s_waitcnt lgkmcnt(2)
	v_mfma_f32_16x16x32_bf16 v[28:31], v[40:43], v[60:63], v[28:31]
	s_waitcnt lgkmcnt(1)
	v_mfma_f32_16x16x32_bf16 v[28:31], v[32:35], v[64:67], v[28:31]
	ds_read_b128 v[32:35], v68 offset:43648
	ds_read_b128 v[40:43], v68 offset:43712
	s_waitcnt lgkmcnt(1)
	v_mfma_f32_16x16x32_bf16 v[28:31], v[32:35], v[94:97], v[28:31]
	v_mfma_f32_16x16x32_bf16 v[28:31], v[36:39], v[98:101], v[28:31]
	ds_read_b128 v[32:35], v68 offset:13056
	ds_read_b128 v[36:39], v68 offset:13120
	s_waitcnt lgkmcnt(2)
	v_mfma_f32_16x16x32_bf16 v[28:31], v[40:43], v[16:19], v[28:31]
	ds_read_b128 v[40:43], v68 offset:47872
	ds_read_b128 v[44:47], v68 offset:47936
	s_waitcnt lgkmcnt(3)
	v_mfma_f32_16x16x32_bf16 v[32:35], v[32:35], v[48:51], 0
	s_waitcnt lgkmcnt(1)
	v_mfma_f32_16x16x32_bf16 v[32:35], v[40:43], v[52:55], v[32:35]
	v_mfma_f32_16x16x32_bf16 v[32:35], v[36:39], v[56:59], v[32:35]
	ds_read_b128 v[36:39], v68 offset:13184
	ds_read_b128 v[40:43], v68 offset:13248
	s_waitcnt lgkmcnt(2)
; #define LAS __attribute__((address_space(3)))
; #define MFMA16(a, b, c) __builtin_amdgcn_mfma_f32_16x16x32_bf16((a), (b), (c), 0, 0, 0)
; DI void ret_out_item(const Params& p, int l, int b, int h, int c, LAS unsigned char* lds) {
;     ...
; #pragma unroll
;     for (int d = 0; d < 8; ++d)
; #pragma unroll
;         for (int ks = 0; ks < 4; ++ks) {
;             oacc[d] = MFMA16(*(const LAS bf16x8*)(sfp + d * 16 * RS + ks * 64), qff[ks], oacc[d]);
;             oacc[d] = MFMA16(*(const LAS bf16x8*)(sbp + d * 16 * RS + ks * 64), qfb[ks], oacc[d]);
;         }
; #pragma unroll
;     for (int kc = 0; kc < 4; ++kc) {
;         f32x4 s[2];
; #pragma unroll
;         for (int hf = 0; hf < 2; ++hf) {
;             s[hf] = (f32x4){0.f, 0.f, 0.f, 0.f};
; #pragma unroll
;             for (int ks = 0; ks < 4; ++ks) s[hf] = MFMA16(*(const LAS bf16x8*)(kcp + (2 * kc + hf) * 16 * RS + ks * 64), qf[ks], s[hf]);
; #pragma unroll
;             for (int j = 0; j < 4; ++j) {
;                 const int m = (2 * kc + hf) * 16 + q4 * 4 + j, d = tl - m;
;                 const float w = (d >= 0 ? exp2f(lgf * (float)d) : 0.f) + (d <= 0 ? exp2f(-lgb * (float)d) : 0.f);
;                 s[hf][j] *= w;
;             }
	v_mfma_f32_16x16x32_bf16 v[32:35], v[44:47], v[60:63], v[32:35]
	s_waitcnt lgkmcnt(1)
	v_mfma_f32_16x16x32_bf16 v[32:35], v[36:39], v[64:67], v[32:35]
	ds_read_b128 v[36:39], v68 offset:48000
	ds_read_b128 v[44:47], v68 offset:48064
	s_waitcnt lgkmcnt(1)
	v_mfma_f32_16x16x32_bf16 v[32:35], v[36:39], v[94:97], v[32:35]
	v_mfma_f32_16x16x32_bf16 v[32:35], v[40:43], v[98:101], v[32:35]
	ds_read_b128 v[36:39], v68 offset:17408
	ds_read_b128 v[40:43], v68 offset:17472
	s_waitcnt lgkmcnt(2)
	v_mfma_f32_16x16x32_bf16 v[32:35], v[44:47], v[16:19], v[32:35]
	ds_read_b128 v[44:47], v68 offset:52224
	ds_read_b128 v[102:105], v68 offset:52288
	s_waitcnt lgkmcnt(3)
	v_mfma_f32_16x16x32_bf16 v[36:39], v[36:39], v[48:51], 0
	s_waitcnt lgkmcnt(1)
	v_mfma_f32_16x16x32_bf16 v[36:39], v[44:47], v[52:55], v[36:39]
	v_mfma_f32_16x16x32_bf16 v[36:39], v[40:43], v[56:59], v[36:39]
	ds_read_b128 v[40:43], v68 offset:17536
	ds_read_b128 v[44:47], v68 offset:17600
	s_waitcnt lgkmcnt(2)
	v_mfma_f32_16x16x32_bf16 v[36:39], v[102:105], v[60:63], v[36:39]
	s_waitcnt lgkmcnt(1)
	v_mfma_f32_16x16x32_bf16 v[36:39], v[40:43], v[64:67], v[36:39]
	ds_read_b128 v[40:43], v68 offset:52352
	ds_read_b128 v[102:105], v68 offset:52416
	s_waitcnt lgkmcnt(1)
	v_mfma_f32_16x16x32_bf16 v[36:39], v[40:43], v[94:97], v[36:39]
	v_mfma_f32_16x16x32_bf16 v[36:39], v[44:47], v[98:101], v[36:39]
	ds_read_b128 v[40:43], v68 offset:21760
	ds_read_b128 v[44:47], v68 offset:21824
	s_waitcnt lgkmcnt(2)
	v_mfma_f32_16x16x32_bf16 v[36:39], v[102:105], v[16:19], v[36:39]
	ds_read_b128 v[102:105], v68 offset:56576
	ds_read_b128 v[106:109], v68 offset:56640
	s_waitcnt lgkmcnt(3)
	v_mfma_f32_16x16x32_bf16 v[40:43], v[40:43], v[48:51], 0
	s_waitcnt lgkmcnt(1)
	v_mfma_f32_16x16x32_bf16 v[40:43], v[102:105], v[52:55], v[40:43]
	v_mfma_f32_16x16x32_bf16 v[40:43], v[44:47], v[56:59], v[40:43]
	ds_read_b128 v[44:47], v68 offset:21888
	ds_read_b128 v[102:105], v68 offset:21952
	s_waitcnt lgkmcnt(2)
	v_mfma_f32_16x16x32_bf16 v[40:43], v[106:109], v[60:63], v[40:43]
	s_waitcnt lgkmcnt(1)
	v_mfma_f32_16x16x32_bf16 v[40:43], v[44:47], v[64:67], v[40:43]
	ds_read_b128 v[44:47], v68 offset:56704
	ds_read_b128 v[106:109], v68 offset:56768
	s_waitcnt lgkmcnt(1)
	v_mfma_f32_16x16x32_bf16 v[40:43], v[44:47], v[94:97], v[40:43]
	v_mfma_f32_16x16x32_bf16 v[40:43], v[102:105], v[98:101], v[40:43]
	ds_read_b128 v[44:47], v68 offset:26112
	ds_read_b128 v[102:105], v68 offset:26176
	s_waitcnt lgkmcnt(2)
	v_mfma_f32_16x16x32_bf16 v[40:43], v[106:109], v[16:19], v[40:43]
	ds_read_b128 v[106:109], v68 offset:60928
	ds_read_b128 v[110:113], v68 offset:60992
	s_waitcnt lgkmcnt(3)
	v_mfma_f32_16x16x32_bf16 v[44:47], v[44:47], v[48:51], 0
	s_waitcnt lgkmcnt(1)
	v_mfma_f32_16x16x32_bf16 v[44:47], v[106:109], v[52:55], v[44:47]
	v_mfma_f32_16x16x32_bf16 v[44:47], v[102:105], v[56:59], v[44:47]
	ds_read_b128 v[102:105], v68 offset:26240
	ds_read_b128 v[106:109], v68 offset:26304
	s_waitcnt lgkmcnt(2)
	v_mfma_f32_16x16x32_bf16 v[44:47], v[110:113], v[60:63], v[44:47]
	s_waitcnt lgkmcnt(1)
	v_mfma_f32_16x16x32_bf16 v[44:47], v[102:105], v[64:67], v[44:47]
	ds_read_b128 v[102:105], v68 offset:61056
	ds_read_b128 v[110:113], v68 offset:61120
	s_waitcnt lgkmcnt(1)
	v_mfma_f32_16x16x32_bf16 v[44:47], v[102:105], v[94:97], v[44:47]
	v_mfma_f32_16x16x32_bf16 v[44:47], v[106:109], v[98:101], v[44:47]
	ds_read_b128 v[102:105], v68 offset:30464
	ds_read_b128 v[106:109], v68 offset:30528
	s_waitcnt lgkmcnt(2)
	v_mfma_f32_16x16x32_bf16 v[44:47], v[110:113], v[16:19], v[44:47]
	s_waitcnt lgkmcnt(1)
	v_mfma_f32_16x16x32_bf16 v[48:51], v[102:105], v[48:51], 0
	ds_read_b128 v[102:105], v68 offset:65280
	ds_read_b128 v[110:113], v68 offset:65344
	s_waitcnt lgkmcnt(1)
	v_mfma_f32_16x16x32_bf16 v[48:51], v[102:105], v[52:55], v[48:51]
	v_mfma_f32_16x16x32_bf16 v[48:51], v[106:109], v[56:59], v[48:51]
	ds_read_b128 v[52:55], v68 offset:30592
	ds_read_b128 v[56:59], v68 offset:30656
	s_waitcnt lgkmcnt(2)
	v_mfma_f32_16x16x32_bf16 v[48:51], v[110:113], v[60:63], v[48:51]
	v_add3_u32 v62, s23, v81, v80
	v_lshlrev_b32_e32 v61, 2, v92
	v_sub_u32_e32 v63, v78, v61
	s_waitcnt lgkmcnt(1)
	v_mfma_f32_16x16x32_bf16 v[48:51], v[52:55], v[64:67], v[48:51]
	ds_read_b128 v[64:67], v68 offset:65408
	ds_read_b128 v[52:55], v68 offset:65472
	v_cvt_f32_u32_e32 v80, v63
	s_waitcnt lgkmcnt(1)
	v_mfma_f32_16x16x32_bf16 v[48:51], v[64:67], v[94:97], v[48:51]
	ds_read_b128 v[64:67], v62
	ds_read_b128 v[94:97], v62 offset:128
	v_lshlrev_b32_e32 v68, 3, v92
	v_mfma_f32_16x16x32_bf16 v[56:59], v[56:59], v[98:101], v[48:51]
	v_add3_u32 v60, s27, v81, v68
	v_mul_f32_e32 v81, v79, v80
	v_cmp_gt_f32_e32 vcc, s7, v81
	s_nop 0
	ds_read_b128 v[48:51], v62 offset:64
	s_waitcnt lgkmcnt(2)
	v_mfma_f32_16x16x32_bf16 v[64:67], v[64:67], v[0:3], 0
	v_cndmask_b32_e32 v81, 0, v82, vcc
	v_fmac_f32_e32 v81, v79, v80
	v_exp_f32_e32 v80, v81
	s_waitcnt lgkmcnt(0)
	v_mfma_f32_16x16x32_bf16 v[48:51], v[48:51], v[4:7], v[64:67]
	s_nop 2
	ds_read_b128 v[64:67], v62 offset:192
	v_cvt_f32_i32_e32 v81, v63
	v_cmp_lt_i32_e64 s[0:1], -1, v63
	v_mfma_f32_16x16x32_bf16 v[48:51], v[94:97], v[8:11], v[48:51]
	ds_read_b128 v[96:99], v62 offset:4480
	s_waitcnt lgkmcnt(1)
; #define LAS __attribute__((address_space(3)))
; DI unsigned cvt_pk_bf16(float lo, float hi) { unsigned r; asm volatile("v_cvt_pk_bf16_f32 %0, %1, %2" : "=v"(r) : "v"(lo), "v"(hi)); return r; }
; #define MFMA16(a, b, c) __builtin_amdgcn_mfma_f32_16x16x32_bf16((a), (b), (c), 0, 0, 0)
; DI void ret_out_item(const Params& p, int l, int b, int h, int c, LAS unsigned char* lds) {
;     ...
;     for (int kc = 0; kc < 4; ++kc) {
;         f32x4 s[2];
; #pragma unroll
;         for (int hf = 0; hf < 2; ++hf) {
;             s[hf] = (f32x4){0.f, 0.f, 0.f, 0.f};
; #pragma unroll
;             for (int ks = 0; ks < 4; ++ks) s[hf] = MFMA16(*(const LAS bf16x8*)(kcp + (2 * kc + hf) * 16 * RS + ks * 64), qf[ks], s[hf]);
; #pragma unroll
;             for (int j = 0; j < 4; ++j) {
;                 const int m = (2 * kc + hf) * 16 + q4 * 4 + j, d = tl - m;
;                 const float w = (d >= 0 ? exp2f(lgf * (float)d) : 0.f) + (d <= 0 ? exp2f(-lgb * (float)d) : 0.f);
;                 s[hf][j] *= w;
;             }
;         }
;         u32x4 w4; w4.x = cvt_pk_bf16(s[0][0], s[0][1]); w4.y = cvt_pk_bf16(s[0][2], s[0][3]); w4.z = cvt_pk_bf16(s[1][0], s[1][1]); w4.w = cvt_pk_bf16(s[1][2], s[1][3]);
;         const bf16x8 pb = __builtin_bit_cast(bf16x8, w4);
; #pragma unroll
;         for (int d = 0; d < 8; ++d) {
;             const u32x2 lo = *(const LAS u32x2*)(vtp + d * 16 * RS + kc * 64), hi = *(const LAS u32x2*)(vtp + d * 16 * RS + kc * 64 + 32);
;             u32x4 a4; a4.x = lo.x; a4.y = lo.y; a4.z = hi.x; a4.w = hi.y;
;             oacc[d] = MFMA16(__builtin_bit_cast(bf16x8, a4), pb, oacc[d]);
;         }
	v_mfma_f32_16x16x32_bf16 v[48:51], v[64:67], v[12:15], v[48:51]
	v_mul_f32_e32 v65, v81, v73
	v_cndmask_b32_e32 v64, 0, v86, vcc
	v_cmp_gt_f32_e32 vcc, s7, v65
	v_ldexp_f32 v64, v80, v64
	v_cndmask_b32_e64 v64, 0, v64, s[0:1]
	v_cndmask_b32_e32 v65, 0, v82, vcc
	v_fmac_f32_e32 v65, v81, v73
	v_exp_f32_e32 v65, v65
	v_cndmask_b32_e32 v66, 0, v86, vcc
	v_cmp_gt_i32_e32 vcc, 1, v63
	v_mfma_f32_16x16x32_bf16 v[52:55], v[52:55], v[16:19], v[56:59]
	v_ldexp_f32 v65, v65, v66
	v_xad_u32 v66, v61, -1, v78
	v_cvt_f32_u32_e32 v67, v66
	v_cndmask_b32_e32 v63, 0, v65, vcc
	v_add_f32_e32 v63, v64, v63
	v_cvt_f32_i32_e32 v65, v66
	v_mul_f32_e32 v64, v79, v67
	v_cmp_gt_f32_e32 vcc, s7, v64
	v_mul_f32_e32 v63, v63, v48
	v_cmp_lt_i32_e64 s[0:1], -1, v66
	v_cndmask_b32_e32 v64, 0, v82, vcc
	v_fmac_f32_e32 v64, v79, v67
	v_exp_f32_e32 v64, v64
	v_cndmask_b32_e32 v48, 0, v86, vcc
	v_ldexp_f32 v48, v64, v48
	v_mul_f32_e32 v64, v65, v73
	v_cmp_gt_f32_e32 vcc, s7, v64
	v_cndmask_b32_e64 v48, 0, v48, s[0:1]
	s_nop 0
	v_cndmask_b32_e32 v64, 0, v82, vcc
	v_fmac_f32_e32 v64, v65, v73
	v_exp_f32_e32 v64, v64
	v_cndmask_b32_e32 v65, 0, v86, vcc
	v_cmp_gt_i32_e32 vcc, 1, v66
	v_ldexp_f32 v64, v64, v65
	v_or_b32_e32 v65, 2, v61
	v_sub_u32_e32 v65, v78, v65
	v_cvt_f32_u32_e32 v67, v65
	v_cvt_f32_i32_e32 v66, v65
	v_cndmask_b32_e32 v64, 0, v64, vcc
	v_add_f32_e32 v48, v48, v64
	v_mul_f32_e32 v64, v79, v67
	v_cmp_gt_f32_e32 vcc, s7, v64
	v_mul_f32_e32 v80, v48, v49
	v_mul_f32_e32 v49, v66, v73
	v_cndmask_b32_e32 v64, 0, v82, vcc
	v_cndmask_b32_e32 v48, 0, v86, vcc
	v_cmp_gt_f32_e32 vcc, s7, v49
	v_fmac_f32_e32 v64, v79, v67
	v_exp_f32_e32 v64, v64
	v_cndmask_b32_e32 v49, 0, v82, vcc
	v_fmac_f32_e32 v49, v66, v73
	v_exp_f32_e32 v49, v49
	v_ldexp_f32 v48, v64, v48
	v_cndmask_b32_e32 v64, 0, v86, vcc
	v_cmp_lt_i32_e64 s[0:1], -1, v65
	v_ldexp_f32 v49, v49, v64
	v_or_b32_e32 v64, 3, v61
	v_sub_u32_e32 v81, v78, v64
	v_cvt_f32_u32_e32 v64, v81
	v_cmp_gt_i32_e32 vcc, 1, v65
	v_cndmask_b32_e64 v48, 0, v48, s[0:1]
	v_cvt_f32_i32_e32 v92, v81
	v_cndmask_b32_e32 v49, 0, v49, vcc
	v_add_f32_e32 v48, v48, v49
	v_mul_f32_e32 v49, v79, v64
	v_cmp_gt_f32_e32 vcc, s7, v49
	v_mul_f32_e32 v100, v48, v50
	v_cmp_lt_i32_e64 s[0:1], -1, v81
	v_cndmask_b32_e32 v49, 0, v82, vcc
	v_fmac_f32_e32 v49, v79, v64
	v_exp_f32_e32 v49, v49
	v_cndmask_b32_e32 v48, 0, v86, vcc
	ds_read_b128 v[64:67], v62 offset:4352
	v_ldexp_f32 v48, v49, v48
	v_mul_f32_e32 v49, v92, v73
	v_cmp_gt_f32_e32 vcc, s7, v49
	v_cndmask_b32_e64 v48, 0, v48, s[0:1]
	s_nop 0
	v_cndmask_b32_e32 v49, 0, v82, vcc
	v_fmac_f32_e32 v49, v92, v73
	ds_read_b128 v[92:95], v62 offset:4416
	v_exp_f32_e32 v49, v49
	v_cndmask_b32_e32 v50, 0, v86, vcc
	s_waitcnt lgkmcnt(1)
	v_mfma_f32_16x16x32_bf16 v[64:67], v[64:67], v[0:3], 0
	v_cmp_gt_i32_e32 vcc, 1, v81
	v_ldexp_f32 v49, v49, v50
	s_nop 0
	v_cndmask_b32_e32 v49, 0, v49, vcc
	v_add_f32_e32 v48, v48, v49
	v_or_b32_e32 v49, 16, v61
	v_sub_u32_e32 v81, v78, v49
	s_waitcnt lgkmcnt(0)
	v_mfma_f32_16x16x32_bf16 v[64:67], v[92:95], v[4:7], v[64:67]
	v_cvt_f32_u32_e32 v101, v81
	ds_read_b128 v[92:95], v62 offset:4544
	v_mul_f32_e32 v102, v48, v51
	v_mfma_f32_16x16x32_bf16 v[48:51], v[96:99], v[8:11], v[64:67]
	v_cmp_lt_i32_e64 s[0:1], -1, v81
	s_nop 2
	v_mul_f32_e32 v64, v79, v101
	v_cmp_gt_f32_e32 vcc, s7, v64
	v_cvt_f32_i32_e32 v65, v81
	s_waitcnt lgkmcnt(0)
	v_mfma_f32_16x16x32_bf16 v[48:51], v[92:95], v[12:15], v[48:51]
	v_cndmask_b32_e32 v64, 0, v82, vcc
	v_fmac_f32_e32 v64, v79, v101
	v_exp_f32_e32 v64, v64
	v_cndmask_b32_e32 v66, 0, v86, vcc
	v_ldexp_f32 v64, v64, v66
	v_mul_f32_e32 v66, v65, v73
	v_cmp_gt_f32_e32 vcc, s7, v66
	v_cndmask_b32_e64 v64, 0, v64, s[0:1]
	s_nop 0
	v_cndmask_b32_e32 v66, 0, v82, vcc
	v_fmac_f32_e32 v66, v65, v73
	v_exp_f32_e32 v65, v66
	v_cndmask_b32_e32 v66, 0, v86, vcc
	v_cmp_gt_i32_e32 vcc, 1, v81
	v_ldexp_f32 v65, v65, v66
	v_or_b32_e32 v66, 17, v61
	v_sub_u32_e32 v66, v78, v66
	v_cvt_f32_u32_e32 v67, v66
	v_cndmask_b32_e32 v65, 0, v65, vcc
	v_add_f32_e32 v64, v64, v65
	v_mul_f32_e32 v64, v64, v48
	v_mul_f32_e32 v65, v79, v67
	v_cmp_gt_f32_e32 vcc, s7, v65
	v_cmp_lt_i32_e64 s[0:1], -1, v66
	s_nop 0
	v_cndmask_b32_e32 v65, 0, v82, vcc
	v_fmac_f32_e32 v65, v79, v67
	v_exp_f32_e32 v65, v65
	v_cvt_f32_i32_e32 v67, v66
	v_cndmask_b32_e32 v48, 0, v86, vcc
	v_ldexp_f32 v48, v65, v48
	v_mul_f32_e32 v65, v67, v73
	v_cmp_gt_f32_e32 vcc, s7, v65
	v_cndmask_b32_e64 v48, 0, v48, s[0:1]
	s_nop 0
	v_cndmask_b32_e32 v65, 0, v82, vcc
	v_fmac_f32_e32 v65, v67, v73
	v_exp_f32_e32 v65, v65
	v_cndmask_b32_e32 v67, 0, v86, vcc
	v_cmp_gt_i32_e32 vcc, 1, v66
	v_ldexp_f32 v65, v65, v67
	v_or_b32_e32 v67, 18, v61
	v_sub_u32_e32 v67, v78, v67
	v_cvt_f32_u32_e32 v81, v67
	v_cndmask_b32_e32 v65, 0, v65, vcc
	v_cvt_f32_i32_e32 v66, v67
	v_add_f32_e32 v48, v48, v65
	v_mul_f32_e32 v65, v79, v81
	v_cmp_gt_f32_e32 vcc, s7, v65
	v_cmp_lt_i32_e64 s[0:1], -1, v67
	s_nop 0
	v_cndmask_b32_e32 v65, 0, v82, vcc
	v_fmac_f32_e32 v65, v79, v81
	v_mul_f32_e32 v81, v48, v49
	v_mul_f32_e32 v49, v66, v73
	v_cndmask_b32_e32 v48, 0, v86, vcc
	v_cmp_gt_f32_e32 vcc, s7, v49
	v_exp_f32_e32 v65, v65
	s_nop 0
	v_cndmask_b32_e32 v49, 0, v82, vcc
	v_fmac_f32_e32 v49, v66, v73
	v_exp_f32_e32 v49, v49
	v_ldexp_f32 v48, v65, v48
	v_cndmask_b32_e32 v65, 0, v86, vcc
	v_cmp_gt_i32_e32 vcc, 1, v67
	v_ldexp_f32 v49, v49, v65
	v_or_b32_e32 v65, 19, v61
	v_sub_u32_e32 v65, v78, v65
	v_cvt_f32_u32_e32 v66, v65
	v_cndmask_b32_e64 v48, 0, v48, s[0:1]
	v_cndmask_b32_e32 v49, 0, v49, vcc
	v_add_f32_e32 v48, v48, v49
	v_mul_f32_e32 v49, v79, v66
	v_cmp_gt_f32_e32 vcc, s7, v49
	v_mul_f32_e32 v67, v48, v50
	v_cmp_lt_i32_e64 s[0:1], -1, v65
	v_cndmask_b32_e32 v49, 0, v82, vcc
	v_fmac_f32_e32 v49, v79, v66
	v_exp_f32_e32 v49, v49
	v_cvt_f32_i32_e32 v66, v65
	v_cndmask_b32_e32 v48, 0, v86, vcc
	v_ldexp_f32 v48, v49, v48
	v_mul_f32_e32 v49, v66, v73
	v_cmp_gt_f32_e32 vcc, s7, v49
	v_cndmask_b32_e64 v48, 0, v48, s[0:1]
	s_nop 0
	v_cndmask_b32_e32 v49, 0, v82, vcc
	v_fmac_f32_e32 v49, v66, v73
	v_exp_f32_e32 v49, v49
	v_cndmask_b32_e32 v50, 0, v86, vcc
	v_cmp_gt_i32_e32 vcc, 1, v65
	v_ldexp_f32 v49, v49, v50
	s_nop 0
	v_cndmask_b32_e32 v49, 0, v49, vcc
	v_add_f32_e32 v48, v48, v49
	v_mul_f32_e32 v51, v48, v51
	v_cvt_pk_bf16_f32 v48, v63, v80
	v_cvt_pk_bf16_f32 v49, v100, v102
	v_cvt_pk_bf16_f32 v50, v64, v81
	v_cvt_pk_bf16_f32 v51, v67, v51
	ds_read2_b64 v[64:67], v60 offset1:4
	v_add_u32_e32 v63, 0x1000, v60
	ds_read2_b64 v[16:19], v63 offset0:32 offset1:36
	s_waitcnt lgkmcnt(1)
; #define LAS __attribute__((address_space(3)))
; DI unsigned cvt_pk_bf16(float lo, float hi) { unsigned r; asm volatile("v_cvt_pk_bf16_f32 %0, %1, %2" : "=v"(r) : "v"(lo), "v"(hi)); return r; }
; #define MFMA16(a, b, c) __builtin_amdgcn_mfma_f32_16x16x32_bf16((a), (b), (c), 0, 0, 0)
; DI void ret_out_item(const Params& p, int l, int b, int h, int c, LAS unsigned char* lds) {
;     ...
;     for (int kc = 0; kc < 4; ++kc) {
;         f32x4 s[2];
; #pragma unroll
;         for (int hf = 0; hf < 2; ++hf) {
;             s[hf] = (f32x4){0.f, 0.f, 0.f, 0.f};
; #pragma unroll
;             for (int ks = 0; ks < 4; ++ks) s[hf] = MFMA16(*(const LAS bf16x8*)(kcp + (2 * kc + hf) * 16 * RS + ks * 64), qf[ks], s[hf]);
; #pragma unroll
;             for (int j = 0; j < 4; ++j) {
;                 const int m = (2 * kc + hf) * 16 + q4 * 4 + j, d = tl - m;
;                 const float w = (d >= 0 ? exp2f(lgf * (float)d) : 0.f) + (d <= 0 ? exp2f(-lgb * (float)d) : 0.f);
;                 s[hf][j] *= w;
;             }
;         }
;         u32x4 w4; w4.x = cvt_pk_bf16(s[0][0], s[0][1]); w4.y = cvt_pk_bf16(s[0][2], s[0][3]); w4.z = cvt_pk_bf16(s[1][0], s[1][1]); w4.w = cvt_pk_bf16(s[1][2], s[1][3]);
;         const bf16x8 pb = __builtin_bit_cast(bf16x8, w4);
; #pragma unroll
;         for (int d = 0; d < 8; ++d) {
;             const u32x2 lo = *(const LAS u32x2*)(vtp + d * 16 * RS + kc * 64), hi = *(const LAS u32x2*)(vtp + d * 16 * RS + kc * 64 + 32);
;             u32x4 a4; a4.x = lo.x; a4.y = lo.y; a4.z = hi.x; a4.w = hi.y;
;             oacc[d] = MFMA16(__builtin_bit_cast(bf16x8, a4), pb, oacc[d]);
;         }
	v_mfma_f32_16x16x32_bf16 v[20:23], v[64:67], v[48:51], v[20:23]
	v_add_u32_e32 v64, 0x2000, v60
	ds_read2_b64 v[56:59], v64 offset0:64 offset1:68
	v_add_u32_e32 v65, 0x3000, v60
	s_waitcnt lgkmcnt(1)
	v_mfma_f32_16x16x32_bf16 v[24:27], v[16:19], v[48:51], v[24:27]
	ds_read2_b64 v[16:19], v65 offset0:96 offset1:100
	v_add_u32_e32 v66, 0x4000, v60
	v_add_u32_e32 v67, 0x5000, v60
	s_waitcnt lgkmcnt(1)
	v_mfma_f32_16x16x32_bf16 v[28:31], v[56:59], v[48:51], v[28:31]
	ds_read2_b64 v[56:59], v66 offset0:128 offset1:132
	v_add_u32_e32 v80, 0x6000, v60
	ds_read_b128 v[92:95], v62 offset:8832
	s_waitcnt lgkmcnt(2)
	v_mfma_f32_16x16x32_bf16 v[32:35], v[16:19], v[48:51], v[32:35]
	ds_read2_b64 v[16:19], v67 offset0:160 offset1:164
	v_add_u32_e32 v81, 0x7000, v60
	s_waitcnt lgkmcnt(2)
	v_mfma_f32_16x16x32_bf16 v[36:39], v[56:59], v[48:51], v[36:39]
	ds_read2_b64 v[56:59], v80 offset0:192 offset1:196
	s_waitcnt lgkmcnt(1)
	v_mfma_f32_16x16x32_bf16 v[40:43], v[16:19], v[48:51], v[40:43]
	ds_read_b128 v[16:19], v62 offset:8704
	s_waitcnt lgkmcnt(1)
	v_mfma_f32_16x16x32_bf16 v[44:47], v[56:59], v[48:51], v[44:47]
	ds_read_b128 v[56:59], v62 offset:8768
	s_waitcnt lgkmcnt(1)
	v_mfma_f32_16x16x32_bf16 v[16:19], v[16:19], v[0:3], 0
	s_waitcnt lgkmcnt(0)
	v_mfma_f32_16x16x32_bf16 v[16:19], v[56:59], v[4:7], v[16:19]
	v_or_b32_e32 v56, 32, v61
	v_sub_u32_e32 v100, v78, v56
	v_cvt_f32_u32_e32 v101, v100
	v_mfma_f32_16x16x32_bf16 v[16:19], v[92:95], v[8:11], v[16:19]
	v_cvt_f32_i32_e32 v93, v100
	v_cmp_lt_i32_e64 s[0:1], -1, v100
	v_mul_f32_e32 v92, v79, v101
	v_cmp_gt_f32_e32 vcc, s7, v92
	ds_read_b128 v[96:99], v62 offset:8896
	ds_read2_b64 v[56:59], v81 offset0:224 offset1:228
	v_cndmask_b32_e32 v92, 0, v82, vcc
	v_fmac_f32_e32 v92, v79, v101
	v_exp_f32_e32 v92, v92
	v_cndmask_b32_e32 v94, 0, v86, vcc
	s_waitcnt lgkmcnt(1)
	v_mfma_f32_16x16x32_bf16 v[16:19], v[96:99], v[12:15], v[16:19]
	v_ldexp_f32 v92, v92, v94
	v_mul_f32_e32 v94, v93, v73
	v_cmp_gt_f32_e32 vcc, s7, v94
	v_cndmask_b32_e64 v92, 0, v92, s[0:1]
	s_waitcnt lgkmcnt(0)
	v_mfma_f32_16x16x32_bf16 v[48:51], v[56:59], v[48:51], v[52:55]
	v_cndmask_b32_e32 v94, 0, v82, vcc
	v_fmac_f32_e32 v94, v93, v73
	v_exp_f32_e32 v93, v94
	v_cndmask_b32_e32 v94, 0, v86, vcc
	v_cmp_gt_i32_e32 vcc, 1, v100
	ds_read_b128 v[100:103], v62 offset:13184
	v_ldexp_f32 v93, v93, v94
	v_or_b32_e32 v94, 33, v61
	v_sub_u32_e32 v94, v78, v94
	v_cvt_f32_u32_e32 v95, v94
	v_cndmask_b32_e32 v93, 0, v93, vcc
	v_add_f32_e32 v92, v92, v93
	v_mul_f32_e32 v104, v92, v16
	v_mul_f32_e32 v93, v79, v95
	v_cmp_gt_f32_e32 vcc, s7, v93
	v_cmp_lt_i32_e64 s[0:1], -1, v94
	s_nop 0
	v_cndmask_b32_e32 v93, 0, v82, vcc
	v_fmac_f32_e32 v93, v79, v95
	v_cvt_f32_i32_e32 v95, v94
	v_cndmask_b32_e32 v16, 0, v86, vcc
	v_exp_f32_e32 v93, v93
	v_mul_f32_e32 v92, v95, v73
	v_cmp_gt_f32_e32 vcc, s7, v92
	v_ldexp_f32 v16, v93, v16
	v_cndmask_b32_e64 v16, 0, v16, s[0:1]
	v_cndmask_b32_e32 v92, 0, v82, vcc
	v_fmac_f32_e32 v92, v95, v73
	v_exp_f32_e32 v92, v92
	v_cndmask_b32_e32 v93, 0, v86, vcc
	v_cmp_gt_i32_e32 vcc, 1, v94
	v_ldexp_f32 v92, v92, v93
	v_or_b32_e32 v93, 34, v61
	v_sub_u32_e32 v93, v78, v93
	v_cvt_f32_u32_e32 v95, v93
	v_cvt_f32_i32_e32 v94, v93
	v_cndmask_b32_e32 v92, 0, v92, vcc
	v_add_f32_e32 v16, v16, v92
	v_mul_f32_e32 v92, v79, v95
	v_cmp_gt_f32_e32 vcc, s7, v92
	v_mul_f32_e32 v105, v16, v17
	v_mul_f32_e32 v17, v94, v73
	v_cndmask_b32_e32 v92, 0, v82, vcc
	v_cndmask_b32_e32 v16, 0, v86, vcc
	v_cmp_gt_f32_e32 vcc, s7, v17
	v_fmac_f32_e32 v92, v79, v95
	v_exp_f32_e32 v92, v92
	v_cndmask_b32_e32 v17, 0, v82, vcc
	v_fmac_f32_e32 v17, v94, v73
	v_exp_f32_e32 v17, v17
	v_ldexp_f32 v16, v92, v16
	v_cndmask_b32_e32 v92, 0, v86, vcc
	v_cmp_lt_i32_e64 s[0:1], -1, v93
	v_ldexp_f32 v17, v17, v92
	v_or_b32_e32 v92, 35, v61
	v_sub_u32_e32 v106, v78, v92
	v_cvt_f32_u32_e32 v92, v106
	v_cmp_gt_i32_e32 vcc, 1, v93
	v_cndmask_b32_e64 v16, 0, v16, s[0:1]
	v_cvt_f32_i32_e32 v96, v106
	v_cndmask_b32_e32 v17, 0, v17, vcc
	v_add_f32_e32 v16, v16, v17
	v_mul_f32_e32 v17, v79, v92
	v_cmp_gt_f32_e32 vcc, s7, v17
	v_mul_f32_e32 v107, v16, v18
	v_cmp_lt_i32_e64 s[0:1], -1, v106
	v_cndmask_b32_e32 v17, 0, v82, vcc
	v_fmac_f32_e32 v17, v79, v92
	v_exp_f32_e32 v17, v17
	v_cndmask_b32_e32 v16, 0, v86, vcc
	ds_read_b128 v[92:95], v62 offset:13056
	v_ldexp_f32 v16, v17, v16
	v_mul_f32_e32 v17, v96, v73
	v_cmp_gt_f32_e32 vcc, s7, v17
	v_cndmask_b32_e64 v16, 0, v16, s[0:1]
	s_nop 0
	v_cndmask_b32_e32 v17, 0, v82, vcc
	v_fmac_f32_e32 v17, v96, v73
	ds_read_b128 v[96:99], v62 offset:13120
	v_exp_f32_e32 v17, v17
	v_cndmask_b32_e32 v18, 0, v86, vcc
	s_waitcnt lgkmcnt(1)
	v_mfma_f32_16x16x32_bf16 v[92:95], v[92:95], v[0:3], 0
	v_cmp_gt_i32_e32 vcc, 1, v106
	v_ldexp_f32 v17, v17, v18
	s_nop 0
	v_cndmask_b32_e32 v17, 0, v17, vcc
	v_add_f32_e32 v16, v16, v17
	v_or_b32_e32 v17, 48, v61
	v_sub_u32_e32 v106, v78, v17
	s_waitcnt lgkmcnt(0)
	v_mfma_f32_16x16x32_bf16 v[92:95], v[96:99], v[4:7], v[92:95]
	v_cvt_f32_u32_e32 v108, v106
	ds_read_b128 v[96:99], v62 offset:13248
	v_mul_f32_e32 v109, v16, v19
	v_mfma_f32_16x16x32_bf16 v[16:19], v[100:103], v[8:11], v[92:95]
	v_cmp_lt_i32_e64 s[0:1], -1, v106
	s_nop 2
	v_mul_f32_e32 v92, v79, v108
	v_cmp_gt_f32_e32 vcc, s7, v92
	v_cvt_f32_i32_e32 v93, v106
	s_waitcnt lgkmcnt(0)
; #define LAS __attribute__((address_space(3)))
; DI unsigned cvt_pk_bf16(float lo, float hi) { unsigned r; asm volatile("v_cvt_pk_bf16_f32 %0, %1, %2" : "=v"(r) : "v"(lo), "v"(hi)); return r; }
; #define MFMA16(a, b, c) __builtin_amdgcn_mfma_f32_16x16x32_bf16((a), (b), (c), 0, 0, 0)
; DI void ret_out_item(const Params& p, int l, int b, int h, int c, LAS unsigned char* lds) {
;     ...
;     for (int kc = 0; kc < 4; ++kc) {
;         f32x4 s[2];
; #pragma unroll
;         for (int hf = 0; hf < 2; ++hf) {
;             s[hf] = (f32x4){0.f, 0.f, 0.f, 0.f};
; #pragma unroll
;             for (int ks = 0; ks < 4; ++ks) s[hf] = MFMA16(*(const LAS bf16x8*)(kcp + (2 * kc + hf) * 16 * RS + ks * 64), qf[ks], s[hf]);
; #pragma unroll
;             for (int j = 0; j < 4; ++j) {
;                 const int m = (2 * kc + hf) * 16 + q4 * 4 + j, d = tl - m;
;                 const float w = (d >= 0 ? exp2f(lgf * (float)d) : 0.f) + (d <= 0 ? exp2f(-lgb * (float)d) : 0.f);
;                 s[hf][j] *= w;
;             }
;         }
;         u32x4 w4; w4.x = cvt_pk_bf16(s[0][0], s[0][1]); w4.y = cvt_pk_bf16(s[0][2], s[0][3]); w4.z = cvt_pk_bf16(s[1][0], s[1][1]); w4.w = cvt_pk_bf16(s[1][2], s[1][3]);
;         const bf16x8 pb = __builtin_bit_cast(bf16x8, w4);
; #pragma unroll
;         for (int d = 0; d < 8; ++d) {
;             const u32x2 lo = *(const LAS u32x2*)(vtp + d * 16 * RS + kc * 64), hi = *(const LAS u32x2*)(vtp + d * 16 * RS + kc * 64 + 32);
;             u32x4 a4; a4.x = lo.x; a4.y = lo.y; a4.z = hi.x; a4.w = hi.y;
;             oacc[d] = MFMA16(__builtin_bit_cast(bf16x8, a4), pb, oacc[d]);
;         }
	v_mfma_f32_16x16x32_bf16 v[16:19], v[96:99], v[12:15], v[16:19]
	v_cndmask_b32_e32 v92, 0, v82, vcc
	v_fmac_f32_e32 v92, v79, v108
	v_exp_f32_e32 v92, v92
	v_cndmask_b32_e32 v94, 0, v86, vcc
	v_ldexp_f32 v92, v92, v94
	v_mul_f32_e32 v94, v93, v73
	v_cmp_gt_f32_e32 vcc, s7, v94
	v_cndmask_b32_e64 v92, 0, v92, s[0:1]
	s_nop 0
	v_cndmask_b32_e32 v94, 0, v82, vcc
	v_fmac_f32_e32 v94, v93, v73
	v_exp_f32_e32 v93, v94
	v_cndmask_b32_e32 v94, 0, v86, vcc
	v_cmp_gt_i32_e32 vcc, 1, v106
	v_ldexp_f32 v93, v93, v94
	v_or_b32_e32 v94, 49, v61
	v_sub_u32_e32 v94, v78, v94
	v_cvt_f32_u32_e32 v95, v94
	v_cndmask_b32_e32 v93, 0, v93, vcc
	v_add_f32_e32 v92, v92, v93
	v_mul_f32_e32 v92, v92, v16
	v_mul_f32_e32 v93, v79, v95
	v_cmp_gt_f32_e32 vcc, s7, v93
	v_cmp_lt_i32_e64 s[0:1], -1, v94
	s_nop 0
	v_cndmask_b32_e32 v93, 0, v82, vcc
	v_fmac_f32_e32 v93, v79, v95
	v_exp_f32_e32 v93, v93
	v_cvt_f32_i32_e32 v95, v94
	v_cndmask_b32_e32 v16, 0, v86, vcc
	v_ldexp_f32 v16, v93, v16
	v_mul_f32_e32 v93, v95, v73
	v_cmp_gt_f32_e32 vcc, s7, v93
	v_cndmask_b32_e64 v16, 0, v16, s[0:1]
	s_nop 0
	v_cndmask_b32_e32 v93, 0, v82, vcc
	v_fmac_f32_e32 v93, v95, v73
	v_exp_f32_e32 v93, v93
	v_cndmask_b32_e32 v95, 0, v86, vcc
	v_cmp_gt_i32_e32 vcc, 1, v94
	v_ldexp_f32 v93, v93, v95
	v_or_b32_e32 v95, 50, v61
	v_sub_u32_e32 v95, v78, v95
	v_cvt_f32_u32_e32 v96, v95
	v_cndmask_b32_e32 v93, 0, v93, vcc
	v_cvt_f32_i32_e32 v94, v95
	v_add_f32_e32 v16, v16, v93
	v_mul_f32_e32 v93, v79, v96
	v_cmp_gt_f32_e32 vcc, s7, v93
	v_cmp_lt_i32_e64 s[0:1], -1, v95
	s_nop 0
	v_cndmask_b32_e32 v93, 0, v82, vcc
	v_fmac_f32_e32 v93, v79, v96
	v_mul_f32_e32 v96, v16, v17
	v_mul_f32_e32 v17, v94, v73
	v_cndmask_b32_e32 v16, 0, v86, vcc
	v_cmp_gt_f32_e32 vcc, s7, v17
	v_exp_f32_e32 v93, v93
	s_nop 0
	v_cndmask_b32_e32 v17, 0, v82, vcc
	v_fmac_f32_e32 v17, v94, v73
	v_exp_f32_e32 v17, v17
	v_ldexp_f32 v16, v93, v16
	v_cndmask_b32_e32 v93, 0, v86, vcc
	v_cmp_gt_i32_e32 vcc, 1, v95
	v_ldexp_f32 v17, v17, v93
	v_or_b32_e32 v93, 51, v61
	v_sub_u32_e32 v93, v78, v93
	v_cvt_f32_u32_e32 v94, v93
	v_cndmask_b32_e64 v16, 0, v16, s[0:1]
	v_cndmask_b32_e32 v17, 0, v17, vcc
	v_add_f32_e32 v16, v16, v17
	v_mul_f32_e32 v17, v79, v94
	v_cmp_gt_f32_e32 vcc, s7, v17
	v_mul_f32_e32 v95, v16, v18
	v_cmp_lt_i32_e64 s[0:1], -1, v93
	v_cndmask_b32_e32 v17, 0, v82, vcc
	v_fmac_f32_e32 v17, v79, v94
	v_exp_f32_e32 v17, v17
	v_cvt_f32_i32_e32 v94, v93
	v_cndmask_b32_e32 v16, 0, v86, vcc
	v_ldexp_f32 v16, v17, v16
	v_mul_f32_e32 v17, v94, v73
	v_cmp_gt_f32_e32 vcc, s7, v17
	v_cndmask_b32_e64 v16, 0, v16, s[0:1]
	s_nop 0
	v_cndmask_b32_e32 v17, 0, v82, vcc
	v_fmac_f32_e32 v17, v94, v73
	v_exp_f32_e32 v17, v17
	v_cndmask_b32_e32 v18, 0, v86, vcc
	v_cmp_gt_i32_e32 vcc, 1, v93
	v_ldexp_f32 v17, v17, v18
	s_nop 0
	v_cndmask_b32_e32 v17, 0, v17, vcc
	v_add_f32_e32 v16, v16, v17
	v_mul_f32_e32 v19, v16, v19
	v_cvt_pk_bf16_f32 v16, v104, v105
	v_cvt_pk_bf16_f32 v17, v107, v109
	v_cvt_pk_bf16_f32 v18, v92, v96
	v_cvt_pk_bf16_f32 v19, v95, v19
	ds_read2_b64 v[52:55], v63 offset0:40 offset1:44
	ds_read2_b64 v[56:59], v64 offset0:72 offset1:76
	s_waitcnt lgkmcnt(1)
	v_mfma_f32_16x16x32_bf16 v[24:27], v[52:55], v[16:19], v[24:27]
	ds_read2_b64 v[52:55], v65 offset0:104 offset1:108
	ds_read2_b64 v[92:95], v60 offset0:8 offset1:12
	s_waitcnt lgkmcnt(2)
	v_mfma_f32_16x16x32_bf16 v[28:31], v[56:59], v[16:19], v[28:31]
	ds_read2_b64 v[56:59], v66 offset0:136 offset1:140
	s_waitcnt lgkmcnt(2)
	v_mfma_f32_16x16x32_bf16 v[32:35], v[52:55], v[16:19], v[32:35]
	ds_read2_b64 v[52:55], v67 offset0:168 offset1:172
	s_waitcnt lgkmcnt(1)
	v_mfma_f32_16x16x32_bf16 v[36:39], v[56:59], v[16:19], v[36:39]
	ds_read2_b64 v[56:59], v80 offset0:200 offset1:204
	s_waitcnt lgkmcnt(1)
	v_mfma_f32_16x16x32_bf16 v[40:43], v[52:55], v[16:19], v[40:43]
	ds_read_b128 v[52:55], v62 offset:17408
	s_waitcnt lgkmcnt(1)
	v_mfma_f32_16x16x32_bf16 v[44:47], v[56:59], v[16:19], v[44:47]
	ds_read_b128 v[56:59], v62 offset:17472
	s_waitcnt lgkmcnt(1)
	v_mfma_f32_16x16x32_bf16 v[52:55], v[52:55], v[0:3], 0
	v_mfma_f32_16x16x32_bf16 v[20:23], v[92:95], v[16:19], v[20:23]
	ds_read_b128 v[92:95], v62 offset:17536
	s_waitcnt lgkmcnt(1)
	v_mfma_f32_16x16x32_bf16 v[56:59], v[56:59], v[4:7], v[52:55]
	s_nop 3
	v_or_b32_e32 v52, 64, v61
	v_sub_u32_e32 v100, v78, v52
	v_cvt_f32_u32_e32 v101, v100
	s_waitcnt lgkmcnt(0)
	v_mfma_f32_16x16x32_bf16 v[56:59], v[92:95], v[8:11], v[56:59]
	v_cvt_f32_i32_e32 v93, v100
	v_cmp_lt_i32_e64 s[0:1], -1, v100
	v_mul_f32_e32 v92, v79, v101
	v_cmp_gt_f32_e32 vcc, s7, v92
	ds_read_b128 v[96:99], v62 offset:17600
	ds_read2_b64 v[52:55], v81 offset0:232 offset1:236
	v_cndmask_b32_e32 v92, 0, v82, vcc
	v_fmac_f32_e32 v92, v79, v101
	v_exp_f32_e32 v92, v92
	v_cndmask_b32_e32 v94, 0, v86, vcc
	s_waitcnt lgkmcnt(1)
	v_mfma_f32_16x16x32_bf16 v[56:59], v[96:99], v[12:15], v[56:59]
	v_ldexp_f32 v92, v92, v94
	v_mul_f32_e32 v94, v93, v73
	v_cmp_gt_f32_e32 vcc, s7, v94
	v_cndmask_b32_e64 v92, 0, v92, s[0:1]
	s_waitcnt lgkmcnt(0)
; #define LAS __attribute__((address_space(3)))
; DI unsigned cvt_pk_bf16(float lo, float hi) { unsigned r; asm volatile("v_cvt_pk_bf16_f32 %0, %1, %2" : "=v"(r) : "v"(lo), "v"(hi)); return r; }
; #define MFMA16(a, b, c) __builtin_amdgcn_mfma_f32_16x16x32_bf16((a), (b), (c), 0, 0, 0)
; DI void ret_out_item(const Params& p, int l, int b, int h, int c, LAS unsigned char* lds) {
;     ...
;     for (int kc = 0; kc < 4; ++kc) {
;         f32x4 s[2];
; #pragma unroll
;         for (int hf = 0; hf < 2; ++hf) {
;             s[hf] = (f32x4){0.f, 0.f, 0.f, 0.f};
; #pragma unroll
;             for (int ks = 0; ks < 4; ++ks) s[hf] = MFMA16(*(const LAS bf16x8*)(kcp + (2 * kc + hf) * 16 * RS + ks * 64), qf[ks], s[hf]);
; #pragma unroll
;             for (int j = 0; j < 4; ++j) {
;                 const int m = (2 * kc + hf) * 16 + q4 * 4 + j, d = tl - m;
;                 const float w = (d >= 0 ? exp2f(lgf * (float)d) : 0.f) + (d <= 0 ? exp2f(-lgb * (float)d) : 0.f);
;                 s[hf][j] *= w;
;             }
;         }
;         u32x4 w4; w4.x = cvt_pk_bf16(s[0][0], s[0][1]); w4.y = cvt_pk_bf16(s[0][2], s[0][3]); w4.z = cvt_pk_bf16(s[1][0], s[1][1]); w4.w = cvt_pk_bf16(s[1][2], s[1][3]);
;         const bf16x8 pb = __builtin_bit_cast(bf16x8, w4);
; #pragma unroll
;         for (int d = 0; d < 8; ++d) {
;             const u32x2 lo = *(const LAS u32x2*)(vtp + d * 16 * RS + kc * 64), hi = *(const LAS u32x2*)(vtp + d * 16 * RS + kc * 64 + 32);
;             u32x4 a4; a4.x = lo.x; a4.y = lo.y; a4.z = hi.x; a4.w = hi.y;
;             oacc[d] = MFMA16(__builtin_bit_cast(bf16x8, a4), pb, oacc[d]);
;         }
	v_mfma_f32_16x16x32_bf16 v[48:51], v[52:55], v[16:19], v[48:51]
	v_cndmask_b32_e32 v94, 0, v82, vcc
	v_fmac_f32_e32 v94, v93, v73
	v_exp_f32_e32 v93, v94
	v_cndmask_b32_e32 v94, 0, v86, vcc
	v_cmp_gt_i32_e32 vcc, 1, v100
	ds_read_b128 v[100:103], v62 offset:21888
	v_ldexp_f32 v93, v93, v94
	v_or_b32_e32 v94, 0x41, v61
	v_sub_u32_e32 v94, v78, v94
	v_cvt_f32_u32_e32 v95, v94
	v_cndmask_b32_e32 v93, 0, v93, vcc
	v_add_f32_e32 v92, v92, v93
	v_mul_f32_e32 v104, v92, v56
	v_mul_f32_e32 v93, v79, v95
	v_cmp_gt_f32_e32 vcc, s7, v93
	v_cmp_lt_i32_e64 s[0:1], -1, v94
	s_nop 0
	v_cndmask_b32_e32 v93, 0, v82, vcc
	v_fmac_f32_e32 v93, v79, v95
	v_cvt_f32_i32_e32 v95, v94
	v_cndmask_b32_e32 v56, 0, v86, vcc
	v_exp_f32_e32 v93, v93
	v_mul_f32_e32 v92, v95, v73
	v_cmp_gt_f32_e32 vcc, s7, v92
	v_ldexp_f32 v56, v93, v56
	v_cndmask_b32_e64 v56, 0, v56, s[0:1]
	v_cndmask_b32_e32 v92, 0, v82, vcc
	v_fmac_f32_e32 v92, v95, v73
	v_exp_f32_e32 v92, v92
	v_cndmask_b32_e32 v93, 0, v86, vcc
	v_cmp_gt_i32_e32 vcc, 1, v94
	v_ldexp_f32 v92, v92, v93
	v_or_b32_e32 v93, 0x42, v61
	v_sub_u32_e32 v93, v78, v93
	v_cvt_f32_u32_e32 v95, v93
	v_cvt_f32_i32_e32 v94, v93
	v_cndmask_b32_e32 v92, 0, v92, vcc
	v_add_f32_e32 v56, v56, v92
	v_mul_f32_e32 v92, v79, v95
	v_cmp_gt_f32_e32 vcc, s7, v92
	v_mul_f32_e32 v105, v56, v57
	v_mul_f32_e32 v57, v94, v73
	v_cndmask_b32_e32 v92, 0, v82, vcc
	v_cndmask_b32_e32 v56, 0, v86, vcc
	v_cmp_gt_f32_e32 vcc, s7, v57
	v_fmac_f32_e32 v92, v79, v95
	v_exp_f32_e32 v92, v92
	v_cndmask_b32_e32 v57, 0, v82, vcc
	v_fmac_f32_e32 v57, v94, v73
	v_exp_f32_e32 v57, v57
	v_ldexp_f32 v56, v92, v56
	v_cndmask_b32_e32 v92, 0, v86, vcc
	v_cmp_lt_i32_e64 s[0:1], -1, v93
	v_ldexp_f32 v57, v57, v92
	v_or_b32_e32 v92, 0x43, v61
	v_sub_u32_e32 v106, v78, v92
	v_cvt_f32_u32_e32 v92, v106
	v_cmp_gt_i32_e32 vcc, 1, v93
	v_cndmask_b32_e64 v56, 0, v56, s[0:1]
	v_cvt_f32_i32_e32 v96, v106
	v_cndmask_b32_e32 v57, 0, v57, vcc
	v_add_f32_e32 v56, v56, v57
	v_mul_f32_e32 v57, v79, v92
	v_cmp_gt_f32_e32 vcc, s7, v57
	v_mul_f32_e32 v107, v56, v58
	v_cmp_lt_i32_e64 s[0:1], -1, v106
	v_cndmask_b32_e32 v57, 0, v82, vcc
	v_fmac_f32_e32 v57, v79, v92
	v_exp_f32_e32 v57, v57
	v_cndmask_b32_e32 v56, 0, v86, vcc
	ds_read_b128 v[92:95], v62 offset:21760
	v_ldexp_f32 v56, v57, v56
	v_mul_f32_e32 v57, v96, v73
	v_cmp_gt_f32_e32 vcc, s7, v57
	v_cndmask_b32_e64 v56, 0, v56, s[0:1]
	s_nop 0
	v_cndmask_b32_e32 v57, 0, v82, vcc
	v_fmac_f32_e32 v57, v96, v73
	ds_read_b128 v[96:99], v62 offset:21824
	v_exp_f32_e32 v57, v57
	v_cndmask_b32_e32 v58, 0, v86, vcc
	s_waitcnt lgkmcnt(1)
	v_mfma_f32_16x16x32_bf16 v[92:95], v[92:95], v[0:3], 0
	v_cmp_gt_i32_e32 vcc, 1, v106
	v_ldexp_f32 v57, v57, v58
	s_nop 0
	v_cndmask_b32_e32 v57, 0, v57, vcc
	v_add_f32_e32 v56, v56, v57
	v_or_b32_e32 v57, 0x50, v61
	v_sub_u32_e32 v106, v78, v57
	s_waitcnt lgkmcnt(0)
	v_mfma_f32_16x16x32_bf16 v[92:95], v[96:99], v[4:7], v[92:95]
	v_cvt_f32_u32_e32 v108, v106
	ds_read_b128 v[96:99], v62 offset:21952
	v_mul_f32_e32 v109, v56, v59
	v_mfma_f32_16x16x32_bf16 v[56:59], v[100:103], v[8:11], v[92:95]
	v_cmp_lt_i32_e64 s[0:1], -1, v106
	s_nop 2
	v_mul_f32_e32 v92, v79, v108
	v_cmp_gt_f32_e32 vcc, s7, v92
	v_cvt_f32_i32_e32 v93, v106
	s_waitcnt lgkmcnt(0)
	v_mfma_f32_16x16x32_bf16 v[56:59], v[96:99], v[12:15], v[56:59]
	v_cndmask_b32_e32 v92, 0, v82, vcc
	v_fmac_f32_e32 v92, v79, v108
	v_exp_f32_e32 v92, v92
	v_cndmask_b32_e32 v94, 0, v86, vcc
	v_ldexp_f32 v92, v92, v94
	v_mul_f32_e32 v94, v93, v73
	v_cmp_gt_f32_e32 vcc, s7, v94
	v_cndmask_b32_e64 v92, 0, v92, s[0:1]
	s_nop 0
	v_cndmask_b32_e32 v94, 0, v82, vcc
	v_fmac_f32_e32 v94, v93, v73
	v_exp_f32_e32 v93, v94
	v_cndmask_b32_e32 v94, 0, v86, vcc
	v_cmp_gt_i32_e32 vcc, 1, v106
	v_ldexp_f32 v93, v93, v94
	v_or_b32_e32 v94, 0x51, v61
	v_sub_u32_e32 v94, v78, v94
	v_cvt_f32_u32_e32 v95, v94
	v_cndmask_b32_e32 v93, 0, v93, vcc
	v_add_f32_e32 v92, v92, v93
	v_mul_f32_e32 v92, v92, v56
	v_mul_f32_e32 v93, v79, v95
	v_cmp_gt_f32_e32 vcc, s7, v93
	v_cmp_lt_i32_e64 s[0:1], -1, v94
	s_nop 0
	v_cndmask_b32_e32 v93, 0, v82, vcc
	v_fmac_f32_e32 v93, v79, v95
	v_exp_f32_e32 v93, v93
	v_cvt_f32_i32_e32 v95, v94
	v_cndmask_b32_e32 v56, 0, v86, vcc
	v_ldexp_f32 v56, v93, v56
	v_mul_f32_e32 v93, v95, v73
	v_cmp_gt_f32_e32 vcc, s7, v93
	v_cndmask_b32_e64 v56, 0, v56, s[0:1]
	s_nop 0
	v_cndmask_b32_e32 v93, 0, v82, vcc
	v_fmac_f32_e32 v93, v95, v73
	v_exp_f32_e32 v93, v93
	v_cndmask_b32_e32 v95, 0, v86, vcc
	v_cmp_gt_i32_e32 vcc, 1, v94
	v_ldexp_f32 v93, v93, v95
	v_or_b32_e32 v95, 0x52, v61
	v_sub_u32_e32 v95, v78, v95
	v_cvt_f32_u32_e32 v96, v95
	v_cndmask_b32_e32 v93, 0, v93, vcc
	v_cvt_f32_i32_e32 v94, v95
	v_add_f32_e32 v56, v56, v93
	v_mul_f32_e32 v93, v79, v96
	v_cmp_gt_f32_e32 vcc, s7, v93
	v_cmp_lt_i32_e64 s[0:1], -1, v95
	s_nop 0
	v_cndmask_b32_e32 v93, 0, v82, vcc
	v_fmac_f32_e32 v93, v79, v96
	v_mul_f32_e32 v96, v56, v57
	v_mul_f32_e32 v57, v94, v73
	v_cndmask_b32_e32 v56, 0, v86, vcc
	v_cmp_gt_f32_e32 vcc, s7, v57
	v_exp_f32_e32 v93, v93
	s_nop 0
	v_cndmask_b32_e32 v57, 0, v82, vcc
	v_fmac_f32_e32 v57, v94, v73
	v_exp_f32_e32 v57, v57
	v_ldexp_f32 v56, v93, v56
	v_cndmask_b32_e32 v93, 0, v86, vcc
	v_cmp_gt_i32_e32 vcc, 1, v95
	v_ldexp_f32 v57, v57, v93
	v_or_b32_e32 v93, 0x53, v61
	v_sub_u32_e32 v93, v78, v93
	v_cvt_f32_u32_e32 v94, v93
	v_cndmask_b32_e64 v56, 0, v56, s[0:1]
	v_cndmask_b32_e32 v57, 0, v57, vcc
	v_add_f32_e32 v56, v56, v57
	v_mul_f32_e32 v57, v79, v94
	v_cmp_gt_f32_e32 vcc, s7, v57
	v_mul_f32_e32 v95, v56, v58
	v_cmp_lt_i32_e64 s[0:1], -1, v93
	v_cndmask_b32_e32 v57, 0, v82, vcc
	v_fmac_f32_e32 v57, v79, v94
	v_exp_f32_e32 v57, v57
	v_cvt_f32_i32_e32 v94, v93
	v_cndmask_b32_e32 v56, 0, v86, vcc
	v_ldexp_f32 v56, v57, v56
	v_mul_f32_e32 v57, v94, v73
	v_cmp_gt_f32_e32 vcc, s7, v57
	v_cndmask_b32_e64 v56, 0, v56, s[0:1]
	s_nop 0
	v_cndmask_b32_e32 v57, 0, v82, vcc
	v_fmac_f32_e32 v57, v94, v73
	v_exp_f32_e32 v57, v57
	v_cndmask_b32_e32 v58, 0, v86, vcc
	v_cmp_gt_i32_e32 vcc, 1, v93
	v_ldexp_f32 v57, v57, v58
	s_nop 0
	v_cndmask_b32_e32 v57, 0, v57, vcc
	v_add_f32_e32 v56, v56, v57
	v_mul_f32_e32 v59, v56, v59
	v_cvt_pk_bf16_f32 v56, v104, v105
	v_cvt_pk_bf16_f32 v57, v107, v109
	v_cvt_pk_bf16_f32 v58, v92, v96
	v_cvt_pk_bf16_f32 v59, v95, v59
	ds_read2_b64 v[92:95], v60 offset0:16 offset1:20
	ds_read2_b64 v[52:55], v63 offset0:48 offset1:52
	s_waitcnt lgkmcnt(1)
; #define LAS __attribute__((address_space(3)))
; DI unsigned cvt_pk_bf16(float lo, float hi) { unsigned r; asm volatile("v_cvt_pk_bf16_f32 %0, %1, %2" : "=v"(r) : "v"(lo), "v"(hi)); return r; }
; #define MFMA16(a, b, c) __builtin_amdgcn_mfma_f32_16x16x32_bf16((a), (b), (c), 0, 0, 0)
; DI void ret_out_item(const Params& p, int l, int b, int h, int c, LAS unsigned char* lds) {
;     ...
;     for (int kc = 0; kc < 4; ++kc) {
;         f32x4 s[2];
; #pragma unroll
;         for (int hf = 0; hf < 2; ++hf) {
;             s[hf] = (f32x4){0.f, 0.f, 0.f, 0.f};
; #pragma unroll
;             for (int ks = 0; ks < 4; ++ks) s[hf] = MFMA16(*(const LAS bf16x8*)(kcp + (2 * kc + hf) * 16 * RS + ks * 64), qf[ks], s[hf]);
; #pragma unroll
;             for (int j = 0; j < 4; ++j) {
;                 const int m = (2 * kc + hf) * 16 + q4 * 4 + j, d = tl - m;
;                 const float w = (d >= 0 ? exp2f(lgf * (float)d) : 0.f) + (d <= 0 ? exp2f(-lgb * (float)d) : 0.f);
;                 s[hf][j] *= w;
;             }
;         }
;         u32x4 w4; w4.x = cvt_pk_bf16(s[0][0], s[0][1]); w4.y = cvt_pk_bf16(s[0][2], s[0][3]); w4.z = cvt_pk_bf16(s[1][0], s[1][1]); w4.w = cvt_pk_bf16(s[1][2], s[1][3]);
;         const bf16x8 pb = __builtin_bit_cast(bf16x8, w4);
; #pragma unroll
;         for (int d = 0; d < 8; ++d) {
;             const u32x2 lo = *(const LAS u32x2*)(vtp + d * 16 * RS + kc * 64), hi = *(const LAS u32x2*)(vtp + d * 16 * RS + kc * 64 + 32);
;             u32x4 a4; a4.x = lo.x; a4.y = lo.y; a4.z = hi.x; a4.w = hi.y;
;             oacc[d] = MFMA16(__builtin_bit_cast(bf16x8, a4), pb, oacc[d]);
;         }
	v_mfma_f32_16x16x32_bf16 v[16:19], v[92:95], v[56:59], v[20:23]
	ds_read2_b64 v[92:95], v64 offset0:80 offset1:84
	s_waitcnt lgkmcnt(1)
	v_mfma_f32_16x16x32_bf16 v[20:23], v[52:55], v[56:59], v[24:27]
	ds_read2_b64 v[52:55], v66 offset0:144 offset1:148
	s_nop 1
	ds_read2_b64 v[24:27], v65 offset0:112 offset1:116
	s_waitcnt lgkmcnt(0)
	v_mfma_f32_16x16x32_bf16 v[32:35], v[24:27], v[56:59], v[32:35]
	ds_read2_b64 v[24:27], v67 offset0:176 offset1:180
	v_mfma_f32_16x16x32_bf16 v[36:39], v[52:55], v[56:59], v[36:39]
	ds_read2_b64 v[52:55], v80 offset0:208 offset1:212
	s_waitcnt lgkmcnt(1)
	v_mfma_f32_16x16x32_bf16 v[40:43], v[24:27], v[56:59], v[40:43]
	ds_read2_b64 v[24:27], v81 offset0:240 offset1:244
	s_waitcnt lgkmcnt(1)
	v_mfma_f32_16x16x32_bf16 v[44:47], v[52:55], v[56:59], v[44:47]
	ds_read_b128 v[52:55], v62 offset:26112
	s_waitcnt lgkmcnt(1)
	v_mfma_f32_16x16x32_bf16 v[48:51], v[24:27], v[56:59], v[48:51]
	ds_read_b128 v[24:27], v62 offset:26176
	s_waitcnt lgkmcnt(1)
	v_mfma_f32_16x16x32_bf16 v[52:55], v[52:55], v[0:3], 0
	v_mfma_f32_16x16x32_bf16 v[28:31], v[92:95], v[56:59], v[28:31]
	ds_read_b128 v[56:59], v62 offset:26240
	s_waitcnt lgkmcnt(1)
	v_mfma_f32_16x16x32_bf16 v[24:27], v[24:27], v[4:7], v[52:55]
	s_nop 3
	v_or_b32_e32 v52, 0x60, v61
	v_sub_u32_e32 v92, v78, v52
	ds_read_b128 v[52:55], v62 offset:26304
	v_cvt_f32_u32_e32 v93, v92
	s_waitcnt lgkmcnt(1)
	v_mfma_f32_16x16x32_bf16 v[24:27], v[56:59], v[8:11], v[24:27]
	v_cvt_f32_i32_e32 v57, v92
	v_cmp_lt_i32_e64 s[0:1], -1, v92
	v_mul_f32_e32 v56, v79, v93
	v_cmp_gt_f32_e32 vcc, s7, v56
	s_waitcnt lgkmcnt(0)
	v_mfma_f32_16x16x32_bf16 v[24:27], v[52:55], v[12:15], v[24:27]
	v_mul_f32_e32 v53, v57, v73
	v_cndmask_b32_e32 v56, 0, v82, vcc
	v_cndmask_b32_e32 v52, 0, v86, vcc
	v_cmp_gt_f32_e32 vcc, s7, v53
	v_fmac_f32_e32 v56, v79, v93
	v_exp_f32_e32 v56, v56
	v_cndmask_b32_e32 v53, 0, v82, vcc
	v_fmac_f32_e32 v53, v57, v73
	v_exp_f32_e32 v53, v53
	v_cndmask_b32_e32 v54, 0, v86, vcc
	v_ldexp_f32 v52, v56, v52
	v_cmp_gt_i32_e32 vcc, 1, v92
	v_ldexp_f32 v53, v53, v54
	v_or_b32_e32 v54, 0x61, v61
	v_sub_u32_e32 v54, v78, v54
	v_cvt_f32_u32_e32 v55, v54
	v_cndmask_b32_e64 v52, 0, v52, s[0:1]
	v_cndmask_b32_e32 v53, 0, v53, vcc
	v_add_f32_e32 v52, v52, v53
	v_mul_f32_e32 v53, v79, v55
	v_cmp_gt_f32_e32 vcc, s7, v53
	v_mul_f32_e32 v24, v52, v24
	v_cmp_lt_i32_e64 s[0:1], -1, v54
	v_cndmask_b32_e32 v53, 0, v82, vcc
	v_fmac_f32_e32 v53, v79, v55
	v_exp_f32_e32 v53, v53
	v_cvt_f32_i32_e32 v55, v54
	v_cndmask_b32_e32 v52, 0, v86, vcc
	v_ldexp_f32 v52, v53, v52
	v_mul_f32_e32 v53, v55, v73
	v_cmp_gt_f32_e32 vcc, s7, v53
	v_cndmask_b32_e64 v52, 0, v52, s[0:1]
	s_nop 0
	v_cndmask_b32_e32 v53, 0, v82, vcc
	v_fmac_f32_e32 v53, v55, v73
	v_exp_f32_e32 v53, v53
	v_cndmask_b32_e32 v55, 0, v86, vcc
	v_cmp_gt_i32_e32 vcc, 1, v54
	v_ldexp_f32 v53, v53, v55
	v_or_b32_e32 v55, 0x62, v61
	v_sub_u32_e32 v55, v78, v55
	v_cvt_f32_u32_e32 v56, v55
	v_cndmask_b32_e32 v53, 0, v53, vcc
	v_add_f32_e32 v52, v52, v53
	v_cvt_f32_i32_e32 v54, v55
	v_mul_f32_e32 v53, v79, v56
	v_cmp_gt_f32_e32 vcc, s7, v53
	v_mul_f32_e32 v25, v52, v25
	v_cmp_lt_i32_e64 s[0:1], -1, v55
	v_cndmask_b32_e32 v53, 0, v82, vcc
	v_fmac_f32_e32 v53, v79, v56
	v_exp_f32_e32 v53, v53
	v_cndmask_b32_e32 v52, 0, v86, vcc
	v_ldexp_f32 v52, v53, v52
	v_mul_f32_e32 v53, v54, v73
	v_cmp_gt_f32_e32 vcc, s7, v53
	v_cndmask_b32_e64 v52, 0, v52, s[0:1]
	s_nop 0
	v_cndmask_b32_e32 v53, 0, v82, vcc
	v_fmac_f32_e32 v53, v54, v73
	v_exp_f32_e32 v53, v53
	v_cndmask_b32_e32 v54, 0, v86, vcc
	v_cmp_gt_i32_e32 vcc, 1, v55
	v_ldexp_f32 v53, v53, v54
	v_or_b32_e32 v54, 0x63, v61
	v_sub_u32_e32 v92, v78, v54
	v_cvt_f32_u32_e32 v54, v92
	v_cndmask_b32_e32 v53, 0, v53, vcc
	v_add_f32_e32 v52, v52, v53
	v_cvt_f32_i32_e32 v56, v92
	v_mul_f32_e32 v53, v79, v54
	v_cmp_gt_f32_e32 vcc, s7, v53
	v_mul_f32_e32 v26, v52, v26
	v_mul_f32_e32 v57, v56, v73
	v_cndmask_b32_e32 v53, 0, v82, vcc
	v_fmac_f32_e32 v53, v79, v54
	v_exp_f32_e32 v53, v53
	v_cndmask_b32_e32 v52, 0, v86, vcc
	v_cmp_gt_f32_e32 vcc, s7, v57
	v_cmp_lt_i32_e64 s[0:1], -1, v92
	v_ldexp_f32 v93, v53, v52
	ds_read_b128 v[52:55], v62 offset:30464
	v_cndmask_b32_e32 v57, 0, v82, vcc
	v_fmac_f32_e32 v57, v56, v73
	v_exp_f32_e32 v94, v57
	ds_read_b128 v[56:59], v62 offset:30528
	s_waitcnt lgkmcnt(1)
	v_mfma_f32_16x16x32_bf16 v[0:3], v[52:55], v[0:3], 0
	ds_read_b128 v[52:55], v62 offset:30592
	v_cndmask_b32_e32 v95, 0, v86, vcc
	v_ldexp_f32 v94, v94, v95
	s_waitcnt lgkmcnt(1)
	v_mfma_f32_16x16x32_bf16 v[0:3], v[56:59], v[4:7], v[0:3]
	v_or_b32_e32 v4, 0x70, v61
	v_sub_u32_e32 v56, v78, v4
	ds_read_b128 v[4:7], v62 offset:30656
	v_cvt_f32_u32_e32 v57, v56
	s_waitcnt lgkmcnt(1)
	v_mfma_f32_16x16x32_bf16 v[0:3], v[52:55], v[8:11], v[0:3]
	v_cvt_f32_i32_e32 v9, v56
	v_cmp_gt_i32_e32 vcc, 1, v92
	v_mul_f32_e32 v8, v79, v57
	s_waitcnt lgkmcnt(0)
; #define LAS __attribute__((address_space(3)))
; DI unsigned cvt_pk_bf16(float lo, float hi) { unsigned r; asm volatile("v_cvt_pk_bf16_f32 %0, %1, %2" : "=v"(r) : "v"(lo), "v"(hi)); return r; }
; #define MFMA16(a, b, c) __builtin_amdgcn_mfma_f32_16x16x32_bf16((a), (b), (c), 0, 0, 0)
; DI void ret_out_item(const Params& p, int l, int b, int h, int c, LAS unsigned char* lds) {
;     ...
;     for (int kc = 0; kc < 4; ++kc) {
;         f32x4 s[2];
; #pragma unroll
;         for (int hf = 0; hf < 2; ++hf) {
;             s[hf] = (f32x4){0.f, 0.f, 0.f, 0.f};
; #pragma unroll
;             for (int ks = 0; ks < 4; ++ks) s[hf] = MFMA16(*(const LAS bf16x8*)(kcp + (2 * kc + hf) * 16 * RS + ks * 64), qf[ks], s[hf]);
; #pragma unroll
;             for (int j = 0; j < 4; ++j) {
;                 const int m = (2 * kc + hf) * 16 + q4 * 4 + j, d = tl - m;
;                 const float w = (d >= 0 ? exp2f(lgf * (float)d) : 0.f) + (d <= 0 ? exp2f(-lgb * (float)d) : 0.f);
;                 s[hf][j] *= w;
;             }
;         }
;         u32x4 w4; w4.x = cvt_pk_bf16(s[0][0], s[0][1]); w4.y = cvt_pk_bf16(s[0][2], s[0][3]); w4.z = cvt_pk_bf16(s[1][0], s[1][1]); w4.w = cvt_pk_bf16(s[1][2], s[1][3]);
;         const bf16x8 pb = __builtin_bit_cast(bf16x8, w4);
; #pragma unroll
;         for (int d = 0; d < 8; ++d) {
;             const u32x2 lo = *(const LAS u32x2*)(vtp + d * 16 * RS + kc * 64), hi = *(const LAS u32x2*)(vtp + d * 16 * RS + kc * 64 + 32);
;             u32x4 a4; a4.x = lo.x; a4.y = lo.y; a4.z = hi.x; a4.w = hi.y;
;             oacc[d] = MFMA16(__builtin_bit_cast(bf16x8, a4), pb, oacc[d]);
;         }
;     }
;     float sum = 0.f;
; #pragma unroll
;     for (int d = 0; d < 8; ++d) sum += oacc[d][0] + oacc[d][1] + oacc[d][2] + oacc[d][3];
;     sum += __shfl_xor(sum, 16); sum += __shfl_xor(sum, 32);
	v_mfma_f32_16x16x32_bf16 v[0:3], v[4:7], v[12:15], v[0:3]
	v_cndmask_b32_e32 v92, 0, v94, vcc
	v_cmp_gt_f32_e32 vcc, s7, v8
	v_mul_f32_e32 v5, v9, v73
	v_cndmask_b32_e64 v93, 0, v93, s[0:1]
	v_cndmask_b32_e32 v8, 0, v82, vcc
	v_cndmask_b32_e32 v4, 0, v86, vcc
	v_cmp_gt_f32_e32 vcc, s7, v5
	v_fmac_f32_e32 v8, v79, v57
	v_exp_f32_e32 v8, v8
	v_cndmask_b32_e32 v5, 0, v82, vcc
	v_fmac_f32_e32 v5, v9, v73
	v_exp_f32_e32 v5, v5
	v_cndmask_b32_e32 v6, 0, v86, vcc
	v_ldexp_f32 v4, v8, v4
	v_cmp_lt_i32_e64 s[0:1], -1, v56
	v_ldexp_f32 v5, v5, v6
	v_or_b32_e32 v6, 0x71, v61
	v_sub_u32_e32 v6, v78, v6
	v_cvt_f32_u32_e32 v7, v6
	v_cmp_gt_i32_e32 vcc, 1, v56
	v_cndmask_b32_e64 v4, 0, v4, s[0:1]
	v_cmp_lt_i32_e64 s[0:1], -1, v6
	v_cndmask_b32_e32 v5, 0, v5, vcc
	v_add_f32_e32 v4, v4, v5
	v_mul_f32_e32 v5, v79, v7
	v_cmp_gt_f32_e32 vcc, s7, v5
	v_mul_f32_e32 v4, v4, v0
	v_add_f32_e32 v92, v93, v92
	v_cndmask_b32_e32 v5, 0, v82, vcc
	v_fmac_f32_e32 v5, v79, v7
	v_exp_f32_e32 v5, v5
	v_cvt_f32_i32_e32 v7, v6
	v_cndmask_b32_e32 v0, 0, v86, vcc
	v_mul_f32_e32 v27, v92, v27
	v_ldexp_f32 v0, v5, v0
	v_mul_f32_e32 v5, v7, v73
	v_cmp_gt_f32_e32 vcc, s7, v5
	v_cndmask_b32_e64 v0, 0, v0, s[0:1]
	s_nop 0
	v_cndmask_b32_e32 v5, 0, v82, vcc
	v_fmac_f32_e32 v5, v7, v73
	v_exp_f32_e32 v5, v5
	v_cndmask_b32_e32 v7, 0, v86, vcc
	v_cmp_gt_i32_e32 vcc, 1, v6
	v_ldexp_f32 v5, v5, v7
	v_or_b32_e32 v7, 0x72, v61
	v_sub_u32_e32 v7, v78, v7
	v_cvt_f32_u32_e32 v8, v7
	v_cndmask_b32_e32 v5, 0, v5, vcc
	v_cvt_f32_i32_e32 v6, v7
	v_add_f32_e32 v0, v0, v5
	v_mul_f32_e32 v5, v79, v8
	v_cmp_gt_f32_e32 vcc, s7, v5
	v_cmp_lt_i32_e64 s[0:1], -1, v7
	s_nop 0
	v_cndmask_b32_e32 v5, 0, v82, vcc
	v_fmac_f32_e32 v5, v79, v8
	v_mul_f32_e32 v8, v0, v1
	v_mul_f32_e32 v1, v6, v73
	v_cndmask_b32_e32 v0, 0, v86, vcc
	v_cmp_gt_f32_e32 vcc, s7, v1
	v_exp_f32_e32 v5, v5
	s_nop 0
	v_cndmask_b32_e32 v1, 0, v82, vcc
	v_fmac_f32_e32 v1, v6, v73
	v_exp_f32_e32 v1, v1
	v_ldexp_f32 v0, v5, v0
	v_cndmask_b32_e32 v5, 0, v86, vcc
	v_cmp_gt_i32_e32 vcc, 1, v7
	v_ldexp_f32 v1, v1, v5
	v_or_b32_e32 v5, 0x73, v61
	v_sub_u32_e32 v5, v78, v5
	v_cvt_f32_u32_e32 v6, v5
	v_cndmask_b32_e64 v0, 0, v0, s[0:1]
	v_cndmask_b32_e32 v1, 0, v1, vcc
	v_add_f32_e32 v0, v0, v1
	v_mul_f32_e32 v1, v79, v6
	v_cmp_gt_f32_e32 vcc, s7, v1
	v_mul_f32_e32 v7, v0, v2
	v_cmp_lt_i32_e64 s[0:1], -1, v5
	v_cndmask_b32_e32 v1, 0, v82, vcc
	v_fmac_f32_e32 v1, v79, v6
	v_exp_f32_e32 v1, v1
	v_cvt_f32_i32_e32 v6, v5
	v_cndmask_b32_e32 v0, 0, v86, vcc
	v_ldexp_f32 v0, v1, v0
	v_mul_f32_e32 v1, v6, v73
	v_cmp_gt_f32_e32 vcc, s7, v1
	v_cndmask_b32_e64 v0, 0, v0, s[0:1]
	s_nop 0
	v_cndmask_b32_e32 v1, 0, v82, vcc
	v_fmac_f32_e32 v1, v6, v73
	v_exp_f32_e32 v1, v1
	v_cndmask_b32_e32 v2, 0, v86, vcc
	v_cmp_gt_i32_e32 vcc, 1, v5
	v_ldexp_f32 v1, v1, v2
	s_nop 0
	v_cndmask_b32_e32 v1, 0, v1, vcc
	v_add_f32_e32 v0, v0, v1
	v_mul_f32_e32 v3, v0, v3
	v_cvt_pk_bf16_f32 v0, v24, v25
	v_cvt_pk_bf16_f32 v1, v26, v27
	v_cvt_pk_bf16_f32 v2, v4, v8
	v_cvt_pk_bf16_f32 v3, v7, v3
	ds_read2_b64 v[4:7], v60 offset0:24 offset1:28
	s_waitcnt lgkmcnt(0)
	v_mfma_f32_16x16x32_bf16 v[52:55], v[4:7], v[0:3], v[16:19]
	ds_read2_b64 v[4:7], v63 offset0:56 offset1:60
	v_cmp_lt_i32_e32 vcc, v88, v89
	s_waitcnt lgkmcnt(0)
	v_mfma_f32_16x16x32_bf16 v[24:27], v[4:7], v[0:3], v[20:23]
	ds_read2_b64 v[4:7], v64 offset0:88 offset1:92
	s_waitcnt lgkmcnt(0)
	v_mfma_f32_16x16x32_bf16 v[20:23], v[4:7], v[0:3], v[28:31]
	ds_read2_b64 v[4:7], v65 offset0:120 offset1:124
	s_nop 1
	ds_read2_b64 v[28:31], v81 offset0:248 offset1:252
	s_waitcnt lgkmcnt(1)
	v_mfma_f32_16x16x32_bf16 v[16:19], v[4:7], v[0:3], v[32:35]
	ds_read2_b64 v[4:7], v66 offset0:152 offset1:156
	s_waitcnt lgkmcnt(0)
	v_mfma_f32_16x16x32_bf16 v[12:15], v[4:7], v[0:3], v[36:39]
	ds_read2_b64 v[4:7], v67 offset0:184 offset1:188
	s_waitcnt lgkmcnt(0)
	v_mfma_f32_16x16x32_bf16 v[8:11], v[4:7], v[0:3], v[40:43]
	ds_read2_b64 v[4:7], v80 offset0:216 offset1:220
	s_nop 1
	v_lshl_add_u64 v[42:43], v[76:77], 0, v[68:69]
	s_waitcnt lgkmcnt(0)
	v_mfma_f32_16x16x32_bf16 v[4:7], v[4:7], v[0:3], v[44:47]
	v_mfma_f32_16x16x32_bf16 v[0:3], v[28:31], v[0:3], v[48:51]
	v_mov_b32_e32 v28, v52
	v_mov_b32_e32 v29, v24
	v_mov_b32_e32 v30, v53
	v_mov_b32_e32 v31, v25
	v_pk_add_f32 v[28:29], v[28:29], v[30:31]
	v_mov_b32_e32 v30, v54
	v_mov_b32_e32 v31, v26
	v_pk_add_f32 v[28:29], v[30:31], v[28:29]
	v_mov_b32_e32 v30, v55
	v_mov_b32_e32 v31, v27
	v_pk_add_f32 v[28:29], v[30:31], v[28:29]
	v_mov_b32_e32 v30, v21
	v_add_f32_e32 v28, 0, v28
	v_add_f32_e32 v32, v28, v29
	v_mov_b32_e32 v28, v20
	v_mov_b32_e32 v29, v16
	v_mov_b32_e32 v31, v17
	v_pk_add_f32 v[28:29], v[28:29], v[30:31]
	v_mov_b32_e32 v30, v22
	v_mov_b32_e32 v31, v18
	v_pk_add_f32 v[28:29], v[30:31], v[28:29]
	v_mov_b32_e32 v30, v23
	v_mov_b32_e32 v31, v19
	v_pk_add_f32 v[28:29], v[30:31], v[28:29]
	v_mov_b32_e32 v30, v13
	v_add_f32_e32 v28, v32, v28
	v_add_f32_e32 v32, v28, v29
	v_mov_b32_e32 v28, v12
	v_mov_b32_e32 v29, v8
	v_mov_b32_e32 v31, v9
	v_pk_add_f32 v[28:29], v[28:29], v[30:31]
	v_mov_b32_e32 v30, v14
	v_mov_b32_e32 v31, v10
	v_pk_add_f32 v[28:29], v[30:31], v[28:29]
	v_mov_b32_e32 v30, v15
	v_mov_b32_e32 v31, v11
	v_pk_add_f32 v[28:29], v[30:31], v[28:29]
	v_mov_b32_e32 v30, v5
	v_add_f32_e32 v28, v32, v28
	v_add_f32_e32 v32, v28, v29
	v_mov_b32_e32 v28, v4
	v_mov_b32_e32 v29, v0
	v_mov_b32_e32 v31, v1
	v_pk_add_f32 v[28:29], v[28:29], v[30:31]
	v_mov_b32_e32 v30, v6
	v_mov_b32_e32 v31, v2
	v_pk_add_f32 v[28:29], v[30:31], v[28:29]
	v_mov_b32_e32 v30, v7
	v_mov_b32_e32 v31, v3
	v_pk_add_f32 v[28:29], v[30:31], v[28:29]
	s_nop 0
	v_add_f32_e32 v28, v32, v28
	v_add_f32_e32 v28, v28, v29
	v_cndmask_b32_e32 v29, v87, v88, vcc
	v_lshlrev_b32_e32 v50, 2, v29
	ds_bpermute_b32 v29, v50, v28
	v_cmp_lt_i32_e32 vcc, v90, v89
	s_waitcnt lgkmcnt(0)
; DI float silu(float v) { return v * __builtin_amdgcn_rcpf(1.f + __builtin_amdgcn_exp2f(-1.4426950408889634f * v)); }
; DI void st_bf16x4(bf16_t* p, f32x4 v) { u32x2 w; w.x = cvt_pk_bf16(v[0], v[1]); w.y = cvt_pk_bf16(v[2], v[3]); *(u32x2*)p = w; }
; DI void ret_out_item(const Params& p, int l, int b, int h, int c, LAS unsigned char* lds) {
;     ...
;     float sum = 0.f;
; #pragma unroll
;     for (int d = 0; d < 8; ++d) sum += oacc[d][0] + oacc[d][1] + oacc[d][2] + oacc[d][3];
;     sum += __shfl_xor(sum, 16); sum += __shfl_xor(sum, 32);
;     const float mu = sum * (1.f / 128.f);
;     float sq = 0.f;
; #pragma unroll
;     for (int d = 0; d < 8; ++d) { oacc[d] -= mu; sq += oacc[d][0] * oacc[d][0] + oacc[d][1] * oacc[d][1] + oacc[d][2] * oacc[d][2] + oacc[d][3] * oacc[d][3]; }
;     sq += __shfl_xor(sq, 16); sq += __shfl_xor(sq, 32);
;     const float rs = rsqrtf(sq * (1.f / 128.f) + 1e-5f);
;     const bf16_t* gp = P + row * INP + C_RG + h * 128 + q4 * 4;
;     bf16_t* op = (bf16_t*)(ws + WS_YMIX) + row * DM + 1408 + h * 128 + q4 * 4;
; #pragma unroll
;     for (int d = 0; d < 8; ++d) {
;         const u32x2 g2 = *(const u32x2*)(gp + d * 16);
;         f32x4 g; g[0] = __uint_as_float(g2.x << 16); g[1] = __uint_as_float(g2.x & 0xffff0000u); g[2] = __uint_as_float(g2.y << 16); g[3] = __uint_as_float(g2.y & 0xffff0000u);
;         f32x4 y;
; #pragma unroll
;         for (int j = 0; j < 4; ++j) y[j] = oacc[d][j] * rs * silu(g[j]);
;         st_bf16x4(op + d * 16, y);
	v_add_f32_e32 v28, v28, v29
	v_cndmask_b32_e32 v29, v87, v90, vcc
	v_lshlrev_b32_e32 v51, 2, v29
	ds_bpermute_b32 v29, v51, v28
	s_waitcnt lgkmcnt(0)
	v_add_f32_e32 v56, v28, v29
	v_add_co_u32_e32 v28, vcc, s37, v42
	v_fmamk_f32 v38, v56, 0xbc000000, v53
	s_nop 0
	v_addc_co_u32_e32 v29, vcc, 0, v43, vcc
	global_load_dwordx2 v[44:45], v[28:29], off offset:2432
	global_load_dwordx2 v[140:141], v[28:29], off offset:2464
	global_load_dwordx2 v[142:143], v[28:29], off offset:2496
	global_load_dwordx2 v[144:145], v[28:29], off offset:2528
	global_load_dwordx2 v[146:147], v[28:29], off offset:2560
	global_load_dwordx2 v[148:149], v[28:29], off offset:2592
	global_load_dwordx2 v[150:151], v[28:29], off offset:2624
	global_load_dwordx2 v[152:153], v[28:29], off offset:2656
	v_fmamk_f32 v39, v56, 0xbc000000, v25
	v_fmac_f32_e32 v24, 0xbc000000, v56
	v_fmac_f32_e32 v52, 0xbc000000, v56
	v_fmamk_f32 v31, v56, 0xbc000000, v27
	v_fmamk_f32 v35, v56, 0xbc000000, v26
	v_mov_b32_e32 v53, v24
	v_pk_mul_f32 v[26:27], v[38:39], v[38:39]
	v_fmamk_f32 v34, v56, 0xbc000000, v54
	v_pk_fma_f32 v[26:27], v[52:53], v[52:53], v[26:27]
	v_fmamk_f32 v30, v56, 0xbc000000, v55
	v_pk_fma_f32 v[26:27], v[34:35], v[34:35], v[26:27]
	v_fmamk_f32 v29, v56, 0xbc000000, v13
	v_fmac_f32_e32 v12, 0xbc000000, v56
	v_fmamk_f32 v28, v56, 0xbc000000, v9
	v_pk_fma_f32 v[46:47], v[30:31], v[30:31], v[26:27]
	v_fmamk_f32 v37, v56, 0xbc000000, v22
	v_fmamk_f32 v41, v56, 0xbc000000, v21
	v_fmac_f32_e32 v20, 0xbc000000, v56
	v_fmamk_f32 v40, v56, 0xbc000000, v17
	v_fmamk_f32 v22, v56, 0xbc000000, v11
	v_fmamk_f32 v26, v56, 0xbc000000, v10
	v_fmac_f32_e32 v8, 0xbc000000, v56
	v_mov_b32_e32 v9, v12
	v_pk_mul_f32 v[10:11], v[28:29], v[28:29]
	v_fmamk_f32 v32, v56, 0xbc000000, v19
	v_fmamk_f32 v36, v56, 0xbc000000, v18
	v_fmac_f32_e32 v16, 0xbc000000, v56
	v_mov_b32_e32 v17, v20
	v_pk_mul_f32 v[18:19], v[40:41], v[40:41]
	v_fmamk_f32 v27, v56, 0xbc000000, v14
	v_pk_fma_f32 v[10:11], v[8:9], v[8:9], v[10:11]
	v_fmamk_f32 v33, v56, 0xbc000000, v23
	v_pk_fma_f32 v[18:19], v[16:17], v[16:17], v[18:19]
	v_fmamk_f32 v23, v56, 0xbc000000, v15
	v_pk_fma_f32 v[10:11], v[26:27], v[26:27], v[10:11]
	v_fmamk_f32 v15, v56, 0xbc000000, v5
	v_fmac_f32_e32 v4, 0xbc000000, v56
	v_fmamk_f32 v14, v56, 0xbc000000, v1
	v_pk_fma_f32 v[18:19], v[36:37], v[36:37], v[18:19]
	v_pk_fma_f32 v[48:49], v[22:23], v[22:23], v[10:11]
	v_fmamk_f32 v11, v56, 0xbc000000, v6
	v_fmamk_f32 v6, v56, 0xbc000000, v3
	v_fmamk_f32 v10, v56, 0xbc000000, v2
	v_fmac_f32_e32 v0, 0xbc000000, v56
	v_mov_b32_e32 v1, v4
	v_pk_mul_f32 v[2:3], v[14:15], v[14:15]
	v_pk_fma_f32 v[18:19], v[32:33], v[32:33], v[18:19]
	v_pk_fma_f32 v[2:3], v[0:1], v[0:1], v[2:3]
	v_add_f32_e32 v1, v46, v47
	v_add_f32_e32 v1, v19, v1
	v_add_f32_e32 v1, v18, v1
	v_fmamk_f32 v7, v56, 0xbc000000, v7
	v_pk_fma_f32 v[2:3], v[10:11], v[10:11], v[2:3]
	v_add_f32_e32 v1, v49, v1
	v_pk_fma_f32 v[2:3], v[6:7], v[6:7], v[2:3]
	v_add_f32_e32 v1, v48, v1
	v_add_f32_e32 v1, v3, v1
	v_add_f32_e32 v1, v2, v1
	ds_bpermute_b32 v2, v50, v1
	v_lshl_add_u64 v[18:19], v[42:43], 0, s[10:11]
	v_mov_b32_e32 v49, v52
	s_waitcnt lgkmcnt(0)
	v_add_f32_e32 v1, v1, v2
	ds_bpermute_b32 v2, v51, v1
	v_mov_b32_e32 v51, v24
	s_waitcnt lgkmcnt(0)
	v_add_f32_e32 v1, v1, v2
	v_fmamk_f32 v1, v1, 0x3c000000, v91
	v_mul_f32_e32 v2, 0x4b800000, v1
	v_cmp_gt_f32_e32 vcc, s36, v1
	s_waitcnt vmcnt(7)
	v_and_b32_e32 v42, 0xffff0000, v44
	v_cndmask_b32_e32 v1, v1, v2, vcc
	v_rsq_f32_e32 v1, v1
	v_and_b32_e32 v46, 0xffff0000, v45
	v_mul_f32_e32 v2, 0x45800000, v1
	v_cndmask_b32_e32 v3, v1, v2, vcc
	v_lshlrev_b32_e32 v2, 16, v44
	v_mul_f32_e32 v1, 0xbfb8aa3b, v2
	v_exp_f32_e32 v1, v1
	v_lshlrev_b32_e32 v44, 16, v45
	v_mov_b32_e32 v43, v3
	v_mov_b32_e32 v45, v3
	v_add_f32_e32 v1, 1.0, v1
	v_rcp_f32_e32 v48, v1
	v_mul_f32_e32 v1, 0xbfb8aa3b, v42
	v_exp_f32_e32 v1, v1
	v_mov_b32_e32 v47, v3
	v_pk_mul_f32 v[48:49], v[48:49], v[2:3]
	v_add_f32_e32 v1, 1.0, v1
	v_mul_f32_e32 v2, v48, v49
	v_rcp_f32_e32 v48, v1
	v_mul_f32_e32 v1, 0xbfb8aa3b, v44
	v_exp_f32_e32 v1, v1
	v_mov_b32_e32 v49, v38
	v_pk_mul_f32 v[42:43], v[48:49], v[42:43]
	v_add_f32_e32 v1, 1.0, v1
	v_mul_f32_e32 v5, v42, v43
	v_rcp_f32_e32 v42, v1
	v_mul_f32_e32 v1, 0xbfb8aa3b, v46
	v_exp_f32_e32 v1, v1
	v_mov_b32_e32 v43, v34
	v_pk_mul_f32 v[42:43], v[42:43], v[44:45]
	v_mov_b32_e32 v45, v30
	v_add_f32_e32 v1, 1.0, v1
	v_rcp_f32_e32 v44, v1
	v_mul_f32_e32 v1, v42, v43
	v_pk_mul_f32 v[42:43], v[44:45], v[46:47]
	s_nop 0
	v_mul_f32_e32 v9, v42, v43
	v_cvt_pk_bf16_f32 v42, v2, v5
	v_cvt_pk_bf16_f32 v43, v1, v9
	s_waitcnt vmcnt(6)
	v_mov_b32_e32 v44, v140
	v_mov_b32_e32 v45, v141
	v_lshlrev_b64 v[46:47], 12, v[74:75]
	v_lshl_add_u64 v[46:47], s[50:51], 0, v[46:47]
	v_lshl_add_u64 v[46:47], v[46:47], 0, s[14:15]
	v_lshl_add_u64 v[46:47], v[46:47], 0, v[68:69]
	v_add_co_u32_e32 v48, vcc, s54, v46
	v_lshlrev_b32_e32 v2, 16, v44
	v_mul_f32_e32 v1, 0xbfb8aa3b, v2
	v_exp_f32_e32 v1, v1
	v_addc_co_u32_e32 v49, vcc, 0, v47, vcc
	global_store_dwordx2 v[48:49], v[42:43], off offset:2816
	v_add_f32_e32 v1, 1.0, v1
	v_rcp_f32_e32 v50, v1
	v_and_b32_e32 v42, 0xffff0000, v44
	v_lshlrev_b32_e32 v44, 16, v45
	v_mul_f32_e32 v5, 0xbfb8aa3b, v42
	v_and_b32_e32 v48, 0xffff0000, v45
	v_exp_f32_e32 v5, v5
	v_pk_mul_f32 v[24:25], v[50:51], v[2:3]
	v_mul_f32_e32 v2, 0xbfb8aa3b, v44
	v_exp_f32_e32 v2, v2
	v_mul_f32_e32 v9, 0xbfb8aa3b, v48
	v_exp_f32_e32 v9, v9
	v_add_f32_e32 v1, 1.0, v5
	v_rcp_f32_e32 v38, v1
	v_add_f32_e32 v2, 1.0, v2
	v_rcp_f32_e32 v34, v2
	v_add_f32_e32 v2, 1.0, v9
	v_rcp_f32_e32 v30, v2
	v_mov_b32_e32 v43, v3
	v_mul_f32_e32 v1, v24, v25
	v_pk_mul_f32 v[24:25], v[38:39], v[42:43]
	v_mov_b32_e32 v45, v3
	v_mul_f32_e32 v5, v24, v25
	v_pk_mul_f32 v[24:25], v[34:35], v[44:45]
	v_mov_b32_e32 v49, v3
	v_mul_f32_e32 v2, v24, v25
	v_pk_mul_f32 v[24:25], v[30:31], v[48:49]
	v_cvt_pk_bf16_f32 v30, v1, v5
	v_mov_b32_e32 v43, v20
	v_mul_f32_e32 v9, v24, v25
	v_cvt_pk_bf16_f32 v31, v2, v9
	s_waitcnt vmcnt(6)
; DI float silu(float v) { return v * __builtin_amdgcn_rcpf(1.f + __builtin_amdgcn_exp2f(-1.4426950408889634f * v)); }
; DI void st_bf16x4(bf16_t* p, f32x4 v) { u32x2 w; w.x = cvt_pk_bf16(v[0], v[1]); w.y = cvt_pk_bf16(v[2], v[3]); *(u32x2*)p = w; }
; DI void ret_out_item(const Params& p, int l, int b, int h, int c, LAS unsigned char* lds) {
;     ...
;     const bf16_t* gp = P + row * INP + C_RG + h * 128 + q4 * 4;
;     bf16_t* op = (bf16_t*)(ws + WS_YMIX) + row * DM + 1408 + h * 128 + q4 * 4;
; #pragma unroll
;     for (int d = 0; d < 8; ++d) {
;         const u32x2 g2 = *(const u32x2*)(gp + d * 16);
;         f32x4 g; g[0] = __uint_as_float(g2.x << 16); g[1] = __uint_as_float(g2.x & 0xffff0000u); g[2] = __uint_as_float(g2.y << 16); g[3] = __uint_as_float(g2.y & 0xffff0000u);
;         f32x4 y;
; #pragma unroll
;         for (int j = 0; j < 4; ++j) y[j] = oacc[d][j] * rs * silu(g[j]);
;         st_bf16x4(op + d * 16, y);
;     }
	v_mov_b32_e32 v34, v142
	v_mov_b32_e32 v35, v143
	v_lshl_add_u64 v[24:25], v[46:47], 0, s[12:13]
	global_store_dwordx2 v[24:25], v[30:31], off offset:32
	v_mov_b32_e32 v31, v3
	v_mov_b32_e32 v39, v3
	v_lshlrev_b32_e32 v2, 16, v34
	v_mul_f32_e32 v1, 0xbfb8aa3b, v2
	v_exp_f32_e32 v1, v1
	v_and_b32_e32 v30, 0xffff0000, v34
	v_lshlrev_b32_e32 v34, 16, v35
	v_and_b32_e32 v38, 0xffff0000, v35
	v_add_f32_e32 v1, 1.0, v1
	v_rcp_f32_e32 v42, v1
	v_mul_f32_e32 v1, 0xbfb8aa3b, v30
	v_exp_f32_e32 v1, v1
	v_mov_b32_e32 v35, v3
	v_pk_mul_f32 v[20:21], v[42:43], v[2:3]
	v_add_f32_e32 v1, 1.0, v1
	v_mul_f32_e32 v2, v20, v21
	v_rcp_f32_e32 v20, v1
	v_mul_f32_e32 v1, 0xbfb8aa3b, v34
	v_exp_f32_e32 v1, v1
	v_mov_b32_e32 v21, v41
	v_pk_mul_f32 v[20:21], v[20:21], v[30:31]
	v_mov_b32_e32 v31, v33
	v_add_f32_e32 v1, 1.0, v1
	v_mul_f32_e32 v5, v20, v21
	v_rcp_f32_e32 v20, v1
	v_mul_f32_e32 v1, 0xbfb8aa3b, v38
	v_exp_f32_e32 v1, v1
	v_mov_b32_e32 v21, v37
	v_pk_mul_f32 v[20:21], v[20:21], v[34:35]
	v_mov_b32_e32 v33, v12
	v_add_f32_e32 v1, 1.0, v1
	v_rcp_f32_e32 v30, v1
	v_mul_f32_e32 v1, v20, v21
	v_pk_mul_f32 v[20:21], v[30:31], v[38:39]
	s_nop 0
	v_mul_f32_e32 v9, v20, v21
	v_cvt_pk_bf16_f32 v20, v2, v5
	v_cvt_pk_bf16_f32 v21, v1, v9
	s_waitcnt vmcnt(6)
	v_mov_b32_e32 v30, v144
	v_mov_b32_e32 v31, v145
	v_mov_b32_e32 v39, v16
	global_store_dwordx2 v[24:25], v[20:21], off offset:64
	v_mov_b32_e32 v21, v3
	v_lshlrev_b32_e32 v2, 16, v30
	v_mul_f32_e32 v1, 0xbfb8aa3b, v2
	v_exp_f32_e32 v1, v1
	v_and_b32_e32 v20, 0xffff0000, v30
	v_lshlrev_b32_e32 v30, 16, v31
	v_and_b32_e32 v34, 0xffff0000, v31
	v_add_f32_e32 v1, 1.0, v1
	v_rcp_f32_e32 v38, v1
	v_mul_f32_e32 v1, 0xbfb8aa3b, v20
	v_exp_f32_e32 v1, v1
	v_mov_b32_e32 v31, v3
	v_pk_mul_f32 v[16:17], v[38:39], v[2:3]
	v_add_f32_e32 v1, 1.0, v1
	v_mul_f32_e32 v2, v16, v17
	v_rcp_f32_e32 v16, v1
	v_mul_f32_e32 v1, 0xbfb8aa3b, v30
	v_exp_f32_e32 v1, v1
	v_mov_b32_e32 v17, v40
	v_pk_mul_f32 v[16:17], v[16:17], v[20:21]
	v_mov_b32_e32 v21, v32
	v_add_f32_e32 v1, 1.0, v1
	v_mul_f32_e32 v5, v16, v17
	v_rcp_f32_e32 v16, v1
	v_mul_f32_e32 v1, 0xbfb8aa3b, v34
	v_exp_f32_e32 v1, v1
	v_mov_b32_e32 v17, v36
	v_pk_mul_f32 v[16:17], v[16:17], v[30:31]
	v_add_f32_e32 v1, 1.0, v1
	v_rcp_f32_e32 v20, v1
	v_mul_f32_e32 v1, v16, v17
	v_pk_mul_f32 v[16:17], v[20:21], v[34:35]
	s_nop 0
	v_mul_f32_e32 v9, v16, v17
	v_cvt_pk_bf16_f32 v16, v2, v5
	v_cvt_pk_bf16_f32 v17, v1, v9
	s_waitcnt vmcnt(6)
	v_mov_b32_e32 v20, v146
	v_mov_b32_e32 v21, v147
	v_lshlrev_b32_e32 v2, 16, v20
	v_mul_f32_e32 v1, 0xbfb8aa3b, v2
	v_exp_f32_e32 v1, v1
	global_store_dwordx2 v[24:25], v[16:17], off offset:96
	v_and_b32_e32 v16, 0xffff0000, v20
	v_lshlrev_b32_e32 v20, 16, v21
	v_add_f32_e32 v1, 1.0, v1
	v_rcp_f32_e32 v32, v1
	v_mul_f32_e32 v1, 0xbfb8aa3b, v16
	v_exp_f32_e32 v1, v1
	v_mov_b32_e32 v17, v3
	v_pk_mul_f32 v[12:13], v[32:33], v[2:3]
	v_and_b32_e32 v30, 0xffff0000, v21
	v_add_f32_e32 v1, 1.0, v1
	v_mul_f32_e32 v2, v12, v13
	v_rcp_f32_e32 v12, v1
	v_mul_f32_e32 v1, 0xbfb8aa3b, v20
	v_exp_f32_e32 v1, v1
	v_mov_b32_e32 v13, v29
	v_pk_mul_f32 v[12:13], v[12:13], v[16:17]
	v_mov_b32_e32 v21, v3
	v_add_f32_e32 v1, 1.0, v1
	v_mul_f32_e32 v5, v12, v13
	v_rcp_f32_e32 v12, v1
	v_mul_f32_e32 v1, 0xbfb8aa3b, v30
	v_exp_f32_e32 v1, v1
	v_mov_b32_e32 v13, v27
	v_pk_mul_f32 v[12:13], v[12:13], v[20:21]
	v_mov_b32_e32 v17, v23
	v_add_f32_e32 v1, 1.0, v1
	v_rcp_f32_e32 v16, v1
	v_mul_f32_e32 v1, v12, v13
	v_mov_b32_e32 v20, v3
	v_pk_mul_f32 v[12:13], v[16:17], v[30:31]
	s_nop 0
	v_mul_f32_e32 v9, v12, v13
	v_cvt_pk_bf16_f32 v12, v2, v5
	v_cvt_pk_bf16_f32 v13, v1, v9
	s_waitcnt vmcnt(6)
	v_mov_b32_e32 v16, v148
	v_mov_b32_e32 v17, v149
	v_mov_b32_e32 v30, v3
	global_store_dwordx2 v[24:25], v[12:13], off offset:128
	v_mov_b32_e32 v12, v3
	v_lshlrev_b32_e32 v13, 16, v16
	v_and_b32_e32 v21, 0xffff0000, v16
	v_mul_f32_e32 v1, 0xbfb8aa3b, v13
	v_exp_f32_e32 v1, v1
	v_mul_f32_e32 v2, 0xbfb8aa3b, v21
	v_exp_f32_e32 v2, v2
	v_lshlrev_b32_e32 v31, 16, v17
	v_add_f32_e32 v1, 1.0, v1
	v_rcp_f32_e32 v9, v1
	v_add_f32_e32 v1, 1.0, v2
	v_rcp_f32_e32 v29, v1
	v_and_b32_e32 v17, 0xffff0000, v17
	v_pk_mul_f32 v[8:9], v[8:9], v[12:13]
	v_mul_f32_e32 v2, 0xbfb8aa3b, v31
	v_mul_f32_e32 v1, v8, v9
	v_pk_mul_f32 v[8:9], v[28:29], v[20:21]
	v_exp_f32_e32 v2, v2
	v_mul_f32_e32 v5, v8, v9
	v_mul_f32_e32 v8, 0xbfb8aa3b, v17
	v_exp_f32_e32 v8, v8
	v_add_f32_e32 v2, 1.0, v2
	v_rcp_f32_e32 v27, v2
	v_mov_b32_e32 v16, v3
	v_add_f32_e32 v2, 1.0, v8
	v_rcp_f32_e32 v23, v2
	v_pk_mul_f32 v[8:9], v[26:27], v[30:31]
	s_nop 0
	v_mul_f32_e32 v2, v8, v9
	v_pk_mul_f32 v[8:9], v[22:23], v[16:17]
	s_nop 0
	v_mul_f32_e32 v9, v8, v9
	v_cvt_pk_bf16_f32 v8, v1, v5
	v_cvt_pk_bf16_f32 v9, v2, v9
	s_waitcnt vmcnt(6)
	v_mov_b32_e32 v12, v150
	v_mov_b32_e32 v13, v151
	v_and_b32_e32 v17, 0xffff0000, v12
	global_store_dwordx2 v[24:25], v[8:9], off offset:160
	v_lshlrev_b32_e32 v9, 16, v12
	v_mul_f32_e32 v1, 0xbfb8aa3b, v9
	v_exp_f32_e32 v1, v1
	v_mov_b32_e32 v8, v3
	v_lshlrev_b32_e32 v21, 16, v13
	v_and_b32_e32 v13, 0xffff0000, v13
	v_add_f32_e32 v1, 1.0, v1
	v_rcp_f32_e32 v5, v1
	v_mul_f32_e32 v1, 0xbfb8aa3b, v17
	v_exp_f32_e32 v1, v1
	v_mov_b32_e32 v12, v3
	v_pk_mul_f32 v[4:5], v[4:5], v[8:9]
	v_mov_b32_e32 v8, v7
	v_add_f32_e32 v1, 1.0, v1
	v_mul_f32_e32 v2, v4, v5
	v_rcp_f32_e32 v5, v1
	v_mul_f32_e32 v1, 0xbfb8aa3b, v21
	v_exp_f32_e32 v1, v1
	v_mov_b32_e32 v4, v15
	v_pk_mul_f32 v[4:5], v[4:5], v[16:17]
	v_add_f32_e32 v1, 1.0, v1
	v_mul_f32_e32 v15, v4, v5
	v_rcp_f32_e32 v5, v1
	v_mul_f32_e32 v1, 0xbfb8aa3b, v13
	v_exp_f32_e32 v1, v1
	v_mov_b32_e32 v4, v11
	v_pk_mul_f32 v[4:5], v[4:5], v[20:21]
	v_add_f32_e32 v1, 1.0, v1
	v_rcp_f32_e32 v9, v1
	v_mul_f32_e32 v1, v4, v5
	v_pk_mul_f32 v[4:5], v[8:9], v[12:13]
	s_nop 0
	v_mul_f32_e32 v5, v4, v5
	v_cvt_pk_bf16_f32 v4, v2, v15
	v_cvt_pk_bf16_f32 v5, v1, v5
	s_waitcnt vmcnt(6)
	v_mov_b32_e32 v8, v152
	v_mov_b32_e32 v9, v153
	v_and_b32_e32 v13, 0xffff0000, v8
	global_store_dwordx2 v[24:25], v[4:5], off offset:192
	v_lshlrev_b32_e32 v5, 16, v8
	v_mul_f32_e32 v1, 0xbfb8aa3b, v5
	v_exp_f32_e32 v1, v1
	v_mul_f32_e32 v2, 0xbfb8aa3b, v13
	v_exp_f32_e32 v2, v2
	v_mov_b32_e32 v4, v3
	v_add_f32_e32 v1, 1.0, v1
	v_rcp_f32_e32 v1, v1
	v_add_f32_e32 v2, 1.0, v2
	v_rcp_f32_e32 v15, v2
	v_lshlrev_b32_e32 v17, 16, v9
	v_pk_mul_f32 v[0:1], v[0:1], v[4:5]
	v_and_b32_e32 v9, 0xffff0000, v9
	v_mul_f32_e32 v2, v0, v1
	v_pk_mul_f32 v[0:1], v[14:15], v[12:13]
	v_mul_f32_e32 v4, 0xbfb8aa3b, v17
	v_exp_f32_e32 v4, v4
	v_mul_f32_e32 v5, v0, v1
	v_mul_f32_e32 v0, 0xbfb8aa3b, v9
	v_exp_f32_e32 v0, v0
	v_add_f32_e32 v1, 1.0, v4
	v_rcp_f32_e32 v11, v1
	v_mov_b32_e32 v8, v3
	v_add_f32_e32 v0, 1.0, v0
	v_rcp_f32_e32 v7, v0
	v_pk_mul_f32 v[0:1], v[10:11], v[16:17]
	s_nop 0
	v_mul_f32_e32 v4, v0, v1
	v_pk_mul_f32 v[0:1], v[6:7], v[8:9]
	s_nop 0
	v_mul_f32_e32 v1, v0, v1
	v_cvt_pk_bf16_f32 v0, v2, v5
	v_cvt_pk_bf16_f32 v1, v4, v1
	global_store_dwordx2 v[24:25], v[0:1], off offset:224
	s_barrier
; #define LAS __attribute__((address_space(3)))
; #define MFMA16(a, b, c) __builtin_amdgcn_mfma_f32_16x16x32_bf16((a), (b), (c), 0, 0, 0)
; DI void na_block_item(const Params& p, int l, int b, int h, int rp, LAS unsigned char* lds) {
;     ...
;     constexpr int KROW = 272, KTILE = 64 * KROW, VROW = 144, VTILE = 128 * VROW;
;     const int gr = 2 * rp + (wid >> 2), jq = wid & 3;
;     const int gc = jq * 16 + r16, r0w = min(max(gr - 4, 0), 24), band = min(max(jq * 16 - 8, 0), 32), cs = min(max(gc - 8, 0), 48);
;     const int r0a = min(max(2 * rp - 4, 0), 24), r0b = min(max(2 * rp - 3, 0), 24), nloc = r0b + 8 - r0a, ntl = nloc + 4;
;     const size_t rowb = (size_t)b * RB, rowq = rowb + CL + gr * 64 + gc;
;     const float sl2 = 0.08838834764831845f * 1.4426950408889634f;
;     const float* rpb = p.in[11] + (size_t)(l * 6 + h) * 15 * 31;
;     bf16x8 qf[4];
; #pragma unroll
;     for (int ks = 0; ks < 4; ++ks) qf[ks] = *(const bf16x8*)(P + rowq * INP + C_NAQ + h * 128 + ks * 32 + q4 * 8);
;     f32x4 oacc[8];
; #pragma unroll
;     for (int d = 0; d < 8; ++d) oacc[d] = (f32x4){0.f, 0.f, 0.f, 0.f};
;     float mrun = -1e30f, lsum = 0.f;
;     const bf16_t* kg = P + rowb * INP + C_NAK + h * 128;
;     const bf16_t* vg = (const bf16_t*)(ws + WS_VTNA) + ((size_t)b * 768 + h * 128) * RB;
;     u32x4 kstA[2], vstA[2], kstB[2], vstB[2];
;     ...
;             float bias8[8];
;             if (local) {
;                 const LAS float* rp_ = s_rpb + (kr - gr + 7) * 31;
; #pragma unroll
;                 for (int e = 0; e < 8; ++e) { const int kcol = band + (e >> 2) * 16 + q4 * 4 + (e & 3); bias8[e] = rp_[min(max(kcol - gc + 15, 0), 30)]; }
;             }
;             f32x4 s[2];
; #pragma unroll
;             for (int hf = 0; hf < 2; ++hf) {
;                 s[hf] = (f32x4){0.f, 0.f, 0.f, 0.f};
; #pragma unroll
;                 for (int ks = 0; ks < 4; ++ks) s[hf] = MFMA16(*(const LAS bf16x8*)(kb_ + hf * 16 * KROW + ks * 64), qf[ks], s[hf]);
;             }
;             if (local) {
; #pragma unroll
;                 for (int hf = 0; hf < 2; ++hf)
; #pragma unroll
;                     for (int j = 0; j < 4; ++j) {
;                         const int kcol = band + hf * 16 + q4 * 4 + j; const bool inw = kcol >= cs && kcol < cs + 16;
;                         s[hf][j] = inw ? s[hf][j] * sl2 + bias8[hf * 4 + j] * 1.4426950408889634f : -1e30f;
;                     }
	s_and_saveexec_b64 s[0:1], s[24:25]
	s_cbranch_execz .LBB0_2626
	s_mov_b64 s[16:17], exec
	v_mbcnt_lo_u32_b32 v0, s16, 0
	v_mbcnt_hi_u32_b32 v0, s17, v0
	v_cmp_eq_u32_e32 vcc, 0, v0
	s_and_saveexec_b64 s[14:15], vcc
	s_cbranch_execz .LBB0_2625
	s_bcnt1_i32_b64 s16, s[16:17]
	v_mov_b32_e32 v1, s16
	global_atomic_add v1, v69, v1, s[34:35] sc0
	s_branch .LBB0_2625
.LBB0_2630:
	s_cmpk_gt_u32 s0, 0x35f
	s_cbranch_scc1 .LBB0_2681
	s_mov_b32 s29, s0
	s_mov_b32 s22, 0x3e0293ee
	s_mov_b32 s23, 0x3fb8aa3b
	v_and_b32_e32 v196, 15, v202
	v_bfe_u32 v197, v202, 4, 2
	v_lshrrev_b32_e32 v198, 6, v202
	s_nop 0
	v_readfirstlane_b32 s74, v198
	v_mov_b32_e32 v199, v202
	v_lshrrev_b32_e32 v200, 4, v199
	v_and_b32_e32 v201, 15, v199
	v_lshlrev_b32_e32 v201, 4, v201
	v_mul_u32_u24_e32 v230, 0x3000, v200
	v_add_u32_e32 v230, v230, v201
	v_mul_u32_u24_e32 v234, 0x110, v200
	v_add_u32_e32 v234, v234, v201
	v_lshrrev_b32_e32 v200, 3, v199
	v_and_b32_e32 v201, 7, v199
	v_lshlrev_b32_e32 v201, 4, v201
	v_mul_u32_u24_e32 v232, 0x1200, v200
	v_add_u32_e32 v232, v232, v201
	v_mul_u32_u24_e32 v236, 0x90, v200
	v_add_u32_e32 v236, v236, v201
	v_add_u32_e32 v236, 0xcc00, v236
	v_add_u32_e32 v199, 0x200, v202
	v_lshrrev_b32_e32 v200, 4, v199
	v_and_b32_e32 v201, 15, v199
	v_lshlrev_b32_e32 v201, 4, v201
	v_mul_u32_u24_e32 v231, 0x3000, v200
	v_add_u32_e32 v231, v231, v201
	v_mul_u32_u24_e32 v235, 0x110, v200
	v_add_u32_e32 v235, v235, v201
	v_lshrrev_b32_e32 v200, 3, v199
	v_and_b32_e32 v201, 7, v199
	v_lshlrev_b32_e32 v201, 4, v201
	v_mul_u32_u24_e32 v233, 0x1200, v200
	v_add_u32_e32 v233, v233, v201
	v_mul_u32_u24_e32 v237, 0x90, v200
	v_add_u32_e32 v237, v237, v201
	v_add_u32_e32 v237, 0xcc00, v237
	v_mul_u32_u24_e32 v199, 0x110, v196
	v_lshl_add_u32 v238, v197, 4, v199
	v_mul_u32_u24_e32 v199, 0x90, v196
	v_lshl_add_u32 v199, v197, 3, v199
	v_add_u32_e32 v239, 0xcc00, v199
	v_mul_u32_u24_e32 v199, 0x3000, v196
	v_lshl_add_u32 v251, v197, 4, v199
	v_lshlrev_b32_e32 v199, 12, v196
	v_lshl_add_u32 v246, v197, 3, v199
	s_and_b32 s73, s74, 3
	s_lshl_b32 s73, s73, 4
	s_sub_i32 s56, s73, 8
	s_max_i32 s56, s56, 0
	s_min_i32 s56, s56, 32
	v_add_u32_e32 v220, s73, v196
	v_subrev_u32_e32 v221, 8, v220
	v_max_i32_e32 v221, 0, v221
	v_min_i32_e32 v221, 48, v221
	v_add_u32_e32 v222, 16, v221
	v_lshlrev_b32_e32 v223, 2, v197
	v_mov_b32_e32 v224, 0xf149f2ca
	v_mov_b32_e32 v225, 0x7f7fffff
	s_add_u32 s57, s56, 0
	v_add_u32_e32 v199, s57, v223
	v_sub_u32_e32 v200, v199, v220
	v_add_u32_e32 v200, 15, v200
	v_max_i32_e32 v200, 0, v200
	v_min_i32_e32 v200, 30, v200
	v_lshlrev_b32_e32 v200, 2, v200
	v_add_u32_e32 v132, 0x1a400, v200
	v_cmp_ge_i32_e32 vcc, v199, v221
	v_cmp_lt_i32_e64 s[0:1], v199, v222
	s_and_b64 vcc, vcc, s[0:1]
	v_cndmask_b32_e32 v140, v224, v225, vcc
	s_add_u32 s57, s56, 1
	v_add_u32_e32 v199, s57, v223
	v_sub_u32_e32 v200, v199, v220
	v_add_u32_e32 v200, 15, v200
	v_max_i32_e32 v200, 0, v200
	v_min_i32_e32 v200, 30, v200
	v_lshlrev_b32_e32 v200, 2, v200
	v_add_u32_e32 v133, 0x1a400, v200
	v_cmp_ge_i32_e32 vcc, v199, v221
	v_cmp_lt_i32_e64 s[0:1], v199, v222
	s_and_b64 vcc, vcc, s[0:1]
	v_cndmask_b32_e32 v141, v224, v225, vcc
	s_add_u32 s57, s56, 2
	v_add_u32_e32 v199, s57, v223
	v_sub_u32_e32 v200, v199, v220
	v_add_u32_e32 v200, 15, v200
	v_max_i32_e32 v200, 0, v200
	v_min_i32_e32 v200, 30, v200
	v_lshlrev_b32_e32 v200, 2, v200
	v_add_u32_e32 v134, 0x1a400, v200
	v_cmp_ge_i32_e32 vcc, v199, v221
	v_cmp_lt_i32_e64 s[0:1], v199, v222
	s_and_b64 vcc, vcc, s[0:1]
	v_cndmask_b32_e32 v142, v224, v225, vcc
	s_add_u32 s57, s56, 3
	v_add_u32_e32 v199, s57, v223
	v_sub_u32_e32 v200, v199, v220
	v_add_u32_e32 v200, 15, v200
	v_max_i32_e32 v200, 0, v200
	v_min_i32_e32 v200, 30, v200
	v_lshlrev_b32_e32 v200, 2, v200
	v_add_u32_e32 v135, 0x1a400, v200
	v_cmp_ge_i32_e32 vcc, v199, v221
	v_cmp_lt_i32_e64 s[0:1], v199, v222
	s_and_b64 vcc, vcc, s[0:1]
	v_cndmask_b32_e32 v143, v224, v225, vcc
	s_add_u32 s57, s56, 16
	v_add_u32_e32 v199, s57, v223
	v_sub_u32_e32 v200, v199, v220
	v_add_u32_e32 v200, 15, v200
	v_max_i32_e32 v200, 0, v200
	v_min_i32_e32 v200, 30, v200
	v_lshlrev_b32_e32 v200, 2, v200
	v_add_u32_e32 v136, 0x1a400, v200
	v_cmp_ge_i32_e32 vcc, v199, v221
	v_cmp_lt_i32_e64 s[0:1], v199, v222
	s_and_b64 vcc, vcc, s[0:1]
	v_cndmask_b32_e32 v144, v224, v225, vcc
	s_add_u32 s57, s56, 17
	v_add_u32_e32 v199, s57, v223
	v_sub_u32_e32 v200, v199, v220
	v_add_u32_e32 v200, 15, v200
	v_max_i32_e32 v200, 0, v200
	v_min_i32_e32 v200, 30, v200
	v_lshlrev_b32_e32 v200, 2, v200
	v_add_u32_e32 v137, 0x1a400, v200
	v_cmp_ge_i32_e32 vcc, v199, v221
	v_cmp_lt_i32_e64 s[0:1], v199, v222
	s_and_b64 vcc, vcc, s[0:1]
	v_cndmask_b32_e32 v145, v224, v225, vcc
	s_add_u32 s57, s56, 18
	v_add_u32_e32 v199, s57, v223
	v_sub_u32_e32 v200, v199, v220
	v_add_u32_e32 v200, 15, v200
	v_max_i32_e32 v200, 0, v200
	v_min_i32_e32 v200, 30, v200
	v_lshlrev_b32_e32 v200, 2, v200
	v_add_u32_e32 v138, 0x1a400, v200
	v_cmp_ge_i32_e32 vcc, v199, v221
	v_cmp_lt_i32_e64 s[0:1], v199, v222
	s_and_b64 vcc, vcc, s[0:1]
	v_cndmask_b32_e32 v146, v224, v225, vcc
	s_add_u32 s57, s56, 19
	v_add_u32_e32 v199, s57, v223
	v_sub_u32_e32 v200, v199, v220
	v_add_u32_e32 v200, 15, v200
	v_max_i32_e32 v200, 0, v200
	v_min_i32_e32 v200, 30, v200
	v_lshlrev_b32_e32 v200, 2, v200
	v_add_u32_e32 v139, 0x1a400, v200
	v_cmp_ge_i32_e32 vcc, v199, v221
	v_cmp_lt_i32_e64 s[0:1], v199, v222
	s_and_b64 vcc, vcc, s[0:1]
	v_cndmask_b32_e32 v147, v224, v225, vcc
	v_readlane_b32 s10, v255, 62
	v_readlane_b32 s11, v255, 63
	s_nop 4
	s_load_dwordx2 s[8:9], s[10:11], 0x58
	s_waitcnt lgkmcnt(0)
	v_writelane_b32 v254, s8, 0
	v_writelane_b32 v254, s9, 1
	v_writelane_b32 v254, s74, 2
; #define LAS __attribute__((address_space(3)))
; #define NA_LOAD(t, ks_, vs_) do { const int tb_ = NA_TB(t); \
;         _Pragma("unroll") for (int i = 0; i < 2; ++i) { const int cid = tid + i * 512; \
;             ks_[i] = *(const u32x4*)(kg + (size_t)(tb_ + (cid >> 4)) * INP + (cid & 15) * 8); \
;             vs_[i] = *(const u32x4*)(vg + (size_t)(cid >> 3) * RB + tb_ + (cid & 7) * 8); } } while (0)
; #define NA_STORE(buf, ks_, vs_) do { \
;         _Pragma("unroll") for (int i = 0; i < 2; ++i) { const int cid = tid + i * 512; \
;             *(LAS u32x4*)(lds + (buf) * KTILE + (cid >> 4) * KROW + (cid & 15) * 16) = ks_[i]; \
;             *(LAS u32x4*)(lds + 3 * KTILE + (buf) * VTILE + (cid >> 3) * VROW + (cid & 7) * 16) = vs_[i]; } } while (0)
; DI void na_block_item(const Params& p, int l, int b, int h, int rp, LAS unsigned char* lds) {
;     ...
;     const int gr = 2 * rp + (wid >> 2), jq = wid & 3;
;     const int gc = jq * 16 + r16, r0w = min(max(gr - 4, 0), 24), band = min(max(jq * 16 - 8, 0), 32), cs = min(max(gc - 8, 0), 48);
;     const int r0a = min(max(2 * rp - 4, 0), 24), r0b = min(max(2 * rp - 3, 0), 24), nloc = r0b + 8 - r0a, ntl = nloc + 4;
;     const size_t rowb = (size_t)b * RB, rowq = rowb + CL + gr * 64 + gc;
;     const float sl2 = 0.08838834764831845f * 1.4426950408889634f;
;     const float* rpb = p.in[11] + (size_t)(l * 6 + h) * 15 * 31;
;     bf16x8 qf[4];
; #pragma unroll
;     for (int ks = 0; ks < 4; ++ks) qf[ks] = *(const bf16x8*)(P + rowq * INP + C_NAQ + h * 128 + ks * 32 + q4 * 8);
;     f32x4 oacc[8];
; #pragma unroll
;     for (int d = 0; d < 8; ++d) oacc[d] = (f32x4){0.f, 0.f, 0.f, 0.f};
;     float mrun = -1e30f, lsum = 0.f;
;     const bf16_t* kg = P + rowb * INP + C_NAK + h * 128;
;     const bf16_t* vg = (const bf16_t*)(ws + WS_VTNA) + ((size_t)b * 768 + h * 128) * RB;
;     u32x4 kstA[2], vstA[2], kstB[2], vstB[2];
;     ...
;     LAS float* s_rpb = (LAS float*)(lds + 3 * KTILE + 3 * VTILE);
;     if (tid < 465) s_rpb[tid] = rpb[tid];
;     NA_LOAD(0, kstA, vstA); NA_LOAD(1, kstB, vstB);
;     NA_STORE(0, kstA, vstA);
;     NA_LOAD(2, kstA, vstA);
;     __syncthreads();
na1_item:
	s_sub_u32 s57, s29, 0x1e0
	s_and_b32 s71, s57, 15
	s_lshr_b32 s57, s57, 4
	s_mul_i32 s73, s57, 43
	s_lshr_b32 s73, s73, 8
	s_mul_i32 s63, s73, 6
	s_sub_u32 s72, s57, s63
	s_lshl_b32 s57, s71, 1
	s_sub_i32 s36, s57, 4
	s_max_i32 s36, s36, 0
	s_min_i32 s36, s36, 24
	s_sub_i32 s63, s57, 3
	s_max_i32 s63, s63, 0
	s_min_i32 s63, s63, 24
	s_sub_u32 s30, s63, s36
	s_add_u32 s30, s30, 8
	s_add_u32 s31, s30, 4
	v_readlane_b32 s74, v254, 2
	s_lshr_b32 s63, s74, 2
	s_add_u32 s37, s57, s63
	s_sub_i32 s54, s37, 4
	s_max_i32 s54, s54, 0
	s_min_i32 s54, s54, 24
	s_mul_i32 s68, s73, 0x900
	s_mul_i32 s57, s68, 0x3000
	s_lshl_b32 s63, s72, 8
	s_add_u32 s57, s57, s63
	s_add_u32 s57, s57, 0x113a0600
	s_add_u32 s2, s50, s57
	s_addc_u32 s3, s51, 0
	s_mul_i32 s57, s73, 0x300
	s_lshl_b32 s69, s72, 7
	s_add_u32 s57, s57, s69
	s_mul_i32 s57, s57, 0x1200
	s_add_u32 s57, s57, 0x17fa0000
	s_add_u32 s4, s50, s57
	s_addc_u32 s5, s51, 0
	s_and_b32 s69, s74, 3
	s_lshl_b32 s69, s69, 4
	s_lshl_b32 s70, s37, 6
	s_add_u32 s69, s69, s70
	s_add_u32 s69, s69, s68
	s_addk_i32 s69, 0x100
	s_mul_i32 s57, s69, 0x3000
	s_add_u32 s57, s57, s63
	s_add_u32 s57, s57, 0x113a0000
	s_add_u32 s6, s50, s57
	s_addc_u32 s7, s51, 0
	global_load_dwordx4 v[0:3], v251, s[6:7] offset:0
	global_load_dwordx4 v[4:7], v251, s[6:7] offset:64
	global_load_dwordx4 v[8:11], v251, s[6:7] offset:128
	global_load_dwordx4 v[12:15], v251, s[6:7] offset:192
	s_lshl_b32 s57, s69, 12
	s_add_u32 s57, s57, s63
	s_add_u32 s57, s57, 0x1d9a0000
	s_add_u32 s10, s50, s57
	s_addc_u32 s11, s51, 0
	v_readlane_b32 s6, v254, 0
	v_readlane_b32 s7, v254, 1
	s_mul_i32 s57, s72, 0x744
	s_add_u32 s57, s57, 0x2b98
	s_nop 2
	s_add_u32 s6, s6, s57
	s_addc_u32 s7, s7, 0
	v_lshlrev_b32_e32 v196, 2, v202
	v_cmp_gt_u32_e32 vcc, 0x1d1, v202
	s_and_saveexec_b64 s[0:1], vcc
	global_load_dword v197, v196, s[6:7]
	s_or_b64 exec, exec, s[0:1]
	s_mov_b32 s70, 0
	s_add_u32 s57, s36, s70
	s_lshl_b32 s57, s57, 6
	s_addk_i32 s57, 0x100
	s_sub_u32 s63, s70, s30
	s_lshl_b32 s63, s63, 6
	s_cmp_lt_u32 s70, s30
	s_cselect_b32 s57, s57, s63
	s_mul_i32 s63, s57, 0x3000
	s_add_u32 s6, s2, s63
	s_addc_u32 s7, s3, 0
	s_lshl_b32 s63, s57, 1
	s_add_u32 s8, s4, s63
	s_addc_u32 s9, s5, 0
	global_load_dwordx4 v[148:151], v230, s[6:7]
	global_load_dwordx4 v[152:155], v231, s[6:7]
	global_load_dwordx4 v[156:159], v232, s[8:9]
	global_load_dwordx4 v[160:163], v233, s[8:9]
	s_mov_b32 s70, 1
	s_add_u32 s57, s36, s70
	s_lshl_b32 s57, s57, 6
	s_addk_i32 s57, 0x100
	s_sub_u32 s63, s70, s30
	s_lshl_b32 s63, s63, 6
	s_cmp_lt_u32 s70, s30
	s_cselect_b32 s57, s57, s63
	s_mul_i32 s63, s57, 0x3000
	s_add_u32 s6, s2, s63
	s_addc_u32 s7, s3, 0
	s_lshl_b32 s63, s57, 1
	s_add_u32 s8, s4, s63
	s_addc_u32 s9, s5, 0
	global_load_dwordx4 v[164:167], v230, s[6:7]
	global_load_dwordx4 v[168:171], v231, s[6:7]
	global_load_dwordx4 v[172:175], v232, s[8:9]
	global_load_dwordx4 v[176:179], v233, s[8:9]
	s_mov_b32 s70, 2
	s_add_u32 s57, s36, s70
	s_lshl_b32 s57, s57, 6
	s_addk_i32 s57, 0x100
	s_sub_u32 s63, s70, s30
	s_lshl_b32 s63, s63, 6
	s_cmp_lt_u32 s70, s30
	s_cselect_b32 s57, s57, s63
	s_mul_i32 s63, s57, 0x3000
	s_add_u32 s6, s2, s63
	s_addc_u32 s7, s3, 0
	s_lshl_b32 s63, s57, 1
	s_add_u32 s8, s4, s63
	s_addc_u32 s9, s5, 0
	global_load_dwordx4 v[180:183], v230, s[6:7]
	global_load_dwordx4 v[184:187], v231, s[6:7]
	global_load_dwordx4 v[188:191], v232, s[8:9]
	global_load_dwordx4 v[192:195], v233, s[8:9]
	s_mov_b32 s70, 3
	s_add_u32 s57, s36, s70
	s_lshl_b32 s57, s57, 6
	s_addk_i32 s57, 0x100
	s_sub_u32 s63, s70, s30
	s_lshl_b32 s63, s63, 6
	s_cmp_lt_u32 s70, s30
	s_cselect_b32 s57, s57, s63
	s_mul_i32 s63, s57, 0x3000
	s_add_u32 s6, s2, s63
	s_addc_u32 s7, s3, 0
	s_lshl_b32 s63, s57, 1
	s_add_u32 s8, s4, s63
	s_addc_u32 s9, s5, 0
	global_load_dwordx4 v[204:207], v230, s[6:7]
	global_load_dwordx4 v[208:211], v231, s[6:7]
	global_load_dwordx4 v[212:215], v232, s[8:9]
	global_load_dwordx4 v[216:219], v233, s[8:9]
	v_mov_b32_e32 v16, 0
	v_mov_b32_e32 v17, 0
	v_mov_b32_e32 v18, 0
	v_mov_b32_e32 v19, 0
	v_mov_b32_e32 v20, 0
	v_mov_b32_e32 v21, 0
	v_mov_b32_e32 v22, 0
	v_mov_b32_e32 v23, 0
	v_mov_b32_e32 v24, 0
	v_mov_b32_e32 v25, 0
	v_mov_b32_e32 v26, 0
	v_mov_b32_e32 v27, 0
	v_mov_b32_e32 v28, 0
	v_mov_b32_e32 v29, 0
	v_mov_b32_e32 v30, 0
	v_mov_b32_e32 v31, 0
	v_mov_b32_e32 v32, 0
	v_mov_b32_e32 v33, 0
	v_mov_b32_e32 v34, 0
	v_mov_b32_e32 v35, 0
	v_mov_b32_e32 v36, 0
	v_mov_b32_e32 v37, 0
	v_mov_b32_e32 v38, 0
	v_mov_b32_e32 v39, 0
	v_mov_b32_e32 v40, 0
	v_mov_b32_e32 v41, 0
	v_mov_b32_e32 v42, 0
	v_mov_b32_e32 v43, 0
	v_mov_b32_e32 v44, 0
	v_mov_b32_e32 v45, 0
	v_mov_b32_e32 v46, 0
	v_mov_b32_e32 v47, 0
	v_mov_b32_e32 v242, 0xf149f2ca
	v_mov_b32_e32 v243, 0
	s_waitcnt vmcnt(12)
	v_cmp_gt_u32_e32 vcc, 0x1d1, v202
	s_and_saveexec_b64 s[0:1], vcc
	v_add_u32_e32 v196, 0x1a400, v196
	ds_write_b32 v196, v197
	s_or_b64 exec, exec, s[0:1]
	ds_write_b128 v234, v[148:151]
	ds_write_b128 v235, v[152:155]
	ds_write_b128 v236, v[156:159]
	ds_write_b128 v237, v[160:163]
	s_waitcnt lgkmcnt(0)
	s_mov_b32 s70, 4
	s_add_u32 s57, s36, s70
	s_lshl_b32 s57, s57, 6
	s_addk_i32 s57, 0x100
	s_sub_u32 s63, s70, s30
	s_lshl_b32 s63, s63, 6
	s_cmp_lt_u32 s70, s30
	s_cselect_b32 s57, s57, s63
	s_mul_i32 s63, s57, 0x3000
	s_add_u32 s6, s2, s63
	s_addc_u32 s7, s3, 0
	s_lshl_b32 s63, s57, 1
	s_add_u32 s8, s4, s63
	s_addc_u32 s9, s5, 0
	global_load_dwordx4 v[148:151], v230, s[6:7]
	global_load_dwordx4 v[152:155], v231, s[6:7]
	global_load_dwordx4 v[156:159], v232, s[8:9]
	global_load_dwordx4 v[160:163], v233, s[8:9]
	s_barrier
	s_mov_b32 s27, 0

; DI void na_block_item(const Params& p, int l, int b, int h, int rp, LAS unsigned char* lds) {
;     ...
;         const int cur = t % 3;
;         const bool local = t < nloc; const int kr = r0a + t;
;         const int nch = local ? ((kr >= r0w && kr < r0w + 8) ? 1 : 0) : 2;
;         for (int ci = 0; ci < nch; ++ci) {
;             const int toff = local ? band : ci * 32;
;             const LAS unsigned char* kb_ = lds + cur * KTILE + (toff + r16) * KROW + q4 * 16;
;             const LAS unsigned char* vb_ = lds + 3 * KTILE + cur * VTILE + r16 * VROW + (toff + q4 * 4) * 2;
;             float bias8[8];
;             if (local) {
;                 const LAS float* rp_ = s_rpb + (kr - gr + 7) * 31;
; #pragma unroll
;                 for (int e = 0; e < 8; ++e) { const int kcol = band + (e >> 2) * 16 + q4 * 4 + (e & 3); bias8[e] = rp_[min(max(kcol - gc + 15, 0), 30)]; }
;             }
;             f32x4 s[2];
; #pragma unroll
;             for (int hf = 0; hf < 2; ++hf) {
;                 s[hf] = (f32x4){0.f, 0.f, 0.f, 0.f};
; #pragma unroll
;                 for (int ks = 0; ks < 4; ++ks) s[hf] = MFMA16(*(const LAS bf16x8*)(kb_ + hf * 16 * KROW + ks * 64), qf[ks], s[hf]);
;             }
;             if (local) {
; #pragma unroll
;                 for (int hf = 0; hf < 2; ++hf)
; #pragma unroll
;                     for (int j = 0; j < 4; ++j) {
;                         const int kcol = band + hf * 16 + q4 * 4 + j; const bool inw = kcol >= cs && kcol < cs + 16;
;                         s[hf][j] = inw ? s[hf][j] * sl2 + bias8[hf * 4 + j] * 1.4426950408889634f : -1e30f;
;                     }
;             } else { s[0] *= sl2; s[1] *= sl2; }
;             float mx = fmaxf(fmaxf(fmaxf(s[0][0], s[0][1]), fmaxf(s[0][2], s[0][3])), fmaxf(fmaxf(s[1][0], s[1][1]), fmaxf(s[1][2], s[1][3])));
;             mx = fmaxf(mx, __shfl_xor(mx, 16)); mx = fmaxf(mx, __shfl_xor(mx, 32));
;             const float mnew = fmaxf(mrun, mx), alpha = fast_exp2(mrun - mnew);
;             mrun = mnew;
;             float ps = 0.f;
; #pragma unroll
;             for (int hf = 0; hf < 2; ++hf)
; #pragma unroll
;                 for (int j = 0; j < 4; ++j) { const float pv = fast_exp2(s[hf][j] - mnew); s[hf][j] = pv; ps += pv; }
;             lsum = lsum * alpha + ps;
; #pragma unroll
;             for (int d = 0; d < 8; ++d) oacc[d] *= alpha;
na1_nostage:
	s_mul_hi_u32 s57, s27, 0x55555556
	s_mul_i32 s57, s57, 3
	s_sub_u32 s57, s27, s57
	s_mul_i32 s75, s57, 0x4400
	s_mul_i32 s76, s57, 0x4800
	s_cmp_lt_u32 s27, s30
	s_cbranch_scc0 na1_ctx
	s_add_u32 s68, s36, s27
	s_cmp_lt_i32 s68, s54
	s_cbranch_scc1 na1_bar
	s_add_u32 s69, s54, 8
	s_cmp_ge_i32 s68, s69
	s_cbranch_scc1 na1_bar
	s_sub_i32 s69, s68, s37
	s_add_u32 s69, s69, 7
	s_mul_i32 s69, s69, 0x7c
	s_mul_i32 s57, s56, 0x110
	s_add_u32 s57, s57, s75
	s_lshl_b32 s63, s56, 1
	s_add_u32 s63, s63, s76
	v_add_u32_e32 v240, s57, v238
	v_add_u32_e32 v241, s63, v239
	v_add_u32_e32 v222, s69, v132
	v_add_u32_e32 v223, s69, v133
	v_add_u32_e32 v224, s69, v134
	v_add_u32_e32 v225, s69, v135
	v_add_u32_e32 v226, s69, v136
	v_add_u32_e32 v227, s69, v137
	v_add_u32_e32 v228, s69, v138
	v_add_u32_e32 v229, s69, v139
	ds_read_b32 v124, v222
	ds_read_b32 v125, v223
	ds_read_b32 v126, v224
	ds_read_b32 v127, v225
	ds_read_b32 v128, v226
	ds_read_b32 v129, v227
	ds_read_b32 v130, v228
	ds_read_b32 v131, v229
	ds_read_b128 v[56:59], v240 offset:0
	ds_read_b128 v[72:75], v240 offset:4352
	ds_read_b128 v[60:63], v240 offset:64
	ds_read_b128 v[76:79], v240 offset:4416
	ds_read_b128 v[64:67], v240 offset:128
	ds_read_b128 v[80:83], v240 offset:4480
	ds_read_b128 v[68:71], v240 offset:192
	ds_read_b128 v[84:87], v240 offset:4544
	s_waitcnt lgkmcnt(7)
	v_mfma_f32_16x16x32_bf16 v[48:51], v[56:59], v[0:3], 0
	ds_read_b64 v[88:89], v241 offset:0
	ds_read_b64 v[90:91], v241 offset:32
	s_waitcnt lgkmcnt(8)
	v_mfma_f32_16x16x32_bf16 v[52:55], v[72:75], v[0:3], 0
	ds_read_b64 v[92:93], v241 offset:2304
	ds_read_b64 v[94:95], v241 offset:2336
	s_waitcnt lgkmcnt(9)
	v_mfma_f32_16x16x32_bf16 v[48:51], v[60:63], v[4:7], v[48:51]
	ds_read_b64 v[96:97], v241 offset:4608
	ds_read_b64 v[98:99], v241 offset:4640
	s_waitcnt lgkmcnt(10)
	v_mfma_f32_16x16x32_bf16 v[52:55], v[76:79], v[4:7], v[52:55]
	ds_read_b64 v[100:101], v241 offset:6912
	ds_read_b64 v[102:103], v241 offset:6944
	s_waitcnt lgkmcnt(11)
	v_mfma_f32_16x16x32_bf16 v[48:51], v[64:67], v[8:11], v[48:51]
	ds_read_b64 v[104:105], v241 offset:9216
	ds_read_b64 v[106:107], v241 offset:9248
	s_waitcnt lgkmcnt(12)
	v_mfma_f32_16x16x32_bf16 v[52:55], v[80:83], v[8:11], v[52:55]
	ds_read_b64 v[108:109], v241 offset:11520
	ds_read_b64 v[110:111], v241 offset:11552
	s_waitcnt lgkmcnt(13)
	v_mfma_f32_16x16x32_bf16 v[48:51], v[68:71], v[12:15], v[48:51]
	ds_read_b64 v[112:113], v241 offset:13824
	ds_read_b64 v[114:115], v241 offset:13856
	s_waitcnt lgkmcnt(14)
	v_mfma_f32_16x16x32_bf16 v[52:55], v[84:87], v[12:15], v[52:55]
	ds_read_b64 v[116:117], v241 offset:16128
	ds_read_b64 v[118:119], v241 offset:16160
	v_mul_f32_e32 v124, s23, v124
	v_mul_f32_e32 v125, s23, v125
	v_mul_f32_e32 v126, s23, v126
	v_mul_f32_e32 v127, s23, v127
	v_mul_f32_e32 v128, s23, v128
	v_mul_f32_e32 v129, s23, v129
	v_mul_f32_e32 v130, s23, v130
	v_mul_f32_e32 v131, s23, v131
	s_nop 1
	v_fma_f32 v48, v48, s22, v124
	v_fma_f32 v49, v49, s22, v125
	v_fma_f32 v50, v50, s22, v126
	v_fma_f32 v51, v51, s22, v127
	v_fma_f32 v52, v52, s22, v128
	v_fma_f32 v53, v53, s22, v129
	v_fma_f32 v54, v54, s22, v130
	v_fma_f32 v55, v55, s22, v131
	v_min_f32_e32 v48, v48, v140
	v_min_f32_e32 v49, v49, v141
	v_min_f32_e32 v50, v50, v142
	v_min_f32_e32 v51, v51, v143
	v_min_f32_e32 v52, v52, v144
	v_min_f32_e32 v53, v53, v145
	v_min_f32_e32 v54, v54, v146
	v_min_f32_e32 v55, v55, v147
	v_max3_f32 v196, v48, v49, v50
	v_max3_f32 v197, v51, v52, v53
	v_max3_f32 v196, v196, v54, v55
	v_max_f32_e32 v196, v196, v197
	v_mov_b32_e32 v197, v196
	s_nop 1
	v_permlane16_swap_b32_e32 v196, v197
	v_max_f32_e32 v196, v196, v197
	v_mov_b32_e32 v197, v196
	s_nop 1
	v_permlane32_swap_b32_e32 v196, v197
	v_max_f32_e32 v196, v196, v197
	v_max_f32_e32 v197, v242, v196
	v_sub_f32_e32 v196, v242, v197
	v_exp_f32_e32 v244, v196
	v_mov_b32_e32 v242, v197
	v_sub_f32_e32 v48, v48, v197
	v_sub_f32_e32 v49, v49, v197
	v_sub_f32_e32 v50, v50, v197
	v_sub_f32_e32 v51, v51, v197
	v_sub_f32_e32 v52, v52, v197
	v_sub_f32_e32 v53, v53, v197
	v_sub_f32_e32 v54, v54, v197
	v_sub_f32_e32 v55, v55, v197
	v_exp_f32_e32 v48, v48
	v_exp_f32_e32 v49, v49
	v_exp_f32_e32 v50, v50
	v_exp_f32_e32 v51, v51
	v_exp_f32_e32 v52, v52
	v_exp_f32_e32 v53, v53
	v_exp_f32_e32 v54, v54
	v_exp_f32_e32 v55, v55
	v_add_f32_e32 v196, v48, v49
	v_add_f32_e32 v196, v196, v50
	v_add_f32_e32 v196, v196, v51
	v_add_f32_e32 v196, v196, v52
	v_add_f32_e32 v196, v196, v53
	v_add_f32_e32 v196, v196, v54
	v_add_f32_e32 v196, v196, v55
	v_fma_f32 v243, v243, v244, v196
	v_cvt_pk_bf16_f32 v120, v48, v49
	v_cvt_pk_bf16_f32 v121, v50, v51
	v_cvt_pk_bf16_f32 v122, v52, v53
	v_cvt_pk_bf16_f32 v123, v54, v55
	v_pk_mul_f32 v[16:17], v[16:17], v[244:245] op_sel_hi:[1,0]
	v_pk_mul_f32 v[18:19], v[18:19], v[244:245] op_sel_hi:[1,0]
	v_pk_mul_f32 v[20:21], v[20:21], v[244:245] op_sel_hi:[1,0]
	v_pk_mul_f32 v[22:23], v[22:23], v[244:245] op_sel_hi:[1,0]
	v_pk_mul_f32 v[24:25], v[24:25], v[244:245] op_sel_hi:[1,0]
	v_pk_mul_f32 v[26:27], v[26:27], v[244:245] op_sel_hi:[1,0]
	v_pk_mul_f32 v[28:29], v[28:29], v[244:245] op_sel_hi:[1,0]
	v_pk_mul_f32 v[30:31], v[30:31], v[244:245] op_sel_hi:[1,0]
	v_pk_mul_f32 v[32:33], v[32:33], v[244:245] op_sel_hi:[1,0]
	v_pk_mul_f32 v[34:35], v[34:35], v[244:245] op_sel_hi:[1,0]
	v_pk_mul_f32 v[36:37], v[36:37], v[244:245] op_sel_hi:[1,0]
	v_pk_mul_f32 v[38:39], v[38:39], v[244:245] op_sel_hi:[1,0]
	v_pk_mul_f32 v[40:41], v[40:41], v[244:245] op_sel_hi:[1,0]
	v_pk_mul_f32 v[42:43], v[42:43], v[244:245] op_sel_hi:[1,0]
	v_pk_mul_f32 v[44:45], v[44:45], v[244:245] op_sel_hi:[1,0]
	v_pk_mul_f32 v[46:47], v[46:47], v[244:245] op_sel_hi:[1,0]
	s_waitcnt lgkmcnt(14)
	v_mfma_f32_16x16x32_bf16 v[16:19], v[88:91], v[120:123], v[16:19]
	s_waitcnt lgkmcnt(12)
	v_mfma_f32_16x16x32_bf16 v[20:23], v[92:95], v[120:123], v[20:23]
	s_waitcnt lgkmcnt(10)
	v_mfma_f32_16x16x32_bf16 v[24:27], v[96:99], v[120:123], v[24:27]
	s_waitcnt lgkmcnt(8)
	v_mfma_f32_16x16x32_bf16 v[28:31], v[100:103], v[120:123], v[28:31]
	s_waitcnt lgkmcnt(6)
	v_mfma_f32_16x16x32_bf16 v[32:35], v[104:107], v[120:123], v[32:35]
	s_waitcnt lgkmcnt(4)
	v_mfma_f32_16x16x32_bf16 v[36:39], v[108:111], v[120:123], v[36:39]
	s_waitcnt lgkmcnt(2)
	v_mfma_f32_16x16x32_bf16 v[40:43], v[112:115], v[120:123], v[40:43]
	s_waitcnt lgkmcnt(0)
	v_mfma_f32_16x16x32_bf16 v[44:47], v[116:119], v[120:123], v[44:47]
	s_branch na1_bar
